# GEMM K-loops: priority flip pair (s_setprio 0/1) after every 8 MFMAs instead of every 16
# speedup vs baseline: 1.0041x; 1.0041x over previous
; #define PG8_STAGE(bufoff, gbase, voff) do { _Pragma("unroll") for (int _i = 0; _i < 2; ++_i) \
;         __builtin_amdgcn_global_load_lds((const unsigned*)((const char*)(gbase) + (voff)[_i]), (PG8_LAS unsigned*)(lds + (bufoff) + ldsw + _i * 8192), 16, 0, 0); } while (0)
; #define PG8_LDA(dst, b, h) do { _Pragma("unroll") for (int m = 0; m < 4; ++m) _Pragma("unroll") for (int k = 0; k < 2; ++k) dst[m][k] = *(const PG8_LAS bf16x8*)(lds + PG8_SA(b, h) + aoff + m * 2048 + k * 1024); } while (0)
; #define PG8_LDB(dst, b, h) do { _Pragma("unroll") for (int n = 0; n < 2; ++n) _Pragma("unroll") for (int k = 0; k < 2; ++k) dst[n][k] = *(const PG8_LAS bf16x8*)(lds + PG8_SB(b, h) + boff + n * 2048 + k * 1024); } while (0)
; #define PG8_MMA(ai, bj, At, Bt) do { __builtin_amdgcn_s_setprio(1); _Pragma("unroll") for (int m = 0; m < 4; ++m) _Pragma("unroll") for (int n = 0; n < 2; ++n) _Pragma("unroll") for (int k = 0; k < 2; ++k) \
;         acc[ai][bj][m][n] = __builtin_amdgcn_mfma_f32_16x16x32_bf16(Bt[n][k], At[m][k], acc[ai][bj][m][n], 0, 0, 0); __builtin_amdgcn_s_setprio(0); } while (0)
; #define PG8_WAIT_V(n) asm volatile("s_waitcnt vmcnt(" #n ")" ::: "memory")
; #define PG8_WAIT_L(n) asm volatile("s_waitcnt lgkmcnt(" #n ")" ::: "memory")
; template <class Epi, class Sched, bool ALIGN_EPI = false, bool SP2 = false>
; __device__ __forceinline__ void gemm_phase(PG8_LAS unsigned char* lds, const Gemm g, const Sched& S, const Epi& E, const int wave0) {
;     ...
;             const bool last = (t == nt - 2);
;             const char* a1 = cA + (size_t)(t + 1) * kstep;
;             const char* a2 = last ? nA : cA + (size_t)(t + 2) * kstep; const char* b2 = last ? nB : cB + (size_t)(t + 2) * kstep;
;             const char* a3 = a2 + kstep; const char* b3 = b2 + kstep;
;             if (last && has_next) S.a_ready(nxt);
;             if constexpr (SP2) {
;             PG8_LDB(B0, 0, 0); PG8_LDB(B1, 0, 1); PG8_SCHED; PG8_LDA(At, 0, 0); PG8_STAGE(PG8_SA(1, 1), a1 + hstepA, voffA);
;             PG8_WAIT_V(8); PG8_WAIT_L(0); PG8_BAR; PG8_MMA(0, 0, At, B0); PG8_MMA(0, 1, At, B1); PG8_BAR; PG8_SCHED;
;             PG8_LDA(At, 0, 1); PG8_STAGE(PG8_SB(0, 0), b2, voffB); PG8_STAGE(PG8_SB(0, 1), b2 + hstepB, voffB); PG8_STAGE(PG8_SA(0, 0), a2, voffA);
;             PG8_WAIT_V(8); PG8_WAIT_L(0); PG8_BAR; PG8_MMA(1, 0, At, B0); PG8_MMA(1, 1, At, B1); PG8_BAR; PG8_SCHED;
.LBB0_316:
	s_add_u32 s16, s0, 0xfff80080
	s_addc_u32 s17, s1, -1
	s_add_i32 s38, 0, 0x10000
	s_cmp_eq_u32 s37, 28
	s_cselect_b32 s19, s11, s17
	s_cselect_b32 s18, s33, s16
	s_cselect_b32 s17, s9, s36
	s_cselect_b32 s16, s34, s35
	s_add_i32 s40, 0, 0x14000
	ds_read_b128 v[144:147], v252
	ds_read_b128 v[148:151], v252 offset:1024
	ds_read_b128 v[152:155], v252 offset:2048
	ds_read_b128 v[156:159], v252 offset:3072
	ds_read_b128 v[178:181], v253
	ds_read_b128 v[182:185], v253 offset:1024
	ds_read_b128 v[186:189], v253 offset:2048
	ds_read_b128 v[190:193], v253 offset:3072
	s_add_i32 m0, s23, 0xc000
	ds_read_b128 v[194:197], v143
	ds_read_b128 v[208:211], v143 offset:1024
	ds_read_b128 v[212:215], v143 offset:2048
	ds_read_b128 v[216:219], v143 offset:3072
	ds_read_b128 v[220:223], v143 offset:4096
	ds_read_b128 v[224:227], v143 offset:5120
	ds_read_b128 v[228:231], v143 offset:6144
	ds_read_b128 v[232:235], v143 offset:7168
	global_load_lds_dwordx4 v136, s[0:1]
	s_add_i32 m0, s23, 0xe000
	s_nop 0
	global_load_lds_dwordx4 v138, s[0:1]
	s_waitcnt vmcnt(8)
	s_waitcnt lgkmcnt(0)
	s_barrier
	s_setprio 1
	s_waitcnt lgkmcnt(0)
	v_mfma_f32_16x16x32_bf16 v[126:129], v[144:147], v[194:197], v[126:129]
	v_mfma_f32_16x16x32_bf16 v[122:125], v[152:155], v[194:197], v[122:125]
	v_mfma_f32_16x16x32_bf16 v[118:121], v[144:147], v[212:215], v[118:121]
	v_mfma_f32_16x16x32_bf16 v[114:117], v[152:155], v[212:215], v[114:117]
	v_mfma_f32_16x16x32_bf16 v[102:105], v[144:147], v[220:223], v[102:105]
	v_mfma_f32_16x16x32_bf16 v[98:101], v[152:155], v[220:223], v[98:101]
	v_mfma_f32_16x16x32_bf16 v[86:89], v[144:147], v[228:231], v[86:89]
	v_mfma_f32_16x16x32_bf16 v[82:85], v[152:155], v[228:231], v[82:85]
	s_setprio 0
	s_setprio 1
	v_mfma_f32_16x16x32_bf16 v[126:129], v[148:151], v[208:211], v[126:129]
	v_mfma_f32_16x16x32_bf16 v[122:125], v[156:159], v[208:211], v[122:125]
	v_mfma_f32_16x16x32_bf16 v[118:121], v[148:151], v[216:219], v[118:121]
	v_mfma_f32_16x16x32_bf16 v[114:117], v[156:159], v[216:219], v[114:117]
	v_mfma_f32_16x16x32_bf16 v[102:105], v[148:151], v[224:227], v[102:105]
	v_mfma_f32_16x16x32_bf16 v[98:101], v[156:159], v[224:227], v[98:101]
	v_mfma_f32_16x16x32_bf16 v[86:89], v[148:151], v[232:235], v[86:89]
	v_mfma_f32_16x16x32_bf16 v[82:85], v[156:159], v[232:235], v[82:85]
	s_setprio 0
	s_setprio 1
	v_mfma_f32_16x16x32_bf16 v[110:113], v[178:181], v[194:197], v[110:113]
	v_mfma_f32_16x16x32_bf16 v[106:109], v[186:189], v[194:197], v[106:109]
	v_mfma_f32_16x16x32_bf16 v[94:97], v[178:181], v[212:215], v[94:97]
	v_mfma_f32_16x16x32_bf16 v[90:93], v[186:189], v[212:215], v[90:93]
	v_mfma_f32_16x16x32_bf16 v[78:81], v[178:181], v[220:223], v[78:81]
	v_mfma_f32_16x16x32_bf16 v[74:77], v[186:189], v[220:223], v[74:77]
	v_mfma_f32_16x16x32_bf16 v[70:73], v[178:181], v[228:231], v[70:73]
	v_mfma_f32_16x16x32_bf16 v[66:69], v[186:189], v[228:231], v[66:69]
	s_setprio 0
	s_setprio 1
	v_mfma_f32_16x16x32_bf16 v[110:113], v[182:185], v[208:211], v[110:113]
	v_mfma_f32_16x16x32_bf16 v[106:109], v[190:193], v[208:211], v[106:109]
	v_mfma_f32_16x16x32_bf16 v[94:97], v[182:185], v[216:219], v[94:97]
	v_mfma_f32_16x16x32_bf16 v[90:93], v[190:193], v[216:219], v[90:93]
	v_mfma_f32_16x16x32_bf16 v[78:81], v[182:185], v[224:227], v[78:81]
	v_mfma_f32_16x16x32_bf16 v[74:77], v[190:193], v[224:227], v[74:77]
	v_mfma_f32_16x16x32_bf16 v[70:73], v[182:185], v[232:235], v[70:73]
	v_mfma_f32_16x16x32_bf16 v[66:69], v[190:193], v[232:235], v[66:69]
	s_setprio 0
	s_barrier
	s_add_i32 s38, s38, s22
	s_mov_b32 m0, s38
	ds_read_b128 v[194:197], v143 offset:16384
	ds_read_b128 v[208:211], v143 offset:17408
	ds_read_b128 v[212:215], v143 offset:18432
	ds_read_b128 v[216:219], v143 offset:19456
	ds_read_b128 v[220:223], v143 offset:20480
	ds_read_b128 v[224:227], v143 offset:21504
	ds_read_b128 v[228:231], v143 offset:22528
	ds_read_b128 v[232:235], v143 offset:23552
	global_load_lds_dwordx4 v64, s[16:17]
	s_add_i32 m0, s38, 0x2000
	s_add_u32 s38, s16, 0x80000
	s_addc_u32 s39, s17, 0
	s_add_i32 s40, s40, s22
	global_load_lds_dwordx4 v130, s[16:17]
	s_mov_b32 m0, s40
	s_mov_b64 s[100:101], s[18:19]
	global_load_lds_dwordx4 v64, s[38:39]
	s_add_i32 m0, s40, 0x2000
	s_nop 0
	global_load_lds_dwordx4 v130, s[38:39]
	s_mov_b32 m0, s23
	s_nop 0
	global_load_lds_dwordx4 v134, s[18:19]
	s_mov_b32 m0, s24
	s_nop 0
	global_load_lds_dwordx4 v132, s[18:19]
	s_waitcnt vmcnt(8)
	s_waitcnt lgkmcnt(0)
	s_barrier
	s_setprio 1
	s_waitcnt lgkmcnt(0)
	v_mfma_f32_16x16x32_bf16 v[60:63], v[144:147], v[194:197], v[60:63]
	v_mfma_f32_16x16x32_bf16 v[56:59], v[152:155], v[194:197], v[56:59]
	v_mfma_f32_16x16x32_bf16 v[52:55], v[144:147], v[212:215], v[52:55]
	v_mfma_f32_16x16x32_bf16 v[48:51], v[152:155], v[212:215], v[48:51]
	v_mfma_f32_16x16x32_bf16 v[36:39], v[144:147], v[220:223], v[36:39]
	v_mfma_f32_16x16x32_bf16 v[32:35], v[152:155], v[220:223], v[32:35]
	v_mfma_f32_16x16x32_bf16 v[20:23], v[144:147], v[228:231], v[20:23]
	v_mfma_f32_16x16x32_bf16 v[16:19], v[152:155], v[228:231], v[16:19]
	s_setprio 0
	s_setprio 1
	v_mfma_f32_16x16x32_bf16 v[60:63], v[148:151], v[208:211], v[60:63]
	v_mfma_f32_16x16x32_bf16 v[56:59], v[156:159], v[208:211], v[56:59]
	v_mfma_f32_16x16x32_bf16 v[52:55], v[148:151], v[216:219], v[52:55]
	v_mfma_f32_16x16x32_bf16 v[48:51], v[156:159], v[216:219], v[48:51]
	v_mfma_f32_16x16x32_bf16 v[36:39], v[148:151], v[224:227], v[36:39]
	v_mfma_f32_16x16x32_bf16 v[32:35], v[156:159], v[224:227], v[32:35]
	v_mfma_f32_16x16x32_bf16 v[20:23], v[148:151], v[232:235], v[20:23]
	v_mfma_f32_16x16x32_bf16 v[16:19], v[156:159], v[232:235], v[16:19]
	s_setprio 0
	s_setprio 1
	v_mfma_f32_16x16x32_bf16 v[44:47], v[178:181], v[194:197], v[44:47]
	v_mfma_f32_16x16x32_bf16 v[40:43], v[186:189], v[194:197], v[40:43]
	v_mfma_f32_16x16x32_bf16 v[28:31], v[178:181], v[212:215], v[28:31]
	v_mfma_f32_16x16x32_bf16 v[24:27], v[186:189], v[212:215], v[24:27]
	v_mfma_f32_16x16x32_bf16 v[12:15], v[178:181], v[220:223], v[12:15]
	v_mfma_f32_16x16x32_bf16 v[8:11], v[186:189], v[220:223], v[8:11]
	v_mfma_f32_16x16x32_bf16 v[4:7], v[178:181], v[228:231], v[4:7]
	v_mfma_f32_16x16x32_bf16 v[0:3], v[186:189], v[228:231], v[0:3]
	s_setprio 0
	s_setprio 1
	v_mfma_f32_16x16x32_bf16 v[44:47], v[182:185], v[208:211], v[44:47]
	v_mfma_f32_16x16x32_bf16 v[40:43], v[190:193], v[208:211], v[40:43]
	v_mfma_f32_16x16x32_bf16 v[28:31], v[182:185], v[216:219], v[28:31]
	v_mfma_f32_16x16x32_bf16 v[24:27], v[190:193], v[216:219], v[24:27]
	v_mfma_f32_16x16x32_bf16 v[12:15], v[182:185], v[224:227], v[12:15]
	v_mfma_f32_16x16x32_bf16 v[8:11], v[190:193], v[224:227], v[8:11]
	v_mfma_f32_16x16x32_bf16 v[4:7], v[182:185], v[232:235], v[4:7]
	v_mfma_f32_16x16x32_bf16 v[0:3], v[190:193], v[232:235], v[0:3]
	s_setprio 0
	s_barrier
; #define PG8_STAGE(bufoff, gbase, voff) do { _Pragma("unroll") for (int _i = 0; _i < 2; ++_i) \
;         __builtin_amdgcn_global_load_lds((const unsigned*)((const char*)(gbase) + (voff)[_i]), (PG8_LAS unsigned*)(lds + (bufoff) + ldsw + _i * 8192), 16, 0, 0); } while (0)
; #define PG8_LDA(dst, b, h) do { _Pragma("unroll") for (int m = 0; m < 4; ++m) _Pragma("unroll") for (int k = 0; k < 2; ++k) dst[m][k] = *(const PG8_LAS bf16x8*)(lds + PG8_SA(b, h) + aoff + m * 2048 + k * 1024); } while (0)
; #define PG8_LDB(dst, b, h) do { _Pragma("unroll") for (int n = 0; n < 2; ++n) _Pragma("unroll") for (int k = 0; k < 2; ++k) dst[n][k] = *(const PG8_LAS bf16x8*)(lds + PG8_SB(b, h) + boff + n * 2048 + k * 1024); } while (0)
; #define PG8_MMA(ai, bj, At, Bt) do { __builtin_amdgcn_s_setprio(1); _Pragma("unroll") for (int m = 0; m < 4; ++m) _Pragma("unroll") for (int n = 0; n < 2; ++n) _Pragma("unroll") for (int k = 0; k < 2; ++k) \
;         acc[ai][bj][m][n] = __builtin_amdgcn_mfma_f32_16x16x32_bf16(Bt[n][k], At[m][k], acc[ai][bj][m][n], 0, 0, 0); __builtin_amdgcn_s_setprio(0); } while (0)
; #define PG8_WAIT_V(n) asm volatile("s_waitcnt vmcnt(" #n ")" ::: "memory")
; #define PG8_WAIT_L(n) asm volatile("s_waitcnt lgkmcnt(" #n ")" ::: "memory")
; #define PG8_BAR __builtin_amdgcn_s_barrier()
; #define PG8_SCHED __builtin_amdgcn_sched_barrier(0)
; template <class Epi, class Sched, bool ALIGN_EPI = false, bool SP2 = false>
; __device__ __forceinline__ void gemm_phase(PG8_LAS unsigned char* lds, const Gemm g, const Sched& S, const Epi& E, const int wave0) {
;     ...
;             PG8_LDB(B0, 1, 0); PG8_LDB(B1, 1, 1); PG8_SCHED; PG8_LDA(At, 1, 0); PG8_STAGE(PG8_SA(0, 1), a2 + hstepA, voffA);
;             PG8_WAIT_V(8); PG8_WAIT_L(0); PG8_BAR; PG8_MMA(0, 0, At, B0); PG8_MMA(0, 1, At, B1); PG8_BAR; PG8_SCHED;
;             PG8_LDA(At, 1, 1); PG8_STAGE(PG8_SB(1, 0), b3, voffB); PG8_STAGE(PG8_SB(1, 1), b3 + hstepB, voffB); PG8_STAGE(PG8_SA(1, 0), a3, voffA);
;             PG8_WAIT_V(8); PG8_WAIT_L(0); PG8_BAR; PG8_MMA(1, 0, At, B0); PG8_MMA(1, 1, At, B1); PG8_BAR; PG8_SCHED;
	s_add_i32 s38, 0, 0x18000
	s_add_i32 s39, 0, 0x1c000
	ds_read_b128 v[144:147], v254
	ds_read_b128 v[148:151], v254 offset:1024
	ds_read_b128 v[152:155], v254 offset:2048
	ds_read_b128 v[156:159], v254 offset:3072
	ds_read_b128 v[178:181], v255
	ds_read_b128 v[182:185], v255 offset:1024
	ds_read_b128 v[186:189], v255 offset:2048
	ds_read_b128 v[190:193], v255 offset:3072
	s_add_u32 s18, s18, 0x80000
	s_addc_u32 s19, s19, 0
	s_mov_b32 m0, s25
	ds_read_b128 v[194:197], v143 offset:32768
	ds_read_b128 v[208:211], v143 offset:33792
	ds_read_b128 v[212:215], v143 offset:34816
	ds_read_b128 v[216:219], v143 offset:35840
	ds_read_b128 v[220:223], v143 offset:36864
	ds_read_b128 v[224:227], v143 offset:37888
	ds_read_b128 v[228:231], v143 offset:38912
	ds_read_b128 v[232:235], v143 offset:39936
	global_load_lds_dwordx4 v134, s[18:19]
	s_mov_b32 m0, s26
	s_nop 0
	global_load_lds_dwordx4 v132, s[18:19]
	s_waitcnt vmcnt(8)
	s_waitcnt lgkmcnt(0)
	s_barrier
	s_setprio 1
	s_waitcnt lgkmcnt(0)
	v_mfma_f32_16x16x32_bf16 v[126:129], v[144:147], v[194:197], v[126:129]
	v_mfma_f32_16x16x32_bf16 v[122:125], v[152:155], v[194:197], v[122:125]
	v_mfma_f32_16x16x32_bf16 v[118:121], v[144:147], v[212:215], v[118:121]
	v_mfma_f32_16x16x32_bf16 v[114:117], v[152:155], v[212:215], v[114:117]
	v_mfma_f32_16x16x32_bf16 v[102:105], v[144:147], v[220:223], v[102:105]
	v_mfma_f32_16x16x32_bf16 v[98:101], v[152:155], v[220:223], v[98:101]
	v_mfma_f32_16x16x32_bf16 v[86:89], v[144:147], v[228:231], v[86:89]
	v_mfma_f32_16x16x32_bf16 v[82:85], v[152:155], v[228:231], v[82:85]
	s_setprio 0
	s_setprio 1
	v_mfma_f32_16x16x32_bf16 v[126:129], v[148:151], v[208:211], v[126:129]
	v_mfma_f32_16x16x32_bf16 v[122:125], v[156:159], v[208:211], v[122:125]
	v_mfma_f32_16x16x32_bf16 v[118:121], v[148:151], v[216:219], v[118:121]
	v_mfma_f32_16x16x32_bf16 v[114:117], v[156:159], v[216:219], v[114:117]
	v_mfma_f32_16x16x32_bf16 v[102:105], v[148:151], v[224:227], v[102:105]
	v_mfma_f32_16x16x32_bf16 v[98:101], v[156:159], v[224:227], v[98:101]
	v_mfma_f32_16x16x32_bf16 v[86:89], v[148:151], v[232:235], v[86:89]
	v_mfma_f32_16x16x32_bf16 v[82:85], v[156:159], v[232:235], v[82:85]
	s_setprio 0
	s_setprio 1
	v_mfma_f32_16x16x32_bf16 v[110:113], v[178:181], v[194:197], v[110:113]
	v_mfma_f32_16x16x32_bf16 v[106:109], v[186:189], v[194:197], v[106:109]
	v_mfma_f32_16x16x32_bf16 v[94:97], v[178:181], v[212:215], v[94:97]
	v_mfma_f32_16x16x32_bf16 v[90:93], v[186:189], v[212:215], v[90:93]
	v_mfma_f32_16x16x32_bf16 v[78:81], v[178:181], v[220:223], v[78:81]
	v_mfma_f32_16x16x32_bf16 v[74:77], v[186:189], v[220:223], v[74:77]
	v_mfma_f32_16x16x32_bf16 v[70:73], v[178:181], v[228:231], v[70:73]
	v_mfma_f32_16x16x32_bf16 v[66:69], v[186:189], v[228:231], v[66:69]
	s_setprio 0
	s_setprio 1
	v_mfma_f32_16x16x32_bf16 v[110:113], v[182:185], v[208:211], v[110:113]
	v_mfma_f32_16x16x32_bf16 v[106:109], v[190:193], v[208:211], v[106:109]
	v_mfma_f32_16x16x32_bf16 v[94:97], v[182:185], v[216:219], v[94:97]
	v_mfma_f32_16x16x32_bf16 v[90:93], v[190:193], v[216:219], v[90:93]
	v_mfma_f32_16x16x32_bf16 v[78:81], v[182:185], v[224:227], v[78:81]
	v_mfma_f32_16x16x32_bf16 v[74:77], v[190:193], v[224:227], v[74:77]
	v_mfma_f32_16x16x32_bf16 v[70:73], v[182:185], v[232:235], v[70:73]
	v_mfma_f32_16x16x32_bf16 v[66:69], v[190:193], v[232:235], v[66:69]
	s_setprio 0
	s_barrier
	s_add_i32 s18, s38, s22
	s_add_u32 s42, s16, 0x80
	s_addc_u32 s43, s17, 0
	s_mov_b32 m0, s18
	ds_read_b128 v[194:197], v143 offset:49152
	ds_read_b128 v[208:211], v143 offset:50176
	ds_read_b128 v[212:215], v143 offset:51200
	ds_read_b128 v[216:219], v143 offset:52224
	ds_read_b128 v[220:223], v143 offset:53248
	ds_read_b128 v[224:227], v143 offset:54272
	ds_read_b128 v[228:231], v143 offset:55296
	ds_read_b128 v[232:235], v143 offset:56320
	global_load_lds_dwordx4 v64, s[42:43]
	s_add_i32 m0, s18, 0x2000
	s_add_u32 s16, s16, 0x80080
	s_addc_u32 s17, s17, 0
	s_add_i32 s18, s39, s22
	global_load_lds_dwordx4 v130, s[42:43]
	s_mov_b32 m0, s18
	s_nop 0
	global_load_lds_dwordx4 v64, s[16:17]
	s_add_i32 m0, s18, 0x2000
	s_nop 0
	global_load_lds_dwordx4 v130, s[16:17]
	s_add_u32 s100, s100, 0x80
	s_addc_u32 s101, s101, 0
	s_mov_b32 m0, s27
	s_nop 0
	global_load_lds_dwordx4 v134, s[100:101]
	s_mov_b32 m0, s28
	s_nop 0
	global_load_lds_dwordx4 v132, s[100:101]
	s_waitcnt vmcnt(8)
	s_waitcnt lgkmcnt(0)
	s_barrier
	s_setprio 1
	s_waitcnt lgkmcnt(0)
	v_mfma_f32_16x16x32_bf16 v[60:63], v[144:147], v[194:197], v[60:63]
	v_mfma_f32_16x16x32_bf16 v[56:59], v[152:155], v[194:197], v[56:59]
	v_mfma_f32_16x16x32_bf16 v[52:55], v[144:147], v[212:215], v[52:55]
	v_mfma_f32_16x16x32_bf16 v[48:51], v[152:155], v[212:215], v[48:51]
	v_mfma_f32_16x16x32_bf16 v[36:39], v[144:147], v[220:223], v[36:39]
	v_mfma_f32_16x16x32_bf16 v[32:35], v[152:155], v[220:223], v[32:35]
	v_mfma_f32_16x16x32_bf16 v[20:23], v[144:147], v[228:231], v[20:23]
	v_mfma_f32_16x16x32_bf16 v[16:19], v[152:155], v[228:231], v[16:19]
	s_setprio 0
	s_setprio 1
	v_mfma_f32_16x16x32_bf16 v[60:63], v[148:151], v[208:211], v[60:63]
	v_mfma_f32_16x16x32_bf16 v[56:59], v[156:159], v[208:211], v[56:59]
	v_mfma_f32_16x16x32_bf16 v[52:55], v[148:151], v[216:219], v[52:55]
	v_mfma_f32_16x16x32_bf16 v[48:51], v[156:159], v[216:219], v[48:51]
	v_mfma_f32_16x16x32_bf16 v[36:39], v[148:151], v[224:227], v[36:39]
	v_mfma_f32_16x16x32_bf16 v[32:35], v[156:159], v[224:227], v[32:35]
	v_mfma_f32_16x16x32_bf16 v[20:23], v[148:151], v[232:235], v[20:23]
	v_mfma_f32_16x16x32_bf16 v[16:19], v[156:159], v[232:235], v[16:19]
	s_setprio 0
	s_setprio 1
	v_mfma_f32_16x16x32_bf16 v[44:47], v[178:181], v[194:197], v[44:47]
	v_mfma_f32_16x16x32_bf16 v[40:43], v[186:189], v[194:197], v[40:43]
	v_mfma_f32_16x16x32_bf16 v[28:31], v[178:181], v[212:215], v[28:31]
	v_mfma_f32_16x16x32_bf16 v[24:27], v[186:189], v[212:215], v[24:27]
	v_mfma_f32_16x16x32_bf16 v[12:15], v[178:181], v[220:223], v[12:15]
	v_mfma_f32_16x16x32_bf16 v[8:11], v[186:189], v[220:223], v[8:11]
	v_mfma_f32_16x16x32_bf16 v[4:7], v[178:181], v[228:231], v[4:7]
	v_mfma_f32_16x16x32_bf16 v[0:3], v[186:189], v[228:231], v[0:3]
	s_setprio 0
	s_setprio 1
	v_mfma_f32_16x16x32_bf16 v[44:47], v[182:185], v[208:211], v[44:47]
	v_mfma_f32_16x16x32_bf16 v[40:43], v[190:193], v[208:211], v[40:43]
	v_mfma_f32_16x16x32_bf16 v[28:31], v[182:185], v[216:219], v[28:31]
	v_mfma_f32_16x16x32_bf16 v[24:27], v[190:193], v[216:219], v[24:27]
	v_mfma_f32_16x16x32_bf16 v[12:15], v[182:185], v[224:227], v[12:15]
	v_mfma_f32_16x16x32_bf16 v[8:11], v[190:193], v[224:227], v[8:11]
	v_mfma_f32_16x16x32_bf16 v[4:7], v[182:185], v[232:235], v[4:7]
	v_mfma_f32_16x16x32_bf16 v[0:3], v[190:193], v[232:235], v[0:3]
	s_setprio 0
	s_barrier
	s_add_i32 s37, s37, 2
	s_add_u32 s0, s0, 0x100
	s_addc_u32 s1, s1, 0
	s_add_u32 s35, s35, 0x100
	s_addc_u32 s36, s36, 0
	s_cmp_gt_u32 s37, 29
	s_cbranch_scc0 .LBB0_316
	s_mov_b64 s[42:43], 0x80
	s_and_b64 vcc, exec, s[6:7]
	s_mov_b64 s[34:35], 0x45000
	s_cbranch_vccz .LBB0_319
	s_barrier

; #define PG8_STAGE(bufoff, gbase, voff) do { _Pragma("unroll") for (int _i = 0; _i < 2; ++_i) \
;         __builtin_amdgcn_global_load_lds((const unsigned*)((const char*)(gbase) + (voff)[_i]), (PG8_LAS unsigned*)(lds + (bufoff) + ldsw + _i * 8192), 16, 0, 0); } while (0)
; #define PG8_LDA(dst, b, h) do { _Pragma("unroll") for (int m = 0; m < 4; ++m) _Pragma("unroll") for (int k = 0; k < 2; ++k) dst[m][k] = *(const PG8_LAS bf16x8*)(lds + PG8_SA(b, h) + aoff + m * 2048 + k * 1024); } while (0)
; #define PG8_LDB(dst, b, h) do { _Pragma("unroll") for (int n = 0; n < 2; ++n) _Pragma("unroll") for (int k = 0; k < 2; ++k) dst[n][k] = *(const PG8_LAS bf16x8*)(lds + PG8_SB(b, h) + boff + n * 2048 + k * 1024); } while (0)
; #define PG8_MMA(ai, bj, At, Bt) do { __builtin_amdgcn_s_setprio(1); _Pragma("unroll") for (int m = 0; m < 4; ++m) _Pragma("unroll") for (int n = 0; n < 2; ++n) _Pragma("unroll") for (int k = 0; k < 2; ++k) \
;         acc[ai][bj][m][n] = __builtin_amdgcn_mfma_f32_16x16x32_bf16(Bt[n][k], At[m][k], acc[ai][bj][m][n], 0, 0, 0); __builtin_amdgcn_s_setprio(0); } while (0)
; #define PG8_WAIT_V(n) asm volatile("s_waitcnt vmcnt(" #n ")" ::: "memory")
; #define PG8_WAIT_L(n) asm volatile("s_waitcnt lgkmcnt(" #n ")" ::: "memory")
; template <class Epi, class Sched, bool ALIGN_EPI = false, bool SP2 = false>
; __device__ __forceinline__ void gemm_phase(PG8_LAS unsigned char* lds, const Gemm g, const Sched& S, const Epi& E, const int wave0) {
;     ...
;             const bool last = (t == nt - 2);
;             const char* a1 = cA + (size_t)(t + 1) * kstep;
;             const char* a2 = last ? nA : cA + (size_t)(t + 2) * kstep; const char* b2 = last ? nB : cB + (size_t)(t + 2) * kstep;
;             const char* a3 = a2 + kstep; const char* b3 = b2 + kstep;
;             if (last && has_next) S.a_ready(nxt);
;             if constexpr (SP2) {
;             PG8_LDB(B0, 0, 0); PG8_LDB(B1, 0, 1); PG8_SCHED; PG8_LDA(At, 0, 0); PG8_STAGE(PG8_SA(1, 1), a1 + hstepA, voffA);
;             PG8_WAIT_V(8); PG8_WAIT_L(0); PG8_BAR; PG8_MMA(0, 0, At, B0); PG8_MMA(0, 1, At, B1); PG8_BAR; PG8_SCHED;
;             PG8_LDA(At, 0, 1); PG8_STAGE(PG8_SB(0, 0), b2, voffB); PG8_STAGE(PG8_SB(0, 1), b2 + hstepB, voffB); PG8_STAGE(PG8_SA(0, 0), a2, voffA);
;             PG8_WAIT_V(8); PG8_WAIT_L(0); PG8_BAR; PG8_MMA(1, 0, At, B0); PG8_MMA(1, 1, At, B1); PG8_BAR; PG8_SCHED;
.LBB0_1178:
	s_add_u32 s2, s0, 0xfffc0080
	s_addc_u32 s3, s1, -1
	s_add_i32 s31, 0, 0x10000
	s_cmp_eq_u32 s19, 12
	s_cselect_b32 s17, s45, s3
	s_cselect_b32 s16, s44, s2
	s_cselect_b32 s3, s9, s18
	s_cselect_b32 s2, s11, s13
	s_add_i32 s33, 0, 0x14000
	ds_read_b128 v[130:133], v252
	ds_read_b128 v[134:137], v252 offset:1024
	ds_read_b128 v[148:151], v252 offset:2048
	ds_read_b128 v[152:155], v252 offset:3072
	ds_read_b128 v[178:181], v253
	ds_read_b128 v[182:185], v253 offset:1024
	ds_read_b128 v[186:189], v253 offset:2048
	ds_read_b128 v[190:193], v253 offset:3072
	s_add_i32 m0, s23, 0xc000
	ds_read_b128 v[194:197], v159
	ds_read_b128 v[208:211], v159 offset:1024
	ds_read_b128 v[212:215], v159 offset:2048
	ds_read_b128 v[216:219], v159 offset:3072
	ds_read_b128 v[220:223], v159 offset:4096
	ds_read_b128 v[224:227], v159 offset:5120
	ds_read_b128 v[228:231], v159 offset:6144
	ds_read_b128 v[232:235], v159 offset:7168
	global_load_lds_dwordx4 v144, s[0:1]
	s_add_i32 m0, s23, 0xe000
	s_nop 0
	global_load_lds_dwordx4 v146, s[0:1]
	s_waitcnt vmcnt(8)
	s_waitcnt lgkmcnt(0)
	s_barrier
	s_setprio 1
	s_waitcnt lgkmcnt(0)
	v_mfma_f32_16x16x32_bf16 v[126:129], v[130:133], v[194:197], v[126:129]
	v_mfma_f32_16x16x32_bf16 v[122:125], v[148:151], v[194:197], v[122:125]
	v_mfma_f32_16x16x32_bf16 v[110:113], v[130:133], v[212:215], v[110:113]
	v_mfma_f32_16x16x32_bf16 v[106:109], v[148:151], v[212:215], v[106:109]
	v_mfma_f32_16x16x32_bf16 v[94:97], v[130:133], v[220:223], v[94:97]
	v_mfma_f32_16x16x32_bf16 v[90:93], v[148:151], v[220:223], v[90:93]
	v_mfma_f32_16x16x32_bf16 v[78:81], v[130:133], v[228:231], v[78:81]
	v_mfma_f32_16x16x32_bf16 v[74:77], v[148:151], v[228:231], v[74:77]
	s_setprio 0
	s_setprio 1
	v_mfma_f32_16x16x32_bf16 v[126:129], v[134:137], v[208:211], v[126:129]
	v_mfma_f32_16x16x32_bf16 v[122:125], v[152:155], v[208:211], v[122:125]
	v_mfma_f32_16x16x32_bf16 v[110:113], v[134:137], v[216:219], v[110:113]
	v_mfma_f32_16x16x32_bf16 v[106:109], v[152:155], v[216:219], v[106:109]
	v_mfma_f32_16x16x32_bf16 v[94:97], v[134:137], v[224:227], v[94:97]
	v_mfma_f32_16x16x32_bf16 v[90:93], v[152:155], v[224:227], v[90:93]
	v_mfma_f32_16x16x32_bf16 v[78:81], v[134:137], v[232:235], v[78:81]
	v_mfma_f32_16x16x32_bf16 v[74:77], v[152:155], v[232:235], v[74:77]
	s_setprio 0
	s_setprio 1
	v_mfma_f32_16x16x32_bf16 v[118:121], v[178:181], v[194:197], v[118:121]
	v_mfma_f32_16x16x32_bf16 v[114:117], v[186:189], v[194:197], v[114:117]
	v_mfma_f32_16x16x32_bf16 v[102:105], v[178:181], v[212:215], v[102:105]
	v_mfma_f32_16x16x32_bf16 v[98:101], v[186:189], v[212:215], v[98:101]
	v_mfma_f32_16x16x32_bf16 v[86:89], v[178:181], v[220:223], v[86:89]
	v_mfma_f32_16x16x32_bf16 v[82:85], v[186:189], v[220:223], v[82:85]
	v_mfma_f32_16x16x32_bf16 v[70:73], v[178:181], v[228:231], v[70:73]
	v_mfma_f32_16x16x32_bf16 v[66:69], v[186:189], v[228:231], v[66:69]
	s_setprio 0
	s_setprio 1
	v_mfma_f32_16x16x32_bf16 v[118:121], v[182:185], v[208:211], v[118:121]
	v_mfma_f32_16x16x32_bf16 v[114:117], v[190:193], v[208:211], v[114:117]
	v_mfma_f32_16x16x32_bf16 v[102:105], v[182:185], v[216:219], v[102:105]
	v_mfma_f32_16x16x32_bf16 v[98:101], v[190:193], v[216:219], v[98:101]
	v_mfma_f32_16x16x32_bf16 v[86:89], v[182:185], v[224:227], v[86:89]
	v_mfma_f32_16x16x32_bf16 v[82:85], v[190:193], v[224:227], v[82:85]
	v_mfma_f32_16x16x32_bf16 v[70:73], v[182:185], v[232:235], v[70:73]
	v_mfma_f32_16x16x32_bf16 v[66:69], v[190:193], v[232:235], v[66:69]
	s_setprio 0
	s_barrier
	s_add_i32 s31, s31, s22
	s_mov_b32 m0, s31
	ds_read_b128 v[194:197], v159 offset:16384
	ds_read_b128 v[208:211], v159 offset:17408
	ds_read_b128 v[212:215], v159 offset:18432
	ds_read_b128 v[216:219], v159 offset:19456
	ds_read_b128 v[220:223], v159 offset:20480
	ds_read_b128 v[224:227], v159 offset:21504
	ds_read_b128 v[228:231], v159 offset:22528
	ds_read_b128 v[232:235], v159 offset:23552
	global_load_lds_dwordx4 v64, s[2:3]
	s_add_i32 m0, s31, 0x2000
	s_add_u32 s34, s2, 0x40000
	s_addc_u32 s35, s3, 0
	s_add_i32 s31, s33, s22
	global_load_lds_dwordx4 v138, s[2:3]
	s_mov_b32 m0, s31
	s_mov_b64 s[100:101], s[16:17]
	global_load_lds_dwordx4 v64, s[34:35]
	s_add_i32 m0, s31, 0x2000
	s_nop 0
	global_load_lds_dwordx4 v138, s[34:35]
	s_mov_b32 m0, s23
	s_nop 0
	global_load_lds_dwordx4 v142, s[16:17]
	s_mov_b32 m0, s24
	s_nop 0
	global_load_lds_dwordx4 v140, s[16:17]
	s_waitcnt vmcnt(8)
	s_waitcnt lgkmcnt(0)
	s_barrier
	s_setprio 1
	s_waitcnt lgkmcnt(0)
	v_mfma_f32_16x16x32_bf16 v[60:63], v[130:133], v[194:197], v[60:63]
	v_mfma_f32_16x16x32_bf16 v[56:59], v[148:151], v[194:197], v[56:59]
	v_mfma_f32_16x16x32_bf16 v[44:47], v[130:133], v[212:215], v[44:47]
	v_mfma_f32_16x16x32_bf16 v[40:43], v[148:151], v[212:215], v[40:43]
	v_mfma_f32_16x16x32_bf16 v[28:31], v[130:133], v[220:223], v[28:31]
	v_mfma_f32_16x16x32_bf16 v[24:27], v[148:151], v[220:223], v[24:27]
	v_mfma_f32_16x16x32_bf16 v[12:15], v[130:133], v[228:231], v[12:15]
	v_mfma_f32_16x16x32_bf16 v[8:11], v[148:151], v[228:231], v[8:11]
	s_setprio 0
	s_setprio 1
	v_mfma_f32_16x16x32_bf16 v[60:63], v[134:137], v[208:211], v[60:63]
	v_mfma_f32_16x16x32_bf16 v[56:59], v[152:155], v[208:211], v[56:59]
	v_mfma_f32_16x16x32_bf16 v[44:47], v[134:137], v[216:219], v[44:47]
	v_mfma_f32_16x16x32_bf16 v[40:43], v[152:155], v[216:219], v[40:43]
	v_mfma_f32_16x16x32_bf16 v[28:31], v[134:137], v[224:227], v[28:31]
	v_mfma_f32_16x16x32_bf16 v[24:27], v[152:155], v[224:227], v[24:27]
	v_mfma_f32_16x16x32_bf16 v[12:15], v[134:137], v[232:235], v[12:15]
	v_mfma_f32_16x16x32_bf16 v[8:11], v[152:155], v[232:235], v[8:11]
	s_setprio 0
	s_setprio 1
	v_mfma_f32_16x16x32_bf16 v[52:55], v[178:181], v[194:197], v[52:55]
	v_mfma_f32_16x16x32_bf16 v[48:51], v[186:189], v[194:197], v[48:51]
	v_mfma_f32_16x16x32_bf16 v[36:39], v[178:181], v[212:215], v[36:39]
	v_mfma_f32_16x16x32_bf16 v[32:35], v[186:189], v[212:215], v[32:35]
	v_mfma_f32_16x16x32_bf16 v[20:23], v[178:181], v[220:223], v[20:23]
	v_mfma_f32_16x16x32_bf16 v[16:19], v[186:189], v[220:223], v[16:19]
	v_mfma_f32_16x16x32_bf16 v[4:7], v[178:181], v[228:231], v[4:7]
	v_mfma_f32_16x16x32_bf16 v[0:3], v[186:189], v[228:231], v[0:3]
	s_setprio 0
	s_setprio 1
	v_mfma_f32_16x16x32_bf16 v[52:55], v[182:185], v[208:211], v[52:55]
	v_mfma_f32_16x16x32_bf16 v[48:51], v[190:193], v[208:211], v[48:51]
	v_mfma_f32_16x16x32_bf16 v[36:39], v[182:185], v[216:219], v[36:39]
	v_mfma_f32_16x16x32_bf16 v[32:35], v[190:193], v[216:219], v[32:35]
	v_mfma_f32_16x16x32_bf16 v[20:23], v[182:185], v[224:227], v[20:23]
	v_mfma_f32_16x16x32_bf16 v[16:19], v[190:193], v[224:227], v[16:19]
	v_mfma_f32_16x16x32_bf16 v[4:7], v[182:185], v[232:235], v[4:7]
	v_mfma_f32_16x16x32_bf16 v[0:3], v[190:193], v[232:235], v[0:3]
	s_setprio 0
	s_barrier
; #define PG8_STAGE(bufoff, gbase, voff) do { _Pragma("unroll") for (int _i = 0; _i < 2; ++_i) \
;         __builtin_amdgcn_global_load_lds((const unsigned*)((const char*)(gbase) + (voff)[_i]), (PG8_LAS unsigned*)(lds + (bufoff) + ldsw + _i * 8192), 16, 0, 0); } while (0)
; #define PG8_LDA(dst, b, h) do { _Pragma("unroll") for (int m = 0; m < 4; ++m) _Pragma("unroll") for (int k = 0; k < 2; ++k) dst[m][k] = *(const PG8_LAS bf16x8*)(lds + PG8_SA(b, h) + aoff + m * 2048 + k * 1024); } while (0)
; #define PG8_LDB(dst, b, h) do { _Pragma("unroll") for (int n = 0; n < 2; ++n) _Pragma("unroll") for (int k = 0; k < 2; ++k) dst[n][k] = *(const PG8_LAS bf16x8*)(lds + PG8_SB(b, h) + boff + n * 2048 + k * 1024); } while (0)
; #define PG8_MMA(ai, bj, At, Bt) do { __builtin_amdgcn_s_setprio(1); _Pragma("unroll") for (int m = 0; m < 4; ++m) _Pragma("unroll") for (int n = 0; n < 2; ++n) _Pragma("unroll") for (int k = 0; k < 2; ++k) \
;         acc[ai][bj][m][n] = __builtin_amdgcn_mfma_f32_16x16x32_bf16(Bt[n][k], At[m][k], acc[ai][bj][m][n], 0, 0, 0); __builtin_amdgcn_s_setprio(0); } while (0)
; #define PG8_WAIT_V(n) asm volatile("s_waitcnt vmcnt(" #n ")" ::: "memory")
; #define PG8_WAIT_L(n) asm volatile("s_waitcnt lgkmcnt(" #n ")" ::: "memory")
; #define PG8_BAR __builtin_amdgcn_s_barrier()
; #define PG8_SCHED __builtin_amdgcn_sched_barrier(0)
; template <class Epi, class Sched, bool ALIGN_EPI = false, bool SP2 = false>
; __device__ __forceinline__ void gemm_phase(PG8_LAS unsigned char* lds, const Gemm g, const Sched& S, const Epi& E, const int wave0) {
;     ...
;             PG8_LDB(B0, 1, 0); PG8_LDB(B1, 1, 1); PG8_SCHED; PG8_LDA(At, 1, 0); PG8_STAGE(PG8_SA(0, 1), a2 + hstepA, voffA);
;             PG8_WAIT_V(8); PG8_WAIT_L(0); PG8_BAR; PG8_MMA(0, 0, At, B0); PG8_MMA(0, 1, At, B1); PG8_BAR; PG8_SCHED;
;             PG8_LDA(At, 1, 1); PG8_STAGE(PG8_SB(1, 0), b3, voffB); PG8_STAGE(PG8_SB(1, 1), b3 + hstepB, voffB); PG8_STAGE(PG8_SA(1, 0), a3, voffA);
;             PG8_WAIT_V(8); PG8_WAIT_L(0); PG8_BAR; PG8_MMA(1, 0, At, B0); PG8_MMA(1, 1, At, B1); PG8_BAR; PG8_SCHED;
;     ...
;         if constexpr (ALIGN_EPI) { if (wr == 0) PG8_BAR; }
	s_add_i32 s31, 0, 0x18000
	s_add_i32 s33, 0, 0x1c000
	ds_read_b128 v[130:133], v254
	ds_read_b128 v[134:137], v254 offset:1024
	ds_read_b128 v[148:151], v254 offset:2048
	ds_read_b128 v[152:155], v254 offset:3072
	ds_read_b128 v[178:181], v255
	ds_read_b128 v[182:185], v255 offset:1024
	ds_read_b128 v[186:189], v255 offset:2048
	ds_read_b128 v[190:193], v255 offset:3072
	s_add_u32 s16, s16, 0x40000
	s_addc_u32 s17, s17, 0
	s_mov_b32 m0, s25
	ds_read_b128 v[194:197], v159 offset:32768
	ds_read_b128 v[208:211], v159 offset:33792
	ds_read_b128 v[212:215], v159 offset:34816
	ds_read_b128 v[216:219], v159 offset:35840
	ds_read_b128 v[220:223], v159 offset:36864
	ds_read_b128 v[224:227], v159 offset:37888
	ds_read_b128 v[228:231], v159 offset:38912
	ds_read_b128 v[232:235], v159 offset:39936
	global_load_lds_dwordx4 v142, s[16:17]
	s_mov_b32 m0, s26
	s_nop 0
	global_load_lds_dwordx4 v140, s[16:17]
	s_waitcnt vmcnt(8)
	s_waitcnt lgkmcnt(0)
	s_barrier
	s_setprio 1
	s_waitcnt lgkmcnt(0)
	v_mfma_f32_16x16x32_bf16 v[126:129], v[130:133], v[194:197], v[126:129]
	v_mfma_f32_16x16x32_bf16 v[122:125], v[148:151], v[194:197], v[122:125]
	v_mfma_f32_16x16x32_bf16 v[110:113], v[130:133], v[212:215], v[110:113]
	v_mfma_f32_16x16x32_bf16 v[106:109], v[148:151], v[212:215], v[106:109]
	v_mfma_f32_16x16x32_bf16 v[94:97], v[130:133], v[220:223], v[94:97]
	v_mfma_f32_16x16x32_bf16 v[90:93], v[148:151], v[220:223], v[90:93]
	v_mfma_f32_16x16x32_bf16 v[78:81], v[130:133], v[228:231], v[78:81]
	v_mfma_f32_16x16x32_bf16 v[74:77], v[148:151], v[228:231], v[74:77]
	s_setprio 0
	s_setprio 1
	v_mfma_f32_16x16x32_bf16 v[126:129], v[134:137], v[208:211], v[126:129]
	v_mfma_f32_16x16x32_bf16 v[122:125], v[152:155], v[208:211], v[122:125]
	v_mfma_f32_16x16x32_bf16 v[110:113], v[134:137], v[216:219], v[110:113]
	v_mfma_f32_16x16x32_bf16 v[106:109], v[152:155], v[216:219], v[106:109]
	v_mfma_f32_16x16x32_bf16 v[94:97], v[134:137], v[224:227], v[94:97]
	v_mfma_f32_16x16x32_bf16 v[90:93], v[152:155], v[224:227], v[90:93]
	v_mfma_f32_16x16x32_bf16 v[78:81], v[134:137], v[232:235], v[78:81]
	v_mfma_f32_16x16x32_bf16 v[74:77], v[152:155], v[232:235], v[74:77]
	s_setprio 0
	s_setprio 1
	v_mfma_f32_16x16x32_bf16 v[118:121], v[178:181], v[194:197], v[118:121]
	v_mfma_f32_16x16x32_bf16 v[114:117], v[186:189], v[194:197], v[114:117]
	v_mfma_f32_16x16x32_bf16 v[102:105], v[178:181], v[212:215], v[102:105]
	v_mfma_f32_16x16x32_bf16 v[98:101], v[186:189], v[212:215], v[98:101]
	v_mfma_f32_16x16x32_bf16 v[86:89], v[178:181], v[220:223], v[86:89]
	v_mfma_f32_16x16x32_bf16 v[82:85], v[186:189], v[220:223], v[82:85]
	v_mfma_f32_16x16x32_bf16 v[70:73], v[178:181], v[228:231], v[70:73]
	v_mfma_f32_16x16x32_bf16 v[66:69], v[186:189], v[228:231], v[66:69]
	s_setprio 0
	s_setprio 1
	v_mfma_f32_16x16x32_bf16 v[118:121], v[182:185], v[208:211], v[118:121]
	v_mfma_f32_16x16x32_bf16 v[114:117], v[190:193], v[208:211], v[114:117]
	v_mfma_f32_16x16x32_bf16 v[102:105], v[182:185], v[216:219], v[102:105]
	v_mfma_f32_16x16x32_bf16 v[98:101], v[190:193], v[216:219], v[98:101]
	v_mfma_f32_16x16x32_bf16 v[86:89], v[182:185], v[224:227], v[86:89]
	v_mfma_f32_16x16x32_bf16 v[82:85], v[190:193], v[224:227], v[82:85]
	v_mfma_f32_16x16x32_bf16 v[70:73], v[182:185], v[232:235], v[70:73]
	v_mfma_f32_16x16x32_bf16 v[66:69], v[190:193], v[232:235], v[66:69]
	s_setprio 0
	s_barrier
	s_add_i32 s16, s31, s22
	s_add_u32 s36, s2, 0x80
	s_addc_u32 s37, s3, 0
	s_mov_b32 m0, s16
	ds_read_b128 v[194:197], v159 offset:49152
	ds_read_b128 v[208:211], v159 offset:50176
	ds_read_b128 v[212:215], v159 offset:51200
	ds_read_b128 v[216:219], v159 offset:52224
	ds_read_b128 v[220:223], v159 offset:53248
	ds_read_b128 v[224:227], v159 offset:54272
	ds_read_b128 v[228:231], v159 offset:55296
	ds_read_b128 v[232:235], v159 offset:56320
	global_load_lds_dwordx4 v64, s[36:37]
	s_add_i32 m0, s16, 0x2000
	s_add_u32 s2, s2, 0x40080
	s_addc_u32 s3, s3, 0
	s_add_i32 s16, s33, s22
	global_load_lds_dwordx4 v138, s[36:37]
	s_mov_b32 m0, s16
	s_nop 0
	global_load_lds_dwordx4 v64, s[2:3]
	s_add_i32 m0, s16, 0x2000
	s_nop 0
	global_load_lds_dwordx4 v138, s[2:3]
	s_add_u32 s100, s100, 0x80
	s_addc_u32 s101, s101, 0
	s_mov_b32 m0, s27
	s_nop 0
	global_load_lds_dwordx4 v142, s[100:101]
	s_mov_b32 m0, s28
	s_nop 0
	global_load_lds_dwordx4 v140, s[100:101]
	s_waitcnt vmcnt(8)
	s_waitcnt lgkmcnt(0)
	s_barrier
	s_setprio 1
	s_waitcnt lgkmcnt(0)
	v_mfma_f32_16x16x32_bf16 v[60:63], v[130:133], v[194:197], v[60:63]
	v_mfma_f32_16x16x32_bf16 v[56:59], v[148:151], v[194:197], v[56:59]
	v_mfma_f32_16x16x32_bf16 v[44:47], v[130:133], v[212:215], v[44:47]
	v_mfma_f32_16x16x32_bf16 v[40:43], v[148:151], v[212:215], v[40:43]
	v_mfma_f32_16x16x32_bf16 v[28:31], v[130:133], v[220:223], v[28:31]
	v_mfma_f32_16x16x32_bf16 v[24:27], v[148:151], v[220:223], v[24:27]
	v_mfma_f32_16x16x32_bf16 v[12:15], v[130:133], v[228:231], v[12:15]
	v_mfma_f32_16x16x32_bf16 v[8:11], v[148:151], v[228:231], v[8:11]
	s_setprio 0
	s_setprio 1
	v_mfma_f32_16x16x32_bf16 v[60:63], v[134:137], v[208:211], v[60:63]
	v_mfma_f32_16x16x32_bf16 v[56:59], v[152:155], v[208:211], v[56:59]
	v_mfma_f32_16x16x32_bf16 v[44:47], v[134:137], v[216:219], v[44:47]
	v_mfma_f32_16x16x32_bf16 v[40:43], v[152:155], v[216:219], v[40:43]
	v_mfma_f32_16x16x32_bf16 v[28:31], v[134:137], v[224:227], v[28:31]
	v_mfma_f32_16x16x32_bf16 v[24:27], v[152:155], v[224:227], v[24:27]
	v_mfma_f32_16x16x32_bf16 v[12:15], v[134:137], v[232:235], v[12:15]
	v_mfma_f32_16x16x32_bf16 v[8:11], v[152:155], v[232:235], v[8:11]
	s_setprio 0
	s_setprio 1
	v_mfma_f32_16x16x32_bf16 v[52:55], v[178:181], v[194:197], v[52:55]
	v_mfma_f32_16x16x32_bf16 v[48:51], v[186:189], v[194:197], v[48:51]
	v_mfma_f32_16x16x32_bf16 v[36:39], v[178:181], v[212:215], v[36:39]
	v_mfma_f32_16x16x32_bf16 v[32:35], v[186:189], v[212:215], v[32:35]
	v_mfma_f32_16x16x32_bf16 v[20:23], v[178:181], v[220:223], v[20:23]
	v_mfma_f32_16x16x32_bf16 v[16:19], v[186:189], v[220:223], v[16:19]
	v_mfma_f32_16x16x32_bf16 v[4:7], v[178:181], v[228:231], v[4:7]
	v_mfma_f32_16x16x32_bf16 v[0:3], v[186:189], v[228:231], v[0:3]
	s_setprio 0
	s_setprio 1
	v_mfma_f32_16x16x32_bf16 v[52:55], v[182:185], v[208:211], v[52:55]
	v_mfma_f32_16x16x32_bf16 v[48:51], v[190:193], v[208:211], v[48:51]
	v_mfma_f32_16x16x32_bf16 v[36:39], v[182:185], v[216:219], v[36:39]
	v_mfma_f32_16x16x32_bf16 v[32:35], v[190:193], v[216:219], v[32:35]
	v_mfma_f32_16x16x32_bf16 v[20:23], v[182:185], v[224:227], v[20:23]
	v_mfma_f32_16x16x32_bf16 v[16:19], v[190:193], v[224:227], v[16:19]
	v_mfma_f32_16x16x32_bf16 v[4:7], v[182:185], v[232:235], v[4:7]
	v_mfma_f32_16x16x32_bf16 v[0:3], v[190:193], v[232:235], v[0:3]
	s_setprio 0
	s_barrier
	s_add_i32 s19, s19, 2
	s_add_u32 s0, s0, 0x100
	s_addc_u32 s1, s1, 0
	s_add_u32 s13, s13, 0x100
	s_addc_u32 s18, s18, 0
	s_cmp_gt_u32 s19, 13
	s_cbranch_scc0 .LBB0_1178
	s_mov_b64 s[36:37], 0x80
	s_and_b64 vcc, exec, s[6:7]
	s_cbranch_vccz .LBB0_1181
	s_barrier

; #define PG8_STAGE(bufoff, gbase, voff) do { _Pragma("unroll") for (int _i = 0; _i < 2; ++_i) \
;         __builtin_amdgcn_global_load_lds((const unsigned*)((const char*)(gbase) + (voff)[_i]), (PG8_LAS unsigned*)(lds + (bufoff) + ldsw + _i * 8192), 16, 0, 0); } while (0)
; #define PG8_LDA(dst, b, h) do { _Pragma("unroll") for (int m = 0; m < 4; ++m) _Pragma("unroll") for (int k = 0; k < 2; ++k) dst[m][k] = *(const PG8_LAS bf16x8*)(lds + PG8_SA(b, h) + aoff + m * 2048 + k * 1024); } while (0)
; #define PG8_LDB(dst, b, h) do { _Pragma("unroll") for (int n = 0; n < 2; ++n) _Pragma("unroll") for (int k = 0; k < 2; ++k) dst[n][k] = *(const PG8_LAS bf16x8*)(lds + PG8_SB(b, h) + boff + n * 2048 + k * 1024); } while (0)
; #define PG8_MMA(ai, bj, At, Bt) do { __builtin_amdgcn_s_setprio(1); _Pragma("unroll") for (int m = 0; m < 4; ++m) _Pragma("unroll") for (int n = 0; n < 2; ++n) _Pragma("unroll") for (int k = 0; k < 2; ++k) \
;         acc[ai][bj][m][n] = __builtin_amdgcn_mfma_f32_16x16x32_bf16(Bt[n][k], At[m][k], acc[ai][bj][m][n], 0, 0, 0); __builtin_amdgcn_s_setprio(0); } while (0)
; #define PG8_WAIT_V(n) asm volatile("s_waitcnt vmcnt(" #n ")" ::: "memory")
; #define PG8_BAR __builtin_amdgcn_s_barrier()
; template <class Epi, class Sched, bool ALIGN_EPI = false, bool SP2 = false>
; __device__ __forceinline__ void gemm_phase(PG8_LAS unsigned char* lds, const Gemm g, const Sched& S, const Epi& E, const int wave0) {
;     ...
;         for (int t = 0; t < nt; t += 2) {
;             const bool last = (t == nt - 2);
;             const char* a1 = cA + (size_t)(t + 1) * kstep;
;             const char* a2 = last ? nA : cA + (size_t)(t + 2) * kstep; const char* b2 = last ? nB : cB + (size_t)(t + 2) * kstep;
;             const char* a3 = a2 + kstep; const char* b3 = b2 + kstep;
;             if (last && has_next) S.a_ready(nxt);
;             if constexpr (SP2) {
;             PG8_LDB(B0, 0, 0); PG8_LDB(B1, 0, 1); PG8_SCHED; PG8_LDA(At, 0, 0); PG8_STAGE(PG8_SA(1, 1), a1 + hstepA, voffA);
;             PG8_WAIT_V(8); PG8_WAIT_L(0); PG8_BAR; PG8_MMA(0, 0, At, B0); PG8_MMA(0, 1, At, B1); PG8_BAR; PG8_SCHED;
;             PG8_LDA(At, 0, 1); PG8_STAGE(PG8_SB(0, 0), b2, voffB); PG8_STAGE(PG8_SB(0, 1), b2 + hstepB, voffB); PG8_STAGE(PG8_SA(0, 0), a2, voffA);
;             PG8_WAIT_V(8); PG8_WAIT_L(0); PG8_BAR; PG8_MMA(1, 0, At, B0); PG8_MMA(1, 1, At, B1); PG8_BAR; PG8_SCHED;
.LBB0_1231:
	s_add_u32 s2, s0, 0xfffc0080
	s_addc_u32 s3, s1, -1
	s_add_i32 s31, 0, 0x10000
	s_cmp_eq_u32 s19, 12
	s_cselect_b32 s17, s43, s3
	s_cselect_b32 s16, s42, s2
	s_cselect_b32 s3, s9, s18
	s_cselect_b32 s2, s11, s13
	s_add_i32 s33, 0, 0x14000
	ds_read_b128 v[140:143], v252
	ds_read_b128 v[144:147], v252 offset:1024
	ds_read_b128 v[154:157], v252 offset:2048
	ds_read_b128 v[158:161], v252 offset:3072
	ds_read_b128 v[178:181], v253
	ds_read_b128 v[182:185], v253 offset:1024
	ds_read_b128 v[186:189], v253 offset:2048
	ds_read_b128 v[190:193], v253 offset:3072
	s_add_i32 m0, s23, 0xc000
	ds_read_b128 v[194:197], v153
	ds_read_b128 v[208:211], v153 offset:1024
	ds_read_b128 v[212:215], v153 offset:2048
	ds_read_b128 v[216:219], v153 offset:3072
	ds_read_b128 v[220:223], v153 offset:4096
	ds_read_b128 v[224:227], v153 offset:5120
	ds_read_b128 v[228:231], v153 offset:6144
	ds_read_b128 v[232:235], v153 offset:7168
	global_load_lds_dwordx4 v136, s[0:1]
	s_add_i32 m0, s23, 0xe000
	s_nop 0
	global_load_lds_dwordx4 v138, s[0:1]
	s_waitcnt vmcnt(8)
	s_waitcnt lgkmcnt(0)
	s_barrier
	s_setprio 1
	s_waitcnt lgkmcnt(0)
	v_mfma_f32_16x16x32_bf16 v[126:129], v[140:143], v[194:197], v[126:129]
	v_mfma_f32_16x16x32_bf16 v[122:125], v[154:157], v[194:197], v[122:125]
	v_mfma_f32_16x16x32_bf16 v[110:113], v[140:143], v[212:215], v[110:113]
	v_mfma_f32_16x16x32_bf16 v[106:109], v[154:157], v[212:215], v[106:109]
	v_mfma_f32_16x16x32_bf16 v[94:97], v[140:143], v[220:223], v[94:97]
	v_mfma_f32_16x16x32_bf16 v[90:93], v[154:157], v[220:223], v[90:93]
	v_mfma_f32_16x16x32_bf16 v[78:81], v[140:143], v[228:231], v[78:81]
	v_mfma_f32_16x16x32_bf16 v[74:77], v[154:157], v[228:231], v[74:77]
	s_setprio 0
	s_setprio 1
	v_mfma_f32_16x16x32_bf16 v[126:129], v[144:147], v[208:211], v[126:129]
	v_mfma_f32_16x16x32_bf16 v[122:125], v[158:161], v[208:211], v[122:125]
	v_mfma_f32_16x16x32_bf16 v[110:113], v[144:147], v[216:219], v[110:113]
	v_mfma_f32_16x16x32_bf16 v[106:109], v[158:161], v[216:219], v[106:109]
	v_mfma_f32_16x16x32_bf16 v[94:97], v[144:147], v[224:227], v[94:97]
	v_mfma_f32_16x16x32_bf16 v[90:93], v[158:161], v[224:227], v[90:93]
	v_mfma_f32_16x16x32_bf16 v[78:81], v[144:147], v[232:235], v[78:81]
	v_mfma_f32_16x16x32_bf16 v[74:77], v[158:161], v[232:235], v[74:77]
	s_setprio 0
	s_setprio 1
	v_mfma_f32_16x16x32_bf16 v[118:121], v[178:181], v[194:197], v[118:121]
	v_mfma_f32_16x16x32_bf16 v[114:117], v[186:189], v[194:197], v[114:117]
	v_mfma_f32_16x16x32_bf16 v[102:105], v[178:181], v[212:215], v[102:105]
	v_mfma_f32_16x16x32_bf16 v[98:101], v[186:189], v[212:215], v[98:101]
	v_mfma_f32_16x16x32_bf16 v[86:89], v[178:181], v[220:223], v[86:89]
	v_mfma_f32_16x16x32_bf16 v[82:85], v[186:189], v[220:223], v[82:85]
	v_mfma_f32_16x16x32_bf16 v[70:73], v[178:181], v[228:231], v[70:73]
	v_mfma_f32_16x16x32_bf16 v[66:69], v[186:189], v[228:231], v[66:69]
	s_setprio 0
	s_setprio 1
	v_mfma_f32_16x16x32_bf16 v[118:121], v[182:185], v[208:211], v[118:121]
	v_mfma_f32_16x16x32_bf16 v[114:117], v[190:193], v[208:211], v[114:117]
	v_mfma_f32_16x16x32_bf16 v[102:105], v[182:185], v[216:219], v[102:105]
	v_mfma_f32_16x16x32_bf16 v[98:101], v[190:193], v[216:219], v[98:101]
	v_mfma_f32_16x16x32_bf16 v[86:89], v[182:185], v[224:227], v[86:89]
	v_mfma_f32_16x16x32_bf16 v[82:85], v[190:193], v[224:227], v[82:85]
	v_mfma_f32_16x16x32_bf16 v[70:73], v[182:185], v[232:235], v[70:73]
	v_mfma_f32_16x16x32_bf16 v[66:69], v[190:193], v[232:235], v[66:69]
	s_setprio 0
	s_barrier
	s_add_i32 s31, s31, s22
	s_mov_b32 m0, s31
	ds_read_b128 v[194:197], v153 offset:16384
	ds_read_b128 v[208:211], v153 offset:17408
	ds_read_b128 v[212:215], v153 offset:18432
	ds_read_b128 v[216:219], v153 offset:19456
	ds_read_b128 v[220:223], v153 offset:20480
	ds_read_b128 v[224:227], v153 offset:21504
	ds_read_b128 v[228:231], v153 offset:22528
	ds_read_b128 v[232:235], v153 offset:23552
	global_load_lds_dwordx4 v64, s[2:3]
	s_add_i32 m0, s31, 0x2000
	s_add_u32 s34, s2, 0x40000
	s_addc_u32 s35, s3, 0
	s_add_i32 s31, s33, s22
	global_load_lds_dwordx4 v130, s[2:3]
	s_mov_b32 m0, s31
	s_mov_b64 s[100:101], s[16:17]
	global_load_lds_dwordx4 v64, s[34:35]
	s_add_i32 m0, s31, 0x2000
	s_nop 0
	global_load_lds_dwordx4 v130, s[34:35]
	s_mov_b32 m0, s23
	s_nop 0
	global_load_lds_dwordx4 v134, s[16:17]
	s_mov_b32 m0, s24
	s_nop 0
	global_load_lds_dwordx4 v132, s[16:17]
	s_waitcnt vmcnt(8)
	s_waitcnt lgkmcnt(0)
	s_barrier
	s_setprio 1
	s_waitcnt lgkmcnt(0)
	v_mfma_f32_16x16x32_bf16 v[60:63], v[140:143], v[194:197], v[60:63]
	v_mfma_f32_16x16x32_bf16 v[56:59], v[154:157], v[194:197], v[56:59]
	v_mfma_f32_16x16x32_bf16 v[44:47], v[140:143], v[212:215], v[44:47]
	v_mfma_f32_16x16x32_bf16 v[40:43], v[154:157], v[212:215], v[40:43]
	v_mfma_f32_16x16x32_bf16 v[28:31], v[140:143], v[220:223], v[28:31]
	v_mfma_f32_16x16x32_bf16 v[24:27], v[154:157], v[220:223], v[24:27]
	v_mfma_f32_16x16x32_bf16 v[12:15], v[140:143], v[228:231], v[12:15]
	v_mfma_f32_16x16x32_bf16 v[8:11], v[154:157], v[228:231], v[8:11]
	s_setprio 0
	s_setprio 1
	v_mfma_f32_16x16x32_bf16 v[60:63], v[144:147], v[208:211], v[60:63]
	v_mfma_f32_16x16x32_bf16 v[56:59], v[158:161], v[208:211], v[56:59]
	v_mfma_f32_16x16x32_bf16 v[44:47], v[144:147], v[216:219], v[44:47]
	v_mfma_f32_16x16x32_bf16 v[40:43], v[158:161], v[216:219], v[40:43]
	v_mfma_f32_16x16x32_bf16 v[28:31], v[144:147], v[224:227], v[28:31]
	v_mfma_f32_16x16x32_bf16 v[24:27], v[158:161], v[224:227], v[24:27]
	v_mfma_f32_16x16x32_bf16 v[12:15], v[144:147], v[232:235], v[12:15]
	v_mfma_f32_16x16x32_bf16 v[8:11], v[158:161], v[232:235], v[8:11]
	s_setprio 0
	s_setprio 1
	v_mfma_f32_16x16x32_bf16 v[52:55], v[178:181], v[194:197], v[52:55]
	v_mfma_f32_16x16x32_bf16 v[48:51], v[186:189], v[194:197], v[48:51]
	v_mfma_f32_16x16x32_bf16 v[36:39], v[178:181], v[212:215], v[36:39]
	v_mfma_f32_16x16x32_bf16 v[32:35], v[186:189], v[212:215], v[32:35]
	v_mfma_f32_16x16x32_bf16 v[20:23], v[178:181], v[220:223], v[20:23]
	v_mfma_f32_16x16x32_bf16 v[16:19], v[186:189], v[220:223], v[16:19]
	v_mfma_f32_16x16x32_bf16 v[4:7], v[178:181], v[228:231], v[4:7]
	v_mfma_f32_16x16x32_bf16 v[0:3], v[186:189], v[228:231], v[0:3]
	s_setprio 0
	s_setprio 1
	v_mfma_f32_16x16x32_bf16 v[52:55], v[182:185], v[208:211], v[52:55]
	v_mfma_f32_16x16x32_bf16 v[48:51], v[190:193], v[208:211], v[48:51]
	v_mfma_f32_16x16x32_bf16 v[36:39], v[182:185], v[216:219], v[36:39]
	v_mfma_f32_16x16x32_bf16 v[32:35], v[190:193], v[216:219], v[32:35]
	v_mfma_f32_16x16x32_bf16 v[20:23], v[182:185], v[224:227], v[20:23]
	v_mfma_f32_16x16x32_bf16 v[16:19], v[190:193], v[224:227], v[16:19]
	v_mfma_f32_16x16x32_bf16 v[4:7], v[182:185], v[232:235], v[4:7]
	v_mfma_f32_16x16x32_bf16 v[0:3], v[190:193], v[232:235], v[0:3]
	s_setprio 0
	s_barrier
; #define PG8_STAGE(bufoff, gbase, voff) do { _Pragma("unroll") for (int _i = 0; _i < 2; ++_i) \
;         __builtin_amdgcn_global_load_lds((const unsigned*)((const char*)(gbase) + (voff)[_i]), (PG8_LAS unsigned*)(lds + (bufoff) + ldsw + _i * 8192), 16, 0, 0); } while (0)
; #define PG8_LDA(dst, b, h) do { _Pragma("unroll") for (int m = 0; m < 4; ++m) _Pragma("unroll") for (int k = 0; k < 2; ++k) dst[m][k] = *(const PG8_LAS bf16x8*)(lds + PG8_SA(b, h) + aoff + m * 2048 + k * 1024); } while (0)
; #define PG8_LDB(dst, b, h) do { _Pragma("unroll") for (int n = 0; n < 2; ++n) _Pragma("unroll") for (int k = 0; k < 2; ++k) dst[n][k] = *(const PG8_LAS bf16x8*)(lds + PG8_SB(b, h) + boff + n * 2048 + k * 1024); } while (0)
; #define PG8_MMA(ai, bj, At, Bt) do { __builtin_amdgcn_s_setprio(1); _Pragma("unroll") for (int m = 0; m < 4; ++m) _Pragma("unroll") for (int n = 0; n < 2; ++n) _Pragma("unroll") for (int k = 0; k < 2; ++k) \
;         acc[ai][bj][m][n] = __builtin_amdgcn_mfma_f32_16x16x32_bf16(Bt[n][k], At[m][k], acc[ai][bj][m][n], 0, 0, 0); __builtin_amdgcn_s_setprio(0); } while (0)
; #define PG8_WAIT_V(n) asm volatile("s_waitcnt vmcnt(" #n ")" ::: "memory")
; #define PG8_WAIT_L(n) asm volatile("s_waitcnt lgkmcnt(" #n ")" ::: "memory")
; #define PG8_BAR __builtin_amdgcn_s_barrier()
; #define PG8_SCHED __builtin_amdgcn_sched_barrier(0)
; template <class Epi, class Sched, bool ALIGN_EPI = false, bool SP2 = false>
; __device__ __forceinline__ void gemm_phase(PG8_LAS unsigned char* lds, const Gemm g, const Sched& S, const Epi& E, const int wave0) {
;     ...
;             PG8_LDB(B0, 1, 0); PG8_LDB(B1, 1, 1); PG8_SCHED; PG8_LDA(At, 1, 0); PG8_STAGE(PG8_SA(0, 1), a2 + hstepA, voffA);
;             PG8_WAIT_V(8); PG8_WAIT_L(0); PG8_BAR; PG8_MMA(0, 0, At, B0); PG8_MMA(0, 1, At, B1); PG8_BAR; PG8_SCHED;
;             PG8_LDA(At, 1, 1); PG8_STAGE(PG8_SB(1, 0), b3, voffB); PG8_STAGE(PG8_SB(1, 1), b3 + hstepB, voffB); PG8_STAGE(PG8_SA(1, 0), a3, voffA);
;             PG8_WAIT_V(8); PG8_WAIT_L(0); PG8_BAR; PG8_MMA(1, 0, At, B0); PG8_MMA(1, 1, At, B1); PG8_BAR; PG8_SCHED;
;     ...
;         if constexpr (ALIGN_EPI) { if (wr == 0) PG8_BAR; }
	s_add_i32 s31, 0, 0x18000
	s_add_i32 s33, 0, 0x1c000
	ds_read_b128 v[140:143], v254
	ds_read_b128 v[144:147], v254 offset:1024
	ds_read_b128 v[154:157], v254 offset:2048
	ds_read_b128 v[158:161], v254 offset:3072
	ds_read_b128 v[178:181], v255
	ds_read_b128 v[182:185], v255 offset:1024
	ds_read_b128 v[186:189], v255 offset:2048
	ds_read_b128 v[190:193], v255 offset:3072
	s_add_u32 s16, s16, 0x40000
	s_addc_u32 s17, s17, 0
	s_mov_b32 m0, s25
	ds_read_b128 v[194:197], v153 offset:32768
	ds_read_b128 v[208:211], v153 offset:33792
	ds_read_b128 v[212:215], v153 offset:34816
	ds_read_b128 v[216:219], v153 offset:35840
	ds_read_b128 v[220:223], v153 offset:36864
	ds_read_b128 v[224:227], v153 offset:37888
	ds_read_b128 v[228:231], v153 offset:38912
	ds_read_b128 v[232:235], v153 offset:39936
	global_load_lds_dwordx4 v134, s[16:17]
	s_mov_b32 m0, s26
	s_nop 0
	global_load_lds_dwordx4 v132, s[16:17]
	s_waitcnt vmcnt(8)
	s_waitcnt lgkmcnt(0)
	s_barrier
	s_setprio 1
	s_waitcnt lgkmcnt(0)
	v_mfma_f32_16x16x32_bf16 v[126:129], v[140:143], v[194:197], v[126:129]
	v_mfma_f32_16x16x32_bf16 v[122:125], v[154:157], v[194:197], v[122:125]
	v_mfma_f32_16x16x32_bf16 v[110:113], v[140:143], v[212:215], v[110:113]
	v_mfma_f32_16x16x32_bf16 v[106:109], v[154:157], v[212:215], v[106:109]
	v_mfma_f32_16x16x32_bf16 v[94:97], v[140:143], v[220:223], v[94:97]
	v_mfma_f32_16x16x32_bf16 v[90:93], v[154:157], v[220:223], v[90:93]
	v_mfma_f32_16x16x32_bf16 v[78:81], v[140:143], v[228:231], v[78:81]
	v_mfma_f32_16x16x32_bf16 v[74:77], v[154:157], v[228:231], v[74:77]
	s_setprio 0
	s_setprio 1
	v_mfma_f32_16x16x32_bf16 v[126:129], v[144:147], v[208:211], v[126:129]
	v_mfma_f32_16x16x32_bf16 v[122:125], v[158:161], v[208:211], v[122:125]
	v_mfma_f32_16x16x32_bf16 v[110:113], v[144:147], v[216:219], v[110:113]
	v_mfma_f32_16x16x32_bf16 v[106:109], v[158:161], v[216:219], v[106:109]
	v_mfma_f32_16x16x32_bf16 v[94:97], v[144:147], v[224:227], v[94:97]
	v_mfma_f32_16x16x32_bf16 v[90:93], v[158:161], v[224:227], v[90:93]
	v_mfma_f32_16x16x32_bf16 v[78:81], v[144:147], v[232:235], v[78:81]
	v_mfma_f32_16x16x32_bf16 v[74:77], v[158:161], v[232:235], v[74:77]
	s_setprio 0
	s_setprio 1
	v_mfma_f32_16x16x32_bf16 v[118:121], v[178:181], v[194:197], v[118:121]
	v_mfma_f32_16x16x32_bf16 v[114:117], v[186:189], v[194:197], v[114:117]
	v_mfma_f32_16x16x32_bf16 v[102:105], v[178:181], v[212:215], v[102:105]
	v_mfma_f32_16x16x32_bf16 v[98:101], v[186:189], v[212:215], v[98:101]
	v_mfma_f32_16x16x32_bf16 v[86:89], v[178:181], v[220:223], v[86:89]
	v_mfma_f32_16x16x32_bf16 v[82:85], v[186:189], v[220:223], v[82:85]
	v_mfma_f32_16x16x32_bf16 v[70:73], v[178:181], v[228:231], v[70:73]
	v_mfma_f32_16x16x32_bf16 v[66:69], v[186:189], v[228:231], v[66:69]
	s_setprio 0
	s_setprio 1
	v_mfma_f32_16x16x32_bf16 v[118:121], v[182:185], v[208:211], v[118:121]
	v_mfma_f32_16x16x32_bf16 v[114:117], v[190:193], v[208:211], v[114:117]
	v_mfma_f32_16x16x32_bf16 v[102:105], v[182:185], v[216:219], v[102:105]
	v_mfma_f32_16x16x32_bf16 v[98:101], v[190:193], v[216:219], v[98:101]
	v_mfma_f32_16x16x32_bf16 v[86:89], v[182:185], v[224:227], v[86:89]
	v_mfma_f32_16x16x32_bf16 v[82:85], v[190:193], v[224:227], v[82:85]
	v_mfma_f32_16x16x32_bf16 v[70:73], v[182:185], v[232:235], v[70:73]
	v_mfma_f32_16x16x32_bf16 v[66:69], v[190:193], v[232:235], v[66:69]
	s_setprio 0
	s_barrier
	s_add_i32 s16, s31, s22
	s_add_u32 s36, s2, 0x80
	s_addc_u32 s37, s3, 0
	s_mov_b32 m0, s16
	ds_read_b128 v[194:197], v153 offset:49152
	ds_read_b128 v[208:211], v153 offset:50176
	ds_read_b128 v[212:215], v153 offset:51200
	ds_read_b128 v[216:219], v153 offset:52224
	ds_read_b128 v[220:223], v153 offset:53248
	ds_read_b128 v[224:227], v153 offset:54272
	ds_read_b128 v[228:231], v153 offset:55296
	ds_read_b128 v[232:235], v153 offset:56320
	global_load_lds_dwordx4 v64, s[36:37]
	s_add_i32 m0, s16, 0x2000
	s_add_u32 s2, s2, 0x40080
	s_addc_u32 s3, s3, 0
	s_add_i32 s16, s33, s22
	global_load_lds_dwordx4 v130, s[36:37]
	s_mov_b32 m0, s16
	s_nop 0
	global_load_lds_dwordx4 v64, s[2:3]
	s_add_i32 m0, s16, 0x2000
	s_nop 0
	global_load_lds_dwordx4 v130, s[2:3]
	s_add_u32 s100, s100, 0x80
	s_addc_u32 s101, s101, 0
	s_mov_b32 m0, s27
	s_nop 0
	global_load_lds_dwordx4 v134, s[100:101]
	s_mov_b32 m0, s28
	s_nop 0
	global_load_lds_dwordx4 v132, s[100:101]
	s_waitcnt vmcnt(8)
	s_waitcnt lgkmcnt(0)
	s_barrier
	s_setprio 1
	s_waitcnt lgkmcnt(0)
	v_mfma_f32_16x16x32_bf16 v[60:63], v[140:143], v[194:197], v[60:63]
	v_mfma_f32_16x16x32_bf16 v[56:59], v[154:157], v[194:197], v[56:59]
	v_mfma_f32_16x16x32_bf16 v[44:47], v[140:143], v[212:215], v[44:47]
	v_mfma_f32_16x16x32_bf16 v[40:43], v[154:157], v[212:215], v[40:43]
	v_mfma_f32_16x16x32_bf16 v[28:31], v[140:143], v[220:223], v[28:31]
	v_mfma_f32_16x16x32_bf16 v[24:27], v[154:157], v[220:223], v[24:27]
	v_mfma_f32_16x16x32_bf16 v[12:15], v[140:143], v[228:231], v[12:15]
	v_mfma_f32_16x16x32_bf16 v[8:11], v[154:157], v[228:231], v[8:11]
	s_setprio 0
	s_setprio 1
	v_mfma_f32_16x16x32_bf16 v[60:63], v[144:147], v[208:211], v[60:63]
	v_mfma_f32_16x16x32_bf16 v[56:59], v[158:161], v[208:211], v[56:59]
	v_mfma_f32_16x16x32_bf16 v[44:47], v[144:147], v[216:219], v[44:47]
	v_mfma_f32_16x16x32_bf16 v[40:43], v[158:161], v[216:219], v[40:43]
	v_mfma_f32_16x16x32_bf16 v[28:31], v[144:147], v[224:227], v[28:31]
	v_mfma_f32_16x16x32_bf16 v[24:27], v[158:161], v[224:227], v[24:27]
	v_mfma_f32_16x16x32_bf16 v[12:15], v[144:147], v[232:235], v[12:15]
	v_mfma_f32_16x16x32_bf16 v[8:11], v[158:161], v[232:235], v[8:11]
	s_setprio 0
	s_setprio 1
	v_mfma_f32_16x16x32_bf16 v[52:55], v[178:181], v[194:197], v[52:55]
	v_mfma_f32_16x16x32_bf16 v[48:51], v[186:189], v[194:197], v[48:51]
	v_mfma_f32_16x16x32_bf16 v[36:39], v[178:181], v[212:215], v[36:39]
	v_mfma_f32_16x16x32_bf16 v[32:35], v[186:189], v[212:215], v[32:35]
	v_mfma_f32_16x16x32_bf16 v[20:23], v[178:181], v[220:223], v[20:23]
	v_mfma_f32_16x16x32_bf16 v[16:19], v[186:189], v[220:223], v[16:19]
	v_mfma_f32_16x16x32_bf16 v[4:7], v[178:181], v[228:231], v[4:7]
	v_mfma_f32_16x16x32_bf16 v[0:3], v[186:189], v[228:231], v[0:3]
	s_setprio 0
	s_setprio 1
	v_mfma_f32_16x16x32_bf16 v[52:55], v[182:185], v[208:211], v[52:55]
	v_mfma_f32_16x16x32_bf16 v[48:51], v[190:193], v[208:211], v[48:51]
	v_mfma_f32_16x16x32_bf16 v[36:39], v[182:185], v[216:219], v[36:39]
	v_mfma_f32_16x16x32_bf16 v[32:35], v[190:193], v[216:219], v[32:35]
	v_mfma_f32_16x16x32_bf16 v[20:23], v[182:185], v[224:227], v[20:23]
	v_mfma_f32_16x16x32_bf16 v[16:19], v[190:193], v[224:227], v[16:19]
	v_mfma_f32_16x16x32_bf16 v[4:7], v[182:185], v[232:235], v[4:7]
	v_mfma_f32_16x16x32_bf16 v[0:3], v[190:193], v[232:235], v[0:3]
	s_setprio 0
	s_barrier
	s_add_i32 s19, s19, 2
	s_add_u32 s0, s0, 0x100
	s_addc_u32 s1, s1, 0
	s_add_u32 s13, s13, 0x100
	s_addc_u32 s18, s18, 0
	s_cmp_gt_u32 s19, 13
	s_cbranch_scc0 .LBB0_1231
	s_mov_b64 s[36:37], 0x80
	s_and_b64 vcc, exec, s[6:7]
	s_cbranch_vccz .LBB0_1234
	s_barrier

; #define PG8_STAGE(bufoff, gbase, voff) do { _Pragma("unroll") for (int _i = 0; _i < 2; ++_i) \
;         __builtin_amdgcn_global_load_lds((const unsigned*)((const char*)(gbase) + (voff)[_i]), (PG8_LAS unsigned*)(lds + (bufoff) + ldsw + _i * 8192), 16, 0, 0); } while (0)
; #define PG8_LDA(dst, b, h) do { _Pragma("unroll") for (int m = 0; m < 4; ++m) _Pragma("unroll") for (int k = 0; k < 2; ++k) dst[m][k] = *(const PG8_LAS bf16x8*)(lds + PG8_SA(b, h) + aoff + m * 2048 + k * 1024); } while (0)
; #define PG8_LDB(dst, b, h) do { _Pragma("unroll") for (int n = 0; n < 2; ++n) _Pragma("unroll") for (int k = 0; k < 2; ++k) dst[n][k] = *(const PG8_LAS bf16x8*)(lds + PG8_SB(b, h) + boff + n * 2048 + k * 1024); } while (0)
; #define PG8_MMA(ai, bj, At, Bt) do { __builtin_amdgcn_s_setprio(1); _Pragma("unroll") for (int m = 0; m < 4; ++m) _Pragma("unroll") for (int n = 0; n < 2; ++n) _Pragma("unroll") for (int k = 0; k < 2; ++k) \
;         acc[ai][bj][m][n] = __builtin_amdgcn_mfma_f32_16x16x32_bf16(Bt[n][k], At[m][k], acc[ai][bj][m][n], 0, 0, 0); __builtin_amdgcn_s_setprio(0); } while (0)
; #define PG8_WAIT_V(n) asm volatile("s_waitcnt vmcnt(" #n ")" ::: "memory")
; #define PG8_BAR __builtin_amdgcn_s_barrier()
; template <class Epi, class Sched, bool ALIGN_EPI = false, bool SP2 = false>
; __device__ __forceinline__ void gemm_phase(PG8_LAS unsigned char* lds, const Gemm g, const Sched& S, const Epi& E, const int wave0) {
;     ...
;         for (int t = 0; t < nt; t += 2) {
;             const bool last = (t == nt - 2);
;             const char* a1 = cA + (size_t)(t + 1) * kstep;
;             const char* a2 = last ? nA : cA + (size_t)(t + 2) * kstep; const char* b2 = last ? nB : cB + (size_t)(t + 2) * kstep;
;             const char* a3 = a2 + kstep; const char* b3 = b2 + kstep;
;             if (last && has_next) S.a_ready(nxt);
;             if constexpr (SP2) {
;             PG8_LDB(B0, 0, 0); PG8_LDB(B1, 0, 1); PG8_SCHED; PG8_LDA(At, 0, 0); PG8_STAGE(PG8_SA(1, 1), a1 + hstepA, voffA);
;             PG8_WAIT_V(8); PG8_WAIT_L(0); PG8_BAR; PG8_MMA(0, 0, At, B0); PG8_MMA(0, 1, At, B1); PG8_BAR; PG8_SCHED;
;             PG8_LDA(At, 0, 1); PG8_STAGE(PG8_SB(0, 0), b2, voffB); PG8_STAGE(PG8_SB(0, 1), b2 + hstepB, voffB); PG8_STAGE(PG8_SA(0, 0), a2, voffA);
;             PG8_WAIT_V(8); PG8_WAIT_L(0); PG8_BAR; PG8_MMA(1, 0, At, B0); PG8_MMA(1, 1, At, B1); PG8_BAR; PG8_SCHED;
.LBB0_1341:
	s_add_u32 s16, s0, 0xfff80080
	s_addc_u32 s17, s1, -1
	s_add_i32 s40, 0, 0x10000
	s_cmp_eq_u32 s37, 28
	s_cselect_b32 s19, s11, s17
	s_cselect_b32 s18, s33, s16
	s_cselect_b32 s17, s9, s36
	s_cselect_b32 s16, s34, s35
	s_add_i32 s42, 0, 0x14000
	ds_read_b128 v[144:147], v252
	ds_read_b128 v[148:151], v252 offset:1024
	ds_read_b128 v[152:155], v252 offset:2048
	ds_read_b128 v[156:159], v252 offset:3072
	ds_read_b128 v[178:181], v253
	ds_read_b128 v[182:185], v253 offset:1024
	ds_read_b128 v[186:189], v253 offset:2048
	ds_read_b128 v[190:193], v253 offset:3072
	s_add_i32 m0, s23, 0xc000
	ds_read_b128 v[194:197], v143
	ds_read_b128 v[208:211], v143 offset:1024
	ds_read_b128 v[212:215], v143 offset:2048
	ds_read_b128 v[216:219], v143 offset:3072
	ds_read_b128 v[220:223], v143 offset:4096
	ds_read_b128 v[224:227], v143 offset:5120
	ds_read_b128 v[228:231], v143 offset:6144
	ds_read_b128 v[232:235], v143 offset:7168
	global_load_lds_dwordx4 v136, s[0:1]
	s_add_i32 m0, s23, 0xe000
	s_nop 0
	global_load_lds_dwordx4 v138, s[0:1]
	s_waitcnt vmcnt(8)
	s_waitcnt lgkmcnt(0)
	s_barrier
	s_setprio 1
	s_waitcnt lgkmcnt(0)
	v_mfma_f32_16x16x32_bf16 v[126:129], v[144:147], v[194:197], v[126:129]
	v_mfma_f32_16x16x32_bf16 v[122:125], v[152:155], v[194:197], v[122:125]
	v_mfma_f32_16x16x32_bf16 v[118:121], v[144:147], v[212:215], v[118:121]
	v_mfma_f32_16x16x32_bf16 v[114:117], v[152:155], v[212:215], v[114:117]
	v_mfma_f32_16x16x32_bf16 v[102:105], v[144:147], v[220:223], v[102:105]
	v_mfma_f32_16x16x32_bf16 v[98:101], v[152:155], v[220:223], v[98:101]
	v_mfma_f32_16x16x32_bf16 v[86:89], v[144:147], v[228:231], v[86:89]
	v_mfma_f32_16x16x32_bf16 v[82:85], v[152:155], v[228:231], v[82:85]
	s_setprio 0
	s_setprio 1
	v_mfma_f32_16x16x32_bf16 v[126:129], v[148:151], v[208:211], v[126:129]
	v_mfma_f32_16x16x32_bf16 v[122:125], v[156:159], v[208:211], v[122:125]
	v_mfma_f32_16x16x32_bf16 v[118:121], v[148:151], v[216:219], v[118:121]
	v_mfma_f32_16x16x32_bf16 v[114:117], v[156:159], v[216:219], v[114:117]
	v_mfma_f32_16x16x32_bf16 v[102:105], v[148:151], v[224:227], v[102:105]
	v_mfma_f32_16x16x32_bf16 v[98:101], v[156:159], v[224:227], v[98:101]
	v_mfma_f32_16x16x32_bf16 v[86:89], v[148:151], v[232:235], v[86:89]
	v_mfma_f32_16x16x32_bf16 v[82:85], v[156:159], v[232:235], v[82:85]
	s_setprio 0
	s_setprio 1
	v_mfma_f32_16x16x32_bf16 v[110:113], v[178:181], v[194:197], v[110:113]
	v_mfma_f32_16x16x32_bf16 v[106:109], v[186:189], v[194:197], v[106:109]
	v_mfma_f32_16x16x32_bf16 v[94:97], v[178:181], v[212:215], v[94:97]
	v_mfma_f32_16x16x32_bf16 v[90:93], v[186:189], v[212:215], v[90:93]
	v_mfma_f32_16x16x32_bf16 v[78:81], v[178:181], v[220:223], v[78:81]
	v_mfma_f32_16x16x32_bf16 v[74:77], v[186:189], v[220:223], v[74:77]
	v_mfma_f32_16x16x32_bf16 v[70:73], v[178:181], v[228:231], v[70:73]
	v_mfma_f32_16x16x32_bf16 v[66:69], v[186:189], v[228:231], v[66:69]
	s_setprio 0
	s_setprio 1
	v_mfma_f32_16x16x32_bf16 v[110:113], v[182:185], v[208:211], v[110:113]
	v_mfma_f32_16x16x32_bf16 v[106:109], v[190:193], v[208:211], v[106:109]
	v_mfma_f32_16x16x32_bf16 v[94:97], v[182:185], v[216:219], v[94:97]
	v_mfma_f32_16x16x32_bf16 v[90:93], v[190:193], v[216:219], v[90:93]
	v_mfma_f32_16x16x32_bf16 v[78:81], v[182:185], v[224:227], v[78:81]
	v_mfma_f32_16x16x32_bf16 v[74:77], v[190:193], v[224:227], v[74:77]
	v_mfma_f32_16x16x32_bf16 v[70:73], v[182:185], v[232:235], v[70:73]
	v_mfma_f32_16x16x32_bf16 v[66:69], v[190:193], v[232:235], v[66:69]
	s_setprio 0
	s_barrier
	s_add_i32 s40, s40, s22
	s_mov_b32 m0, s40
	ds_read_b128 v[194:197], v143 offset:16384
	ds_read_b128 v[208:211], v143 offset:17408
	ds_read_b128 v[212:215], v143 offset:18432
	ds_read_b128 v[216:219], v143 offset:19456
	ds_read_b128 v[220:223], v143 offset:20480
	ds_read_b128 v[224:227], v143 offset:21504
	ds_read_b128 v[228:231], v143 offset:22528
	ds_read_b128 v[232:235], v143 offset:23552
	global_load_lds_dwordx4 v64, s[16:17]
	s_add_i32 m0, s40, 0x2000
	s_add_u32 s40, s16, 0x80000
	s_addc_u32 s41, s17, 0
	s_add_i32 s42, s42, s22
	global_load_lds_dwordx4 v130, s[16:17]
	s_mov_b32 m0, s42
	s_mov_b64 s[100:101], s[18:19]
	global_load_lds_dwordx4 v64, s[40:41]
	s_add_i32 m0, s42, 0x2000
	s_nop 0
	global_load_lds_dwordx4 v130, s[40:41]
	s_mov_b32 m0, s23
	s_nop 0
	global_load_lds_dwordx4 v134, s[18:19]
	s_mov_b32 m0, s24
	s_nop 0
	global_load_lds_dwordx4 v132, s[18:19]
	s_waitcnt vmcnt(8)
	s_waitcnt lgkmcnt(0)
	s_barrier
	s_setprio 1
	s_waitcnt lgkmcnt(0)
	v_mfma_f32_16x16x32_bf16 v[60:63], v[144:147], v[194:197], v[60:63]
	v_mfma_f32_16x16x32_bf16 v[56:59], v[152:155], v[194:197], v[56:59]
	v_mfma_f32_16x16x32_bf16 v[52:55], v[144:147], v[212:215], v[52:55]
	v_mfma_f32_16x16x32_bf16 v[48:51], v[152:155], v[212:215], v[48:51]
	v_mfma_f32_16x16x32_bf16 v[36:39], v[144:147], v[220:223], v[36:39]
	v_mfma_f32_16x16x32_bf16 v[32:35], v[152:155], v[220:223], v[32:35]
	v_mfma_f32_16x16x32_bf16 v[20:23], v[144:147], v[228:231], v[20:23]
	v_mfma_f32_16x16x32_bf16 v[16:19], v[152:155], v[228:231], v[16:19]
	s_setprio 0
	s_setprio 1
	v_mfma_f32_16x16x32_bf16 v[60:63], v[148:151], v[208:211], v[60:63]
	v_mfma_f32_16x16x32_bf16 v[56:59], v[156:159], v[208:211], v[56:59]
	v_mfma_f32_16x16x32_bf16 v[52:55], v[148:151], v[216:219], v[52:55]
	v_mfma_f32_16x16x32_bf16 v[48:51], v[156:159], v[216:219], v[48:51]
	v_mfma_f32_16x16x32_bf16 v[36:39], v[148:151], v[224:227], v[36:39]
	v_mfma_f32_16x16x32_bf16 v[32:35], v[156:159], v[224:227], v[32:35]
	v_mfma_f32_16x16x32_bf16 v[20:23], v[148:151], v[232:235], v[20:23]
	v_mfma_f32_16x16x32_bf16 v[16:19], v[156:159], v[232:235], v[16:19]
	s_setprio 0
	s_setprio 1
	v_mfma_f32_16x16x32_bf16 v[44:47], v[178:181], v[194:197], v[44:47]
	v_mfma_f32_16x16x32_bf16 v[40:43], v[186:189], v[194:197], v[40:43]
	v_mfma_f32_16x16x32_bf16 v[28:31], v[178:181], v[212:215], v[28:31]
	v_mfma_f32_16x16x32_bf16 v[24:27], v[186:189], v[212:215], v[24:27]
	v_mfma_f32_16x16x32_bf16 v[12:15], v[178:181], v[220:223], v[12:15]
	v_mfma_f32_16x16x32_bf16 v[8:11], v[186:189], v[220:223], v[8:11]
	v_mfma_f32_16x16x32_bf16 v[4:7], v[178:181], v[228:231], v[4:7]
	v_mfma_f32_16x16x32_bf16 v[0:3], v[186:189], v[228:231], v[0:3]
	s_setprio 0
	s_setprio 1
	v_mfma_f32_16x16x32_bf16 v[44:47], v[182:185], v[208:211], v[44:47]
	v_mfma_f32_16x16x32_bf16 v[40:43], v[190:193], v[208:211], v[40:43]
	v_mfma_f32_16x16x32_bf16 v[28:31], v[182:185], v[216:219], v[28:31]
	v_mfma_f32_16x16x32_bf16 v[24:27], v[190:193], v[216:219], v[24:27]
	v_mfma_f32_16x16x32_bf16 v[12:15], v[182:185], v[224:227], v[12:15]
	v_mfma_f32_16x16x32_bf16 v[8:11], v[190:193], v[224:227], v[8:11]
	v_mfma_f32_16x16x32_bf16 v[4:7], v[182:185], v[232:235], v[4:7]
	v_mfma_f32_16x16x32_bf16 v[0:3], v[190:193], v[232:235], v[0:3]
	s_setprio 0
	s_barrier
; #define PG8_STAGE(bufoff, gbase, voff) do { _Pragma("unroll") for (int _i = 0; _i < 2; ++_i) \
;         __builtin_amdgcn_global_load_lds((const unsigned*)((const char*)(gbase) + (voff)[_i]), (PG8_LAS unsigned*)(lds + (bufoff) + ldsw + _i * 8192), 16, 0, 0); } while (0)
; #define PG8_LDA(dst, b, h) do { _Pragma("unroll") for (int m = 0; m < 4; ++m) _Pragma("unroll") for (int k = 0; k < 2; ++k) dst[m][k] = *(const PG8_LAS bf16x8*)(lds + PG8_SA(b, h) + aoff + m * 2048 + k * 1024); } while (0)
; #define PG8_LDB(dst, b, h) do { _Pragma("unroll") for (int n = 0; n < 2; ++n) _Pragma("unroll") for (int k = 0; k < 2; ++k) dst[n][k] = *(const PG8_LAS bf16x8*)(lds + PG8_SB(b, h) + boff + n * 2048 + k * 1024); } while (0)
; #define PG8_MMA(ai, bj, At, Bt) do { __builtin_amdgcn_s_setprio(1); _Pragma("unroll") for (int m = 0; m < 4; ++m) _Pragma("unroll") for (int n = 0; n < 2; ++n) _Pragma("unroll") for (int k = 0; k < 2; ++k) \
;         acc[ai][bj][m][n] = __builtin_amdgcn_mfma_f32_16x16x32_bf16(Bt[n][k], At[m][k], acc[ai][bj][m][n], 0, 0, 0); __builtin_amdgcn_s_setprio(0); } while (0)
; #define PG8_WAIT_V(n) asm volatile("s_waitcnt vmcnt(" #n ")" ::: "memory")
; #define PG8_WAIT_L(n) asm volatile("s_waitcnt lgkmcnt(" #n ")" ::: "memory")
; #define PG8_BAR __builtin_amdgcn_s_barrier()
; #define PG8_SCHED __builtin_amdgcn_sched_barrier(0)
; template <class Epi, class Sched, bool ALIGN_EPI = false, bool SP2 = false>
; __device__ __forceinline__ void gemm_phase(PG8_LAS unsigned char* lds, const Gemm g, const Sched& S, const Epi& E, const int wave0) {
;     ...
;             PG8_LDB(B0, 1, 0); PG8_LDB(B1, 1, 1); PG8_SCHED; PG8_LDA(At, 1, 0); PG8_STAGE(PG8_SA(0, 1), a2 + hstepA, voffA);
;             PG8_WAIT_V(8); PG8_WAIT_L(0); PG8_BAR; PG8_MMA(0, 0, At, B0); PG8_MMA(0, 1, At, B1); PG8_BAR; PG8_SCHED;
;             PG8_LDA(At, 1, 1); PG8_STAGE(PG8_SB(1, 0), b3, voffB); PG8_STAGE(PG8_SB(1, 1), b3 + hstepB, voffB); PG8_STAGE(PG8_SA(1, 0), a3, voffA);
;             PG8_WAIT_V(8); PG8_WAIT_L(0); PG8_BAR; PG8_MMA(1, 0, At, B0); PG8_MMA(1, 1, At, B1); PG8_BAR; PG8_SCHED;
;     ...
;         if constexpr (ALIGN_EPI) { if (wr == 0) PG8_BAR; }
	s_add_i32 s40, 0, 0x18000
	s_add_i32 s41, 0, 0x1c000
	ds_read_b128 v[144:147], v254
	ds_read_b128 v[148:151], v254 offset:1024
	ds_read_b128 v[152:155], v254 offset:2048
	ds_read_b128 v[156:159], v254 offset:3072
	ds_read_b128 v[178:181], v255
	ds_read_b128 v[182:185], v255 offset:1024
	ds_read_b128 v[186:189], v255 offset:2048
	ds_read_b128 v[190:193], v255 offset:3072
	s_add_u32 s18, s18, 0x80000
	s_addc_u32 s19, s19, 0
	s_mov_b32 m0, s25
	ds_read_b128 v[194:197], v143 offset:32768
	ds_read_b128 v[208:211], v143 offset:33792
	ds_read_b128 v[212:215], v143 offset:34816
	ds_read_b128 v[216:219], v143 offset:35840
	ds_read_b128 v[220:223], v143 offset:36864
	ds_read_b128 v[224:227], v143 offset:37888
	ds_read_b128 v[228:231], v143 offset:38912
	ds_read_b128 v[232:235], v143 offset:39936
	global_load_lds_dwordx4 v134, s[18:19]
	s_mov_b32 m0, s26
	s_nop 0
	global_load_lds_dwordx4 v132, s[18:19]
	s_waitcnt vmcnt(8)
	s_waitcnt lgkmcnt(0)
	s_barrier
	s_setprio 1
	s_waitcnt lgkmcnt(0)
	v_mfma_f32_16x16x32_bf16 v[126:129], v[144:147], v[194:197], v[126:129]
	v_mfma_f32_16x16x32_bf16 v[122:125], v[152:155], v[194:197], v[122:125]
	v_mfma_f32_16x16x32_bf16 v[118:121], v[144:147], v[212:215], v[118:121]
	v_mfma_f32_16x16x32_bf16 v[114:117], v[152:155], v[212:215], v[114:117]
	v_mfma_f32_16x16x32_bf16 v[102:105], v[144:147], v[220:223], v[102:105]
	v_mfma_f32_16x16x32_bf16 v[98:101], v[152:155], v[220:223], v[98:101]
	v_mfma_f32_16x16x32_bf16 v[86:89], v[144:147], v[228:231], v[86:89]
	v_mfma_f32_16x16x32_bf16 v[82:85], v[152:155], v[228:231], v[82:85]
	s_setprio 0
	s_setprio 1
	v_mfma_f32_16x16x32_bf16 v[126:129], v[148:151], v[208:211], v[126:129]
	v_mfma_f32_16x16x32_bf16 v[122:125], v[156:159], v[208:211], v[122:125]
	v_mfma_f32_16x16x32_bf16 v[118:121], v[148:151], v[216:219], v[118:121]
	v_mfma_f32_16x16x32_bf16 v[114:117], v[156:159], v[216:219], v[114:117]
	v_mfma_f32_16x16x32_bf16 v[102:105], v[148:151], v[224:227], v[102:105]
	v_mfma_f32_16x16x32_bf16 v[98:101], v[156:159], v[224:227], v[98:101]
	v_mfma_f32_16x16x32_bf16 v[86:89], v[148:151], v[232:235], v[86:89]
	v_mfma_f32_16x16x32_bf16 v[82:85], v[156:159], v[232:235], v[82:85]
	s_setprio 0
	s_setprio 1
	v_mfma_f32_16x16x32_bf16 v[110:113], v[178:181], v[194:197], v[110:113]
	v_mfma_f32_16x16x32_bf16 v[106:109], v[186:189], v[194:197], v[106:109]
	v_mfma_f32_16x16x32_bf16 v[94:97], v[178:181], v[212:215], v[94:97]
	v_mfma_f32_16x16x32_bf16 v[90:93], v[186:189], v[212:215], v[90:93]
	v_mfma_f32_16x16x32_bf16 v[78:81], v[178:181], v[220:223], v[78:81]
	v_mfma_f32_16x16x32_bf16 v[74:77], v[186:189], v[220:223], v[74:77]
	v_mfma_f32_16x16x32_bf16 v[70:73], v[178:181], v[228:231], v[70:73]
	v_mfma_f32_16x16x32_bf16 v[66:69], v[186:189], v[228:231], v[66:69]
	s_setprio 0
	s_setprio 1
	v_mfma_f32_16x16x32_bf16 v[110:113], v[182:185], v[208:211], v[110:113]
	v_mfma_f32_16x16x32_bf16 v[106:109], v[190:193], v[208:211], v[106:109]
	v_mfma_f32_16x16x32_bf16 v[94:97], v[182:185], v[216:219], v[94:97]
	v_mfma_f32_16x16x32_bf16 v[90:93], v[190:193], v[216:219], v[90:93]
	v_mfma_f32_16x16x32_bf16 v[78:81], v[182:185], v[224:227], v[78:81]
	v_mfma_f32_16x16x32_bf16 v[74:77], v[190:193], v[224:227], v[74:77]
	v_mfma_f32_16x16x32_bf16 v[70:73], v[182:185], v[232:235], v[70:73]
	v_mfma_f32_16x16x32_bf16 v[66:69], v[190:193], v[232:235], v[66:69]
	s_setprio 0
	s_barrier
	s_add_i32 s18, s40, s22
	s_add_u32 s44, s16, 0x80
	s_addc_u32 s45, s17, 0
	s_mov_b32 m0, s18
	ds_read_b128 v[194:197], v143 offset:49152
	ds_read_b128 v[208:211], v143 offset:50176
	ds_read_b128 v[212:215], v143 offset:51200
	ds_read_b128 v[216:219], v143 offset:52224
	ds_read_b128 v[220:223], v143 offset:53248
	ds_read_b128 v[224:227], v143 offset:54272
	ds_read_b128 v[228:231], v143 offset:55296
	ds_read_b128 v[232:235], v143 offset:56320
	global_load_lds_dwordx4 v64, s[44:45]
	s_add_i32 m0, s18, 0x2000
	s_add_u32 s16, s16, 0x80080
	s_addc_u32 s17, s17, 0
	s_add_i32 s18, s41, s22
	global_load_lds_dwordx4 v130, s[44:45]
	s_mov_b32 m0, s18
	s_nop 0
	global_load_lds_dwordx4 v64, s[16:17]
	s_add_i32 m0, s18, 0x2000
	s_nop 0
	global_load_lds_dwordx4 v130, s[16:17]
	s_add_u32 s100, s100, 0x80
	s_addc_u32 s101, s101, 0
	s_mov_b32 m0, s27
	s_nop 0
	global_load_lds_dwordx4 v134, s[100:101]
	s_mov_b32 m0, s28
	s_nop 0
	global_load_lds_dwordx4 v132, s[100:101]
	s_waitcnt vmcnt(8)
	s_waitcnt lgkmcnt(0)
	s_barrier
	s_setprio 1
	s_waitcnt lgkmcnt(0)
	v_mfma_f32_16x16x32_bf16 v[60:63], v[144:147], v[194:197], v[60:63]
	v_mfma_f32_16x16x32_bf16 v[56:59], v[152:155], v[194:197], v[56:59]
	v_mfma_f32_16x16x32_bf16 v[52:55], v[144:147], v[212:215], v[52:55]
	v_mfma_f32_16x16x32_bf16 v[48:51], v[152:155], v[212:215], v[48:51]
	v_mfma_f32_16x16x32_bf16 v[36:39], v[144:147], v[220:223], v[36:39]
	v_mfma_f32_16x16x32_bf16 v[32:35], v[152:155], v[220:223], v[32:35]
	v_mfma_f32_16x16x32_bf16 v[20:23], v[144:147], v[228:231], v[20:23]
	v_mfma_f32_16x16x32_bf16 v[16:19], v[152:155], v[228:231], v[16:19]
	s_setprio 0
	s_setprio 1
	v_mfma_f32_16x16x32_bf16 v[60:63], v[148:151], v[208:211], v[60:63]
	v_mfma_f32_16x16x32_bf16 v[56:59], v[156:159], v[208:211], v[56:59]
	v_mfma_f32_16x16x32_bf16 v[52:55], v[148:151], v[216:219], v[52:55]
	v_mfma_f32_16x16x32_bf16 v[48:51], v[156:159], v[216:219], v[48:51]
	v_mfma_f32_16x16x32_bf16 v[36:39], v[148:151], v[224:227], v[36:39]
	v_mfma_f32_16x16x32_bf16 v[32:35], v[156:159], v[224:227], v[32:35]
	v_mfma_f32_16x16x32_bf16 v[20:23], v[148:151], v[232:235], v[20:23]
	v_mfma_f32_16x16x32_bf16 v[16:19], v[156:159], v[232:235], v[16:19]
	s_setprio 0
	s_setprio 1
	v_mfma_f32_16x16x32_bf16 v[44:47], v[178:181], v[194:197], v[44:47]
	v_mfma_f32_16x16x32_bf16 v[40:43], v[186:189], v[194:197], v[40:43]
	v_mfma_f32_16x16x32_bf16 v[28:31], v[178:181], v[212:215], v[28:31]
	v_mfma_f32_16x16x32_bf16 v[24:27], v[186:189], v[212:215], v[24:27]
	v_mfma_f32_16x16x32_bf16 v[12:15], v[178:181], v[220:223], v[12:15]
	v_mfma_f32_16x16x32_bf16 v[8:11], v[186:189], v[220:223], v[8:11]
	v_mfma_f32_16x16x32_bf16 v[4:7], v[178:181], v[228:231], v[4:7]
	v_mfma_f32_16x16x32_bf16 v[0:3], v[186:189], v[228:231], v[0:3]
	s_setprio 0
	s_setprio 1
	v_mfma_f32_16x16x32_bf16 v[44:47], v[182:185], v[208:211], v[44:47]
	v_mfma_f32_16x16x32_bf16 v[40:43], v[190:193], v[208:211], v[40:43]
	v_mfma_f32_16x16x32_bf16 v[28:31], v[182:185], v[216:219], v[28:31]
	v_mfma_f32_16x16x32_bf16 v[24:27], v[190:193], v[216:219], v[24:27]
	v_mfma_f32_16x16x32_bf16 v[12:15], v[182:185], v[224:227], v[12:15]
	v_mfma_f32_16x16x32_bf16 v[8:11], v[190:193], v[224:227], v[8:11]
	v_mfma_f32_16x16x32_bf16 v[4:7], v[182:185], v[232:235], v[4:7]
	v_mfma_f32_16x16x32_bf16 v[0:3], v[190:193], v[232:235], v[0:3]
	s_setprio 0
	s_barrier
	s_add_i32 s37, s37, 2
	s_add_u32 s0, s0, 0x100
	s_addc_u32 s1, s1, 0
	s_add_u32 s35, s35, 0x100
	s_addc_u32 s36, s36, 0
	s_cmp_gt_u32 s37, 29
	s_cbranch_scc0 .LBB0_1341
	s_mov_b64 s[44:45], 0x80
	s_and_b64 vcc, exec, s[6:7]
	s_mov_b64 s[34:35], 0x45000
	s_cbranch_vccz .LBB0_1344
	s_barrier

; #define PG8_STAGE(bufoff, gbase, voff) do { _Pragma("unroll") for (int _i = 0; _i < 2; ++_i) \
;         __builtin_amdgcn_global_load_lds((const unsigned*)((const char*)(gbase) + (voff)[_i]), (PG8_LAS unsigned*)(lds + (bufoff) + ldsw + _i * 8192), 16, 0, 0); } while (0)
; #define PG8_LDA(dst, b, h) do { _Pragma("unroll") for (int m = 0; m < 4; ++m) _Pragma("unroll") for (int k = 0; k < 2; ++k) dst[m][k] = *(const PG8_LAS bf16x8*)(lds + PG8_SA(b, h) + aoff + m * 2048 + k * 1024); } while (0)
; #define PG8_LDB(dst, b, h) do { _Pragma("unroll") for (int n = 0; n < 2; ++n) _Pragma("unroll") for (int k = 0; k < 2; ++k) dst[n][k] = *(const PG8_LAS bf16x8*)(lds + PG8_SB(b, h) + boff + n * 2048 + k * 1024); } while (0)
; #define PG8_MMA(ai, bj, At, Bt) do { __builtin_amdgcn_s_setprio(1); _Pragma("unroll") for (int m = 0; m < 4; ++m) _Pragma("unroll") for (int n = 0; n < 2; ++n) _Pragma("unroll") for (int k = 0; k < 2; ++k) \
;         acc[ai][bj][m][n] = __builtin_amdgcn_mfma_f32_16x16x32_bf16(Bt[n][k], At[m][k], acc[ai][bj][m][n], 0, 0, 0); __builtin_amdgcn_s_setprio(0); } while (0)
; #define PG8_WAIT_V(n) asm volatile("s_waitcnt vmcnt(" #n ")" ::: "memory")
; #define PG8_BAR __builtin_amdgcn_s_barrier()
; template <class Epi, class Sched, bool ALIGN_EPI = false, bool SP2 = false>
; __device__ __forceinline__ void gemm_phase(PG8_LAS unsigned char* lds, const Gemm g, const Sched& S, const Epi& E, const int wave0) {
;     ...
;         for (int t = 0; t < nt; t += 2) {
;             const bool last = (t == nt - 2);
;             const char* a1 = cA + (size_t)(t + 1) * kstep;
;             const char* a2 = last ? nA : cA + (size_t)(t + 2) * kstep; const char* b2 = last ? nB : cB + (size_t)(t + 2) * kstep;
;             const char* a3 = a2 + kstep; const char* b3 = b2 + kstep;
;             if (last && has_next) S.a_ready(nxt);
;             if constexpr (SP2) {
;             PG8_LDB(B0, 0, 0); PG8_LDB(B1, 0, 1); PG8_SCHED; PG8_LDA(At, 0, 0); PG8_STAGE(PG8_SA(1, 1), a1 + hstepA, voffA);
;             PG8_WAIT_V(8); PG8_WAIT_L(0); PG8_BAR; PG8_MMA(0, 0, At, B0); PG8_MMA(0, 1, At, B1); PG8_BAR; PG8_SCHED;
;             PG8_LDA(At, 0, 1); PG8_STAGE(PG8_SB(0, 0), b2, voffB); PG8_STAGE(PG8_SB(0, 1), b2 + hstepB, voffB); PG8_STAGE(PG8_SA(0, 0), a2, voffA);
;             PG8_WAIT_V(8); PG8_WAIT_L(0); PG8_BAR; PG8_MMA(1, 0, At, B0); PG8_MMA(1, 1, At, B1); PG8_BAR; PG8_SCHED;
.LBB0_1360:
	s_add_u32 s16, s0, 0xfff80080
	s_addc_u32 s17, s1, -1
	s_add_i32 s42, 0, 0x10000
	s_cmp_eq_u32 s41, 12
	s_cselect_b32 s19, s5, s17
	s_cselect_b32 s18, s4, s16
	s_cselect_b32 s17, s11, s27
	s_cselect_b32 s16, s13, s15
	s_add_i32 s44, 0, 0x14000
	ds_read_b128 v[144:147], v252
	ds_read_b128 v[148:151], v252 offset:1024
	ds_read_b128 v[152:155], v252 offset:2048
	ds_read_b128 v[156:159], v252 offset:3072
	ds_read_b128 v[178:181], v253
	ds_read_b128 v[182:185], v253 offset:1024
	ds_read_b128 v[186:189], v253 offset:2048
	ds_read_b128 v[190:193], v253 offset:3072
	s_add_i32 m0, s23, 0xc000
	ds_read_b128 v[194:197], v143
	ds_read_b128 v[208:211], v143 offset:1024
	ds_read_b128 v[212:215], v143 offset:2048
	ds_read_b128 v[216:219], v143 offset:3072
	ds_read_b128 v[220:223], v143 offset:4096
	ds_read_b128 v[224:227], v143 offset:5120
	ds_read_b128 v[228:231], v143 offset:6144
	ds_read_b128 v[232:235], v143 offset:7168
	global_load_lds_dwordx4 v136, s[0:1]
	s_add_i32 m0, s23, 0xe000
	s_nop 0
	global_load_lds_dwordx4 v138, s[0:1]
	s_waitcnt vmcnt(8)
	s_waitcnt lgkmcnt(0)
	s_barrier
	s_setprio 1
	s_waitcnt lgkmcnt(0)
	v_mfma_f32_16x16x32_bf16 v[126:129], v[144:147], v[194:197], v[126:129]
	v_mfma_f32_16x16x32_bf16 v[122:125], v[152:155], v[194:197], v[122:125]
	v_mfma_f32_16x16x32_bf16 v[118:121], v[144:147], v[212:215], v[118:121]
	v_mfma_f32_16x16x32_bf16 v[114:117], v[152:155], v[212:215], v[114:117]
	v_mfma_f32_16x16x32_bf16 v[102:105], v[144:147], v[220:223], v[102:105]
	v_mfma_f32_16x16x32_bf16 v[98:101], v[152:155], v[220:223], v[98:101]
	v_mfma_f32_16x16x32_bf16 v[86:89], v[144:147], v[228:231], v[86:89]
	v_mfma_f32_16x16x32_bf16 v[82:85], v[152:155], v[228:231], v[82:85]
	s_setprio 0
	s_setprio 1
	v_mfma_f32_16x16x32_bf16 v[126:129], v[148:151], v[208:211], v[126:129]
	v_mfma_f32_16x16x32_bf16 v[122:125], v[156:159], v[208:211], v[122:125]
	v_mfma_f32_16x16x32_bf16 v[118:121], v[148:151], v[216:219], v[118:121]
	v_mfma_f32_16x16x32_bf16 v[114:117], v[156:159], v[216:219], v[114:117]
	v_mfma_f32_16x16x32_bf16 v[102:105], v[148:151], v[224:227], v[102:105]
	v_mfma_f32_16x16x32_bf16 v[98:101], v[156:159], v[224:227], v[98:101]
	v_mfma_f32_16x16x32_bf16 v[86:89], v[148:151], v[232:235], v[86:89]
	v_mfma_f32_16x16x32_bf16 v[82:85], v[156:159], v[232:235], v[82:85]
	s_setprio 0
	s_setprio 1
	v_mfma_f32_16x16x32_bf16 v[110:113], v[178:181], v[194:197], v[110:113]
	v_mfma_f32_16x16x32_bf16 v[106:109], v[186:189], v[194:197], v[106:109]
	v_mfma_f32_16x16x32_bf16 v[94:97], v[178:181], v[212:215], v[94:97]
	v_mfma_f32_16x16x32_bf16 v[90:93], v[186:189], v[212:215], v[90:93]
	v_mfma_f32_16x16x32_bf16 v[78:81], v[178:181], v[220:223], v[78:81]
	v_mfma_f32_16x16x32_bf16 v[74:77], v[186:189], v[220:223], v[74:77]
	v_mfma_f32_16x16x32_bf16 v[70:73], v[178:181], v[228:231], v[70:73]
	v_mfma_f32_16x16x32_bf16 v[66:69], v[186:189], v[228:231], v[66:69]
	s_setprio 0
	s_setprio 1
	v_mfma_f32_16x16x32_bf16 v[110:113], v[182:185], v[208:211], v[110:113]
	v_mfma_f32_16x16x32_bf16 v[106:109], v[190:193], v[208:211], v[106:109]
	v_mfma_f32_16x16x32_bf16 v[94:97], v[182:185], v[216:219], v[94:97]
	v_mfma_f32_16x16x32_bf16 v[90:93], v[190:193], v[216:219], v[90:93]
	v_mfma_f32_16x16x32_bf16 v[78:81], v[182:185], v[224:227], v[78:81]
	v_mfma_f32_16x16x32_bf16 v[74:77], v[190:193], v[224:227], v[74:77]
	v_mfma_f32_16x16x32_bf16 v[70:73], v[182:185], v[232:235], v[70:73]
	v_mfma_f32_16x16x32_bf16 v[66:69], v[190:193], v[232:235], v[66:69]
	s_setprio 0
	s_barrier
	s_add_i32 s42, s42, s22
	s_mov_b32 m0, s42
	ds_read_b128 v[194:197], v143 offset:16384
	ds_read_b128 v[208:211], v143 offset:17408
	ds_read_b128 v[212:215], v143 offset:18432
	ds_read_b128 v[216:219], v143 offset:19456
	ds_read_b128 v[220:223], v143 offset:20480
	ds_read_b128 v[224:227], v143 offset:21504
	ds_read_b128 v[228:231], v143 offset:22528
	ds_read_b128 v[232:235], v143 offset:23552
	global_load_lds_dwordx4 v64, s[16:17]
	s_add_i32 m0, s42, 0x2000
	s_add_u32 s42, s16, 0x80000
	s_addc_u32 s43, s17, 0
	s_add_i32 s44, s44, s22
	global_load_lds_dwordx4 v130, s[16:17]
	s_mov_b32 m0, s44
	s_mov_b64 s[100:101], s[18:19]
	global_load_lds_dwordx4 v64, s[42:43]
	s_add_i32 m0, s44, 0x2000
	s_nop 0
	global_load_lds_dwordx4 v130, s[42:43]
	s_mov_b32 m0, s23
	s_nop 0
	global_load_lds_dwordx4 v134, s[18:19]
	s_mov_b32 m0, s24
	s_nop 0
	global_load_lds_dwordx4 v132, s[18:19]
	s_waitcnt vmcnt(8)
	s_waitcnt lgkmcnt(0)
	s_barrier
	s_setprio 1
	s_waitcnt lgkmcnt(0)
	v_mfma_f32_16x16x32_bf16 v[60:63], v[144:147], v[194:197], v[60:63]
	v_mfma_f32_16x16x32_bf16 v[56:59], v[152:155], v[194:197], v[56:59]
	v_mfma_f32_16x16x32_bf16 v[52:55], v[144:147], v[212:215], v[52:55]
	v_mfma_f32_16x16x32_bf16 v[48:51], v[152:155], v[212:215], v[48:51]
	v_mfma_f32_16x16x32_bf16 v[36:39], v[144:147], v[220:223], v[36:39]
	v_mfma_f32_16x16x32_bf16 v[32:35], v[152:155], v[220:223], v[32:35]
	v_mfma_f32_16x16x32_bf16 v[20:23], v[144:147], v[228:231], v[20:23]
	v_mfma_f32_16x16x32_bf16 v[16:19], v[152:155], v[228:231], v[16:19]
	s_setprio 0
	s_setprio 1
	v_mfma_f32_16x16x32_bf16 v[60:63], v[148:151], v[208:211], v[60:63]
	v_mfma_f32_16x16x32_bf16 v[56:59], v[156:159], v[208:211], v[56:59]
	v_mfma_f32_16x16x32_bf16 v[52:55], v[148:151], v[216:219], v[52:55]
	v_mfma_f32_16x16x32_bf16 v[48:51], v[156:159], v[216:219], v[48:51]
	v_mfma_f32_16x16x32_bf16 v[36:39], v[148:151], v[224:227], v[36:39]
	v_mfma_f32_16x16x32_bf16 v[32:35], v[156:159], v[224:227], v[32:35]
	v_mfma_f32_16x16x32_bf16 v[20:23], v[148:151], v[232:235], v[20:23]
	v_mfma_f32_16x16x32_bf16 v[16:19], v[156:159], v[232:235], v[16:19]
	s_setprio 0
	s_setprio 1
	v_mfma_f32_16x16x32_bf16 v[44:47], v[178:181], v[194:197], v[44:47]
	v_mfma_f32_16x16x32_bf16 v[40:43], v[186:189], v[194:197], v[40:43]
	v_mfma_f32_16x16x32_bf16 v[28:31], v[178:181], v[212:215], v[28:31]
	v_mfma_f32_16x16x32_bf16 v[24:27], v[186:189], v[212:215], v[24:27]
	v_mfma_f32_16x16x32_bf16 v[12:15], v[178:181], v[220:223], v[12:15]
	v_mfma_f32_16x16x32_bf16 v[8:11], v[186:189], v[220:223], v[8:11]
	v_mfma_f32_16x16x32_bf16 v[4:7], v[178:181], v[228:231], v[4:7]
	v_mfma_f32_16x16x32_bf16 v[0:3], v[186:189], v[228:231], v[0:3]
	s_setprio 0
	s_setprio 1
	v_mfma_f32_16x16x32_bf16 v[44:47], v[182:185], v[208:211], v[44:47]
	v_mfma_f32_16x16x32_bf16 v[40:43], v[190:193], v[208:211], v[40:43]
	v_mfma_f32_16x16x32_bf16 v[28:31], v[182:185], v[216:219], v[28:31]
	v_mfma_f32_16x16x32_bf16 v[24:27], v[190:193], v[216:219], v[24:27]
	v_mfma_f32_16x16x32_bf16 v[12:15], v[182:185], v[224:227], v[12:15]
	v_mfma_f32_16x16x32_bf16 v[8:11], v[190:193], v[224:227], v[8:11]
	v_mfma_f32_16x16x32_bf16 v[4:7], v[182:185], v[232:235], v[4:7]
	v_mfma_f32_16x16x32_bf16 v[0:3], v[190:193], v[232:235], v[0:3]
	s_setprio 0
	s_barrier
; #define PG8_STAGE(bufoff, gbase, voff) do { _Pragma("unroll") for (int _i = 0; _i < 2; ++_i) \
;         __builtin_amdgcn_global_load_lds((const unsigned*)((const char*)(gbase) + (voff)[_i]), (PG8_LAS unsigned*)(lds + (bufoff) + ldsw + _i * 8192), 16, 0, 0); } while (0)
; #define PG8_LDA(dst, b, h) do { _Pragma("unroll") for (int m = 0; m < 4; ++m) _Pragma("unroll") for (int k = 0; k < 2; ++k) dst[m][k] = *(const PG8_LAS bf16x8*)(lds + PG8_SA(b, h) + aoff + m * 2048 + k * 1024); } while (0)
; #define PG8_LDB(dst, b, h) do { _Pragma("unroll") for (int n = 0; n < 2; ++n) _Pragma("unroll") for (int k = 0; k < 2; ++k) dst[n][k] = *(const PG8_LAS bf16x8*)(lds + PG8_SB(b, h) + boff + n * 2048 + k * 1024); } while (0)
; #define PG8_MMA(ai, bj, At, Bt) do { __builtin_amdgcn_s_setprio(1); _Pragma("unroll") for (int m = 0; m < 4; ++m) _Pragma("unroll") for (int n = 0; n < 2; ++n) _Pragma("unroll") for (int k = 0; k < 2; ++k) \
;         acc[ai][bj][m][n] = __builtin_amdgcn_mfma_f32_16x16x32_bf16(Bt[n][k], At[m][k], acc[ai][bj][m][n], 0, 0, 0); __builtin_amdgcn_s_setprio(0); } while (0)
; #define PG8_WAIT_V(n) asm volatile("s_waitcnt vmcnt(" #n ")" ::: "memory")
; #define PG8_WAIT_L(n) asm volatile("s_waitcnt lgkmcnt(" #n ")" ::: "memory")
; #define PG8_BAR __builtin_amdgcn_s_barrier()
; #define PG8_SCHED __builtin_amdgcn_sched_barrier(0)
; template <class Epi, class Sched, bool ALIGN_EPI = false, bool SP2 = false>
; __device__ __forceinline__ void gemm_phase(PG8_LAS unsigned char* lds, const Gemm g, const Sched& S, const Epi& E, const int wave0) {
;     ...
;             PG8_LDB(B0, 1, 0); PG8_LDB(B1, 1, 1); PG8_SCHED; PG8_LDA(At, 1, 0); PG8_STAGE(PG8_SA(0, 1), a2 + hstepA, voffA);
;             PG8_WAIT_V(8); PG8_WAIT_L(0); PG8_BAR; PG8_MMA(0, 0, At, B0); PG8_MMA(0, 1, At, B1); PG8_BAR; PG8_SCHED;
;             PG8_LDA(At, 1, 1); PG8_STAGE(PG8_SB(1, 0), b3, voffB); PG8_STAGE(PG8_SB(1, 1), b3 + hstepB, voffB); PG8_STAGE(PG8_SA(1, 0), a3, voffA);
;             PG8_WAIT_V(8); PG8_WAIT_L(0); PG8_BAR; PG8_MMA(1, 0, At, B0); PG8_MMA(1, 1, At, B1); PG8_BAR; PG8_SCHED;
;     ...
;         if constexpr (ALIGN_EPI) { if (wr == 0) PG8_BAR; }
	s_add_i32 s42, 0, 0x18000
	s_add_i32 s43, 0, 0x1c000
	ds_read_b128 v[144:147], v254
	ds_read_b128 v[148:151], v254 offset:1024
	ds_read_b128 v[152:155], v254 offset:2048
	ds_read_b128 v[156:159], v254 offset:3072
	ds_read_b128 v[178:181], v255
	ds_read_b128 v[182:185], v255 offset:1024
	ds_read_b128 v[186:189], v255 offset:2048
	ds_read_b128 v[190:193], v255 offset:3072
	s_add_u32 s18, s18, 0x80000
	s_addc_u32 s19, s19, 0
	s_mov_b32 m0, s25
	ds_read_b128 v[194:197], v143 offset:32768
	ds_read_b128 v[208:211], v143 offset:33792
	ds_read_b128 v[212:215], v143 offset:34816
	ds_read_b128 v[216:219], v143 offset:35840
	ds_read_b128 v[220:223], v143 offset:36864
	ds_read_b128 v[224:227], v143 offset:37888
	ds_read_b128 v[228:231], v143 offset:38912
	ds_read_b128 v[232:235], v143 offset:39936
	global_load_lds_dwordx4 v134, s[18:19]
	s_mov_b32 m0, s33
	s_nop 0
	global_load_lds_dwordx4 v132, s[18:19]
	s_waitcnt vmcnt(8)
	s_waitcnt lgkmcnt(0)
	s_barrier
	s_setprio 1
	s_waitcnt lgkmcnt(0)
	v_mfma_f32_16x16x32_bf16 v[126:129], v[144:147], v[194:197], v[126:129]
	v_mfma_f32_16x16x32_bf16 v[122:125], v[152:155], v[194:197], v[122:125]
	v_mfma_f32_16x16x32_bf16 v[118:121], v[144:147], v[212:215], v[118:121]
	v_mfma_f32_16x16x32_bf16 v[114:117], v[152:155], v[212:215], v[114:117]
	v_mfma_f32_16x16x32_bf16 v[102:105], v[144:147], v[220:223], v[102:105]
	v_mfma_f32_16x16x32_bf16 v[98:101], v[152:155], v[220:223], v[98:101]
	v_mfma_f32_16x16x32_bf16 v[86:89], v[144:147], v[228:231], v[86:89]
	v_mfma_f32_16x16x32_bf16 v[82:85], v[152:155], v[228:231], v[82:85]
	s_setprio 0
	s_setprio 1
	v_mfma_f32_16x16x32_bf16 v[126:129], v[148:151], v[208:211], v[126:129]
	v_mfma_f32_16x16x32_bf16 v[122:125], v[156:159], v[208:211], v[122:125]
	v_mfma_f32_16x16x32_bf16 v[118:121], v[148:151], v[216:219], v[118:121]
	v_mfma_f32_16x16x32_bf16 v[114:117], v[156:159], v[216:219], v[114:117]
	v_mfma_f32_16x16x32_bf16 v[102:105], v[148:151], v[224:227], v[102:105]
	v_mfma_f32_16x16x32_bf16 v[98:101], v[156:159], v[224:227], v[98:101]
	v_mfma_f32_16x16x32_bf16 v[86:89], v[148:151], v[232:235], v[86:89]
	v_mfma_f32_16x16x32_bf16 v[82:85], v[156:159], v[232:235], v[82:85]
	s_setprio 0
	s_setprio 1
	v_mfma_f32_16x16x32_bf16 v[110:113], v[178:181], v[194:197], v[110:113]
	v_mfma_f32_16x16x32_bf16 v[106:109], v[186:189], v[194:197], v[106:109]
	v_mfma_f32_16x16x32_bf16 v[94:97], v[178:181], v[212:215], v[94:97]
	v_mfma_f32_16x16x32_bf16 v[90:93], v[186:189], v[212:215], v[90:93]
	v_mfma_f32_16x16x32_bf16 v[78:81], v[178:181], v[220:223], v[78:81]
	v_mfma_f32_16x16x32_bf16 v[74:77], v[186:189], v[220:223], v[74:77]
	v_mfma_f32_16x16x32_bf16 v[70:73], v[178:181], v[228:231], v[70:73]
	v_mfma_f32_16x16x32_bf16 v[66:69], v[186:189], v[228:231], v[66:69]
	s_setprio 0
	s_setprio 1
	v_mfma_f32_16x16x32_bf16 v[110:113], v[182:185], v[208:211], v[110:113]
	v_mfma_f32_16x16x32_bf16 v[106:109], v[190:193], v[208:211], v[106:109]
	v_mfma_f32_16x16x32_bf16 v[94:97], v[182:185], v[216:219], v[94:97]
	v_mfma_f32_16x16x32_bf16 v[90:93], v[190:193], v[216:219], v[90:93]
	v_mfma_f32_16x16x32_bf16 v[78:81], v[182:185], v[224:227], v[78:81]
	v_mfma_f32_16x16x32_bf16 v[74:77], v[190:193], v[224:227], v[74:77]
	v_mfma_f32_16x16x32_bf16 v[70:73], v[182:185], v[232:235], v[70:73]
	v_mfma_f32_16x16x32_bf16 v[66:69], v[190:193], v[232:235], v[66:69]
	s_setprio 0
	s_barrier
	s_add_i32 s18, s42, s22
	s_add_u32 s46, s16, 0x80
	s_addc_u32 s47, s17, 0
	s_mov_b32 m0, s18
	ds_read_b128 v[194:197], v143 offset:49152
	ds_read_b128 v[208:211], v143 offset:50176
	ds_read_b128 v[212:215], v143 offset:51200
	ds_read_b128 v[216:219], v143 offset:52224
	ds_read_b128 v[220:223], v143 offset:53248
	ds_read_b128 v[224:227], v143 offset:54272
	ds_read_b128 v[228:231], v143 offset:55296
	ds_read_b128 v[232:235], v143 offset:56320
	global_load_lds_dwordx4 v64, s[46:47]
	s_add_i32 m0, s18, 0x2000
	s_add_u32 s16, s16, 0x80080
	s_addc_u32 s17, s17, 0
	s_add_i32 s18, s43, s22
	global_load_lds_dwordx4 v130, s[46:47]
	s_mov_b32 m0, s18
	s_nop 0
	global_load_lds_dwordx4 v64, s[16:17]
	s_add_i32 m0, s18, 0x2000
	s_nop 0
	global_load_lds_dwordx4 v130, s[16:17]
	s_add_u32 s100, s100, 0x80
	s_addc_u32 s101, s101, 0
	s_mov_b32 m0, s34
	s_nop 0
	global_load_lds_dwordx4 v134, s[100:101]
	s_mov_b32 m0, s35
	s_nop 0
	global_load_lds_dwordx4 v132, s[100:101]
	s_waitcnt vmcnt(8)
	s_waitcnt lgkmcnt(0)
	s_barrier
	s_setprio 1
	s_waitcnt lgkmcnt(0)
	v_mfma_f32_16x16x32_bf16 v[60:63], v[144:147], v[194:197], v[60:63]
	v_mfma_f32_16x16x32_bf16 v[56:59], v[152:155], v[194:197], v[56:59]
	v_mfma_f32_16x16x32_bf16 v[52:55], v[144:147], v[212:215], v[52:55]
	v_mfma_f32_16x16x32_bf16 v[48:51], v[152:155], v[212:215], v[48:51]
	v_mfma_f32_16x16x32_bf16 v[36:39], v[144:147], v[220:223], v[36:39]
	v_mfma_f32_16x16x32_bf16 v[32:35], v[152:155], v[220:223], v[32:35]
	v_mfma_f32_16x16x32_bf16 v[20:23], v[144:147], v[228:231], v[20:23]
	v_mfma_f32_16x16x32_bf16 v[16:19], v[152:155], v[228:231], v[16:19]
	s_setprio 0
	s_setprio 1
	v_mfma_f32_16x16x32_bf16 v[60:63], v[148:151], v[208:211], v[60:63]
	v_mfma_f32_16x16x32_bf16 v[56:59], v[156:159], v[208:211], v[56:59]
	v_mfma_f32_16x16x32_bf16 v[52:55], v[148:151], v[216:219], v[52:55]
	v_mfma_f32_16x16x32_bf16 v[48:51], v[156:159], v[216:219], v[48:51]
	v_mfma_f32_16x16x32_bf16 v[36:39], v[148:151], v[224:227], v[36:39]
	v_mfma_f32_16x16x32_bf16 v[32:35], v[156:159], v[224:227], v[32:35]
	v_mfma_f32_16x16x32_bf16 v[20:23], v[148:151], v[232:235], v[20:23]
	v_mfma_f32_16x16x32_bf16 v[16:19], v[156:159], v[232:235], v[16:19]
	s_setprio 0
	s_setprio 1
	v_mfma_f32_16x16x32_bf16 v[44:47], v[178:181], v[194:197], v[44:47]
	v_mfma_f32_16x16x32_bf16 v[40:43], v[186:189], v[194:197], v[40:43]
	v_mfma_f32_16x16x32_bf16 v[28:31], v[178:181], v[212:215], v[28:31]
	v_mfma_f32_16x16x32_bf16 v[24:27], v[186:189], v[212:215], v[24:27]
	v_mfma_f32_16x16x32_bf16 v[12:15], v[178:181], v[220:223], v[12:15]
	v_mfma_f32_16x16x32_bf16 v[8:11], v[186:189], v[220:223], v[8:11]
	v_mfma_f32_16x16x32_bf16 v[4:7], v[178:181], v[228:231], v[4:7]
	v_mfma_f32_16x16x32_bf16 v[0:3], v[186:189], v[228:231], v[0:3]
	s_setprio 0
	s_setprio 1
	v_mfma_f32_16x16x32_bf16 v[44:47], v[182:185], v[208:211], v[44:47]
	v_mfma_f32_16x16x32_bf16 v[40:43], v[190:193], v[208:211], v[40:43]
	v_mfma_f32_16x16x32_bf16 v[28:31], v[182:185], v[216:219], v[28:31]
	v_mfma_f32_16x16x32_bf16 v[24:27], v[190:193], v[216:219], v[24:27]
	v_mfma_f32_16x16x32_bf16 v[12:15], v[182:185], v[224:227], v[12:15]
	v_mfma_f32_16x16x32_bf16 v[8:11], v[190:193], v[224:227], v[8:11]
	v_mfma_f32_16x16x32_bf16 v[4:7], v[182:185], v[232:235], v[4:7]
	v_mfma_f32_16x16x32_bf16 v[0:3], v[190:193], v[232:235], v[0:3]
	s_setprio 0
	s_barrier
	s_add_i32 s41, s41, 2
	s_add_u32 s0, s0, 0x100
	s_addc_u32 s1, s1, 0
	s_add_u32 s15, s15, 0x100
	s_addc_u32 s27, s27, 0
	s_cmp_gt_u32 s41, 13
	s_cbranch_scc0 .LBB0_1360
	s_mov_b64 s[46:47], 0x80
	s_and_b64 vcc, exec, s[8:9]
	s_cbranch_vccz .LBB0_1363
	s_barrier

; #define PG8_STAGE(bufoff, gbase, voff) do { _Pragma("unroll") for (int _i = 0; _i < 2; ++_i) \
;         __builtin_amdgcn_global_load_lds((const unsigned*)((const char*)(gbase) + (voff)[_i]), (PG8_LAS unsigned*)(lds + (bufoff) + ldsw + _i * 8192), 16, 0, 0); } while (0)
; #define PG8_LDA(dst, b, h) do { _Pragma("unroll") for (int m = 0; m < 4; ++m) _Pragma("unroll") for (int k = 0; k < 2; ++k) dst[m][k] = *(const PG8_LAS bf16x8*)(lds + PG8_SA(b, h) + aoff + m * 2048 + k * 1024); } while (0)
; #define PG8_LDB(dst, b, h) do { _Pragma("unroll") for (int n = 0; n < 2; ++n) _Pragma("unroll") for (int k = 0; k < 2; ++k) dst[n][k] = *(const PG8_LAS bf16x8*)(lds + PG8_SB(b, h) + boff + n * 2048 + k * 1024); } while (0)
; #define PG8_MMA(ai, bj, At, Bt) do { __builtin_amdgcn_s_setprio(1); _Pragma("unroll") for (int m = 0; m < 4; ++m) _Pragma("unroll") for (int n = 0; n < 2; ++n) _Pragma("unroll") for (int k = 0; k < 2; ++k) \
;         acc[ai][bj][m][n] = __builtin_amdgcn_mfma_f32_16x16x32_bf16(Bt[n][k], At[m][k], acc[ai][bj][m][n], 0, 0, 0); __builtin_amdgcn_s_setprio(0); } while (0)
; #define PG8_WAIT_V(n) asm volatile("s_waitcnt vmcnt(" #n ")" ::: "memory")
; #define PG8_BAR __builtin_amdgcn_s_barrier()
; template <class Epi, class Sched, bool ALIGN_EPI = false, bool SP2 = false>
; __device__ __forceinline__ void gemm_phase(PG8_LAS unsigned char* lds, const Gemm g, const Sched& S, const Epi& E, const int wave0) {
;     ...
;         for (int t = 0; t < nt; t += 2) {
;             const bool last = (t == nt - 2);
;             const char* a1 = cA + (size_t)(t + 1) * kstep;
;             const char* a2 = last ? nA : cA + (size_t)(t + 2) * kstep; const char* b2 = last ? nB : cB + (size_t)(t + 2) * kstep;
;             const char* a3 = a2 + kstep; const char* b3 = b2 + kstep;
;             if (last && has_next) S.a_ready(nxt);
;             if constexpr (SP2) {
;             PG8_LDB(B0, 0, 0); PG8_LDB(B1, 0, 1); PG8_SCHED; PG8_LDA(At, 0, 0); PG8_STAGE(PG8_SA(1, 1), a1 + hstepA, voffA);
;             PG8_WAIT_V(8); PG8_WAIT_L(0); PG8_BAR; PG8_MMA(0, 0, At, B0); PG8_MMA(0, 1, At, B1); PG8_BAR; PG8_SCHED;
;             PG8_LDA(At, 0, 1); PG8_STAGE(PG8_SB(0, 0), b2, voffB); PG8_STAGE(PG8_SB(0, 1), b2 + hstepB, voffB); PG8_STAGE(PG8_SA(0, 0), a2, voffA);
;             PG8_WAIT_V(8); PG8_WAIT_L(0); PG8_BAR; PG8_MMA(1, 0, At, B0); PG8_MMA(1, 1, At, B1); PG8_BAR; PG8_SCHED;
.LBB0_1571:
	s_add_u32 s16, s0, 0xfff80080
	s_addc_u32 s17, s1, -1
	s_add_i32 s46, 0, 0x10000
	s_cmp_eq_u32 s45, 28
	s_cselect_b32 s19, s9, s17
	s_cselect_b32 s18, s33, s16
	s_cselect_b32 s17, s7, s44
	s_cselect_b32 s16, s36, s37
	s_add_i32 s48, 0, 0x14000
	ds_read_b128 v[140:143], v252
	ds_read_b128 v[148:151], v252 offset:1024
	ds_read_b128 v[152:155], v252 offset:2048
	ds_read_b128 v[156:159], v252 offset:3072
	ds_read_b128 v[178:181], v253
	ds_read_b128 v[182:185], v253 offset:1024
	ds_read_b128 v[186:189], v253 offset:2048
	ds_read_b128 v[190:193], v253 offset:3072
	s_add_i32 m0, s15, 0xc000
	ds_read_b128 v[194:197], v147
	ds_read_b128 v[208:211], v147 offset:1024
	ds_read_b128 v[212:215], v147 offset:2048
	ds_read_b128 v[216:219], v147 offset:3072
	ds_read_b128 v[220:223], v147 offset:4096
	ds_read_b128 v[224:227], v147 offset:5120
	ds_read_b128 v[228:231], v147 offset:6144
	ds_read_b128 v[232:235], v147 offset:7168
	global_load_lds_dwordx4 v136, s[0:1]
	s_add_i32 m0, s15, 0xe000
	s_nop 0
	global_load_lds_dwordx4 v138, s[0:1]
	s_waitcnt vmcnt(8)
	s_waitcnt lgkmcnt(0)
	s_barrier
	s_setprio 1
	s_waitcnt lgkmcnt(0)
	v_mfma_f32_16x16x32_bf16 v[126:129], v[140:143], v[194:197], v[126:129]
	v_mfma_f32_16x16x32_bf16 v[122:125], v[152:155], v[194:197], v[122:125]
	v_mfma_f32_16x16x32_bf16 v[110:113], v[140:143], v[212:215], v[110:113]
	v_mfma_f32_16x16x32_bf16 v[106:109], v[152:155], v[212:215], v[106:109]
	v_mfma_f32_16x16x32_bf16 v[94:97], v[140:143], v[220:223], v[94:97]
	v_mfma_f32_16x16x32_bf16 v[90:93], v[152:155], v[220:223], v[90:93]
	v_mfma_f32_16x16x32_bf16 v[78:81], v[140:143], v[228:231], v[78:81]
	v_mfma_f32_16x16x32_bf16 v[74:77], v[152:155], v[228:231], v[74:77]
	s_setprio 0
	s_setprio 1
	v_mfma_f32_16x16x32_bf16 v[126:129], v[148:151], v[208:211], v[126:129]
	v_mfma_f32_16x16x32_bf16 v[122:125], v[156:159], v[208:211], v[122:125]
	v_mfma_f32_16x16x32_bf16 v[110:113], v[148:151], v[216:219], v[110:113]
	v_mfma_f32_16x16x32_bf16 v[106:109], v[156:159], v[216:219], v[106:109]
	v_mfma_f32_16x16x32_bf16 v[94:97], v[148:151], v[224:227], v[94:97]
	v_mfma_f32_16x16x32_bf16 v[90:93], v[156:159], v[224:227], v[90:93]
	v_mfma_f32_16x16x32_bf16 v[78:81], v[148:151], v[232:235], v[78:81]
	v_mfma_f32_16x16x32_bf16 v[74:77], v[156:159], v[232:235], v[74:77]
	s_setprio 0
	s_setprio 1
	v_mfma_f32_16x16x32_bf16 v[118:121], v[178:181], v[194:197], v[118:121]
	v_mfma_f32_16x16x32_bf16 v[114:117], v[186:189], v[194:197], v[114:117]
	v_mfma_f32_16x16x32_bf16 v[102:105], v[178:181], v[212:215], v[102:105]
	v_mfma_f32_16x16x32_bf16 v[98:101], v[186:189], v[212:215], v[98:101]
	v_mfma_f32_16x16x32_bf16 v[86:89], v[178:181], v[220:223], v[86:89]
	v_mfma_f32_16x16x32_bf16 v[82:85], v[186:189], v[220:223], v[82:85]
	v_mfma_f32_16x16x32_bf16 v[70:73], v[178:181], v[228:231], v[70:73]
	v_mfma_f32_16x16x32_bf16 v[66:69], v[186:189], v[228:231], v[66:69]
	s_setprio 0
	s_setprio 1
	v_mfma_f32_16x16x32_bf16 v[118:121], v[182:185], v[208:211], v[118:121]
	v_mfma_f32_16x16x32_bf16 v[114:117], v[190:193], v[208:211], v[114:117]
	v_mfma_f32_16x16x32_bf16 v[102:105], v[182:185], v[216:219], v[102:105]
	v_mfma_f32_16x16x32_bf16 v[98:101], v[190:193], v[216:219], v[98:101]
	v_mfma_f32_16x16x32_bf16 v[86:89], v[182:185], v[224:227], v[86:89]
	v_mfma_f32_16x16x32_bf16 v[82:85], v[190:193], v[224:227], v[82:85]
	v_mfma_f32_16x16x32_bf16 v[70:73], v[182:185], v[232:235], v[70:73]
	v_mfma_f32_16x16x32_bf16 v[66:69], v[190:193], v[232:235], v[66:69]
	s_setprio 0
	s_barrier
	s_add_i32 s46, s46, s28
	s_mov_b32 m0, s46
	ds_read_b128 v[194:197], v147 offset:16384
	ds_read_b128 v[208:211], v147 offset:17408
	ds_read_b128 v[212:215], v147 offset:18432
	ds_read_b128 v[216:219], v147 offset:19456
	ds_read_b128 v[220:223], v147 offset:20480
	ds_read_b128 v[224:227], v147 offset:21504
	ds_read_b128 v[228:231], v147 offset:22528
	ds_read_b128 v[232:235], v147 offset:23552
	global_load_lds_dwordx4 v64, s[16:17]
	s_add_i32 m0, s46, 0x2000
	s_add_u32 s46, s16, 0x80000
	s_addc_u32 s47, s17, 0
	s_add_i32 s48, s48, s28
	global_load_lds_dwordx4 v130, s[16:17]
	s_mov_b32 m0, s48
	s_mov_b64 s[100:101], s[18:19]
	global_load_lds_dwordx4 v64, s[46:47]
	s_add_i32 m0, s48, 0x2000
	s_nop 0
	global_load_lds_dwordx4 v130, s[46:47]
	s_mov_b32 m0, s15
	s_nop 0
	global_load_lds_dwordx4 v134, s[18:19]
	s_mov_b32 m0, s27
	s_nop 0
	global_load_lds_dwordx4 v132, s[18:19]
	s_waitcnt vmcnt(8)
	s_waitcnt lgkmcnt(0)
	s_barrier
	s_setprio 1
	s_waitcnt lgkmcnt(0)
	v_mfma_f32_16x16x32_bf16 v[60:63], v[140:143], v[194:197], v[60:63]
	v_mfma_f32_16x16x32_bf16 v[56:59], v[152:155], v[194:197], v[56:59]
	v_mfma_f32_16x16x32_bf16 v[44:47], v[140:143], v[212:215], v[44:47]
	v_mfma_f32_16x16x32_bf16 v[40:43], v[152:155], v[212:215], v[40:43]
	v_mfma_f32_16x16x32_bf16 v[28:31], v[140:143], v[220:223], v[28:31]
	v_mfma_f32_16x16x32_bf16 v[24:27], v[152:155], v[220:223], v[24:27]
	v_mfma_f32_16x16x32_bf16 v[12:15], v[140:143], v[228:231], v[12:15]
	v_mfma_f32_16x16x32_bf16 v[8:11], v[152:155], v[228:231], v[8:11]
	s_setprio 0
	s_setprio 1
	v_mfma_f32_16x16x32_bf16 v[60:63], v[148:151], v[208:211], v[60:63]
	v_mfma_f32_16x16x32_bf16 v[56:59], v[156:159], v[208:211], v[56:59]
	v_mfma_f32_16x16x32_bf16 v[44:47], v[148:151], v[216:219], v[44:47]
	v_mfma_f32_16x16x32_bf16 v[40:43], v[156:159], v[216:219], v[40:43]
	v_mfma_f32_16x16x32_bf16 v[28:31], v[148:151], v[224:227], v[28:31]
	v_mfma_f32_16x16x32_bf16 v[24:27], v[156:159], v[224:227], v[24:27]
	v_mfma_f32_16x16x32_bf16 v[12:15], v[148:151], v[232:235], v[12:15]
	v_mfma_f32_16x16x32_bf16 v[8:11], v[156:159], v[232:235], v[8:11]
	s_setprio 0
	s_setprio 1
	v_mfma_f32_16x16x32_bf16 v[52:55], v[178:181], v[194:197], v[52:55]
	v_mfma_f32_16x16x32_bf16 v[48:51], v[186:189], v[194:197], v[48:51]
	v_mfma_f32_16x16x32_bf16 v[36:39], v[178:181], v[212:215], v[36:39]
	v_mfma_f32_16x16x32_bf16 v[32:35], v[186:189], v[212:215], v[32:35]
	v_mfma_f32_16x16x32_bf16 v[20:23], v[178:181], v[220:223], v[20:23]
	v_mfma_f32_16x16x32_bf16 v[16:19], v[186:189], v[220:223], v[16:19]
	v_mfma_f32_16x16x32_bf16 v[4:7], v[178:181], v[228:231], v[4:7]
	v_mfma_f32_16x16x32_bf16 v[0:3], v[186:189], v[228:231], v[0:3]
	s_setprio 0
	s_setprio 1
	v_mfma_f32_16x16x32_bf16 v[52:55], v[182:185], v[208:211], v[52:55]
	v_mfma_f32_16x16x32_bf16 v[48:51], v[190:193], v[208:211], v[48:51]
	v_mfma_f32_16x16x32_bf16 v[36:39], v[182:185], v[216:219], v[36:39]
	v_mfma_f32_16x16x32_bf16 v[32:35], v[190:193], v[216:219], v[32:35]
	v_mfma_f32_16x16x32_bf16 v[20:23], v[182:185], v[224:227], v[20:23]
	v_mfma_f32_16x16x32_bf16 v[16:19], v[190:193], v[224:227], v[16:19]
	v_mfma_f32_16x16x32_bf16 v[4:7], v[182:185], v[232:235], v[4:7]
	v_mfma_f32_16x16x32_bf16 v[0:3], v[190:193], v[232:235], v[0:3]
	s_setprio 0
	s_barrier
; #define PG8_STAGE(bufoff, gbase, voff) do { _Pragma("unroll") for (int _i = 0; _i < 2; ++_i) \
;         __builtin_amdgcn_global_load_lds((const unsigned*)((const char*)(gbase) + (voff)[_i]), (PG8_LAS unsigned*)(lds + (bufoff) + ldsw + _i * 8192), 16, 0, 0); } while (0)
; #define PG8_LDA(dst, b, h) do { _Pragma("unroll") for (int m = 0; m < 4; ++m) _Pragma("unroll") for (int k = 0; k < 2; ++k) dst[m][k] = *(const PG8_LAS bf16x8*)(lds + PG8_SA(b, h) + aoff + m * 2048 + k * 1024); } while (0)
; #define PG8_LDB(dst, b, h) do { _Pragma("unroll") for (int n = 0; n < 2; ++n) _Pragma("unroll") for (int k = 0; k < 2; ++k) dst[n][k] = *(const PG8_LAS bf16x8*)(lds + PG8_SB(b, h) + boff + n * 2048 + k * 1024); } while (0)
; #define PG8_MMA(ai, bj, At, Bt) do { __builtin_amdgcn_s_setprio(1); _Pragma("unroll") for (int m = 0; m < 4; ++m) _Pragma("unroll") for (int n = 0; n < 2; ++n) _Pragma("unroll") for (int k = 0; k < 2; ++k) \
;         acc[ai][bj][m][n] = __builtin_amdgcn_mfma_f32_16x16x32_bf16(Bt[n][k], At[m][k], acc[ai][bj][m][n], 0, 0, 0); __builtin_amdgcn_s_setprio(0); } while (0)
; #define PG8_WAIT_V(n) asm volatile("s_waitcnt vmcnt(" #n ")" ::: "memory")
; #define PG8_WAIT_L(n) asm volatile("s_waitcnt lgkmcnt(" #n ")" ::: "memory")
; #define PG8_BAR __builtin_amdgcn_s_barrier()
; #define PG8_SCHED __builtin_amdgcn_sched_barrier(0)
; template <class Epi, class Sched, bool ALIGN_EPI = false, bool SP2 = false>
; __device__ __forceinline__ void gemm_phase(PG8_LAS unsigned char* lds, const Gemm g, const Sched& S, const Epi& E, const int wave0) {
;     ...
;             PG8_LDB(B0, 1, 0); PG8_LDB(B1, 1, 1); PG8_SCHED; PG8_LDA(At, 1, 0); PG8_STAGE(PG8_SA(0, 1), a2 + hstepA, voffA);
;             PG8_WAIT_V(8); PG8_WAIT_L(0); PG8_BAR; PG8_MMA(0, 0, At, B0); PG8_MMA(0, 1, At, B1); PG8_BAR; PG8_SCHED;
;             PG8_LDA(At, 1, 1); PG8_STAGE(PG8_SB(1, 0), b3, voffB); PG8_STAGE(PG8_SB(1, 1), b3 + hstepB, voffB); PG8_STAGE(PG8_SA(1, 0), a3, voffA);
;             PG8_WAIT_V(8); PG8_WAIT_L(0); PG8_BAR; PG8_MMA(1, 0, At, B0); PG8_MMA(1, 1, At, B1); PG8_BAR; PG8_SCHED;
;     ...
;         if constexpr (ALIGN_EPI) { if (wr == 0) PG8_BAR; }
	s_add_i32 s46, 0, 0x18000
	s_add_i32 s47, 0, 0x1c000
	ds_read_b128 v[140:143], v254
	ds_read_b128 v[148:151], v254 offset:1024
	ds_read_b128 v[152:155], v254 offset:2048
	ds_read_b128 v[156:159], v254 offset:3072
	ds_read_b128 v[178:181], v255
	ds_read_b128 v[182:185], v255 offset:1024
	ds_read_b128 v[186:189], v255 offset:2048
	ds_read_b128 v[190:193], v255 offset:3072
	s_add_u32 s18, s18, 0x80000
	s_addc_u32 s19, s19, 0
	s_mov_b32 m0, s29
	ds_read_b128 v[194:197], v147 offset:32768
	ds_read_b128 v[208:211], v147 offset:33792
	ds_read_b128 v[212:215], v147 offset:34816
	ds_read_b128 v[216:219], v147 offset:35840
	ds_read_b128 v[220:223], v147 offset:36864
	ds_read_b128 v[224:227], v147 offset:37888
	ds_read_b128 v[228:231], v147 offset:38912
	ds_read_b128 v[232:235], v147 offset:39936
	global_load_lds_dwordx4 v134, s[18:19]
	s_mov_b32 m0, s30
	s_nop 0
	global_load_lds_dwordx4 v132, s[18:19]
	s_waitcnt vmcnt(8)
	s_waitcnt lgkmcnt(0)
	s_barrier
	s_setprio 1
	s_waitcnt lgkmcnt(0)
	v_mfma_f32_16x16x32_bf16 v[126:129], v[140:143], v[194:197], v[126:129]
	v_mfma_f32_16x16x32_bf16 v[122:125], v[152:155], v[194:197], v[122:125]
	v_mfma_f32_16x16x32_bf16 v[110:113], v[140:143], v[212:215], v[110:113]
	v_mfma_f32_16x16x32_bf16 v[106:109], v[152:155], v[212:215], v[106:109]
	v_mfma_f32_16x16x32_bf16 v[94:97], v[140:143], v[220:223], v[94:97]
	v_mfma_f32_16x16x32_bf16 v[90:93], v[152:155], v[220:223], v[90:93]
	v_mfma_f32_16x16x32_bf16 v[78:81], v[140:143], v[228:231], v[78:81]
	v_mfma_f32_16x16x32_bf16 v[74:77], v[152:155], v[228:231], v[74:77]
	s_setprio 0
	s_setprio 1
	v_mfma_f32_16x16x32_bf16 v[126:129], v[148:151], v[208:211], v[126:129]
	v_mfma_f32_16x16x32_bf16 v[122:125], v[156:159], v[208:211], v[122:125]
	v_mfma_f32_16x16x32_bf16 v[110:113], v[148:151], v[216:219], v[110:113]
	v_mfma_f32_16x16x32_bf16 v[106:109], v[156:159], v[216:219], v[106:109]
	v_mfma_f32_16x16x32_bf16 v[94:97], v[148:151], v[224:227], v[94:97]
	v_mfma_f32_16x16x32_bf16 v[90:93], v[156:159], v[224:227], v[90:93]
	v_mfma_f32_16x16x32_bf16 v[78:81], v[148:151], v[232:235], v[78:81]
	v_mfma_f32_16x16x32_bf16 v[74:77], v[156:159], v[232:235], v[74:77]
	s_setprio 0
	s_setprio 1
	v_mfma_f32_16x16x32_bf16 v[118:121], v[178:181], v[194:197], v[118:121]
	v_mfma_f32_16x16x32_bf16 v[114:117], v[186:189], v[194:197], v[114:117]
	v_mfma_f32_16x16x32_bf16 v[102:105], v[178:181], v[212:215], v[102:105]
	v_mfma_f32_16x16x32_bf16 v[98:101], v[186:189], v[212:215], v[98:101]
	v_mfma_f32_16x16x32_bf16 v[86:89], v[178:181], v[220:223], v[86:89]
	v_mfma_f32_16x16x32_bf16 v[82:85], v[186:189], v[220:223], v[82:85]
	v_mfma_f32_16x16x32_bf16 v[70:73], v[178:181], v[228:231], v[70:73]
	v_mfma_f32_16x16x32_bf16 v[66:69], v[186:189], v[228:231], v[66:69]
	s_setprio 0
	s_setprio 1
	v_mfma_f32_16x16x32_bf16 v[118:121], v[182:185], v[208:211], v[118:121]
	v_mfma_f32_16x16x32_bf16 v[114:117], v[190:193], v[208:211], v[114:117]
	v_mfma_f32_16x16x32_bf16 v[102:105], v[182:185], v[216:219], v[102:105]
	v_mfma_f32_16x16x32_bf16 v[98:101], v[190:193], v[216:219], v[98:101]
	v_mfma_f32_16x16x32_bf16 v[86:89], v[182:185], v[224:227], v[86:89]
	v_mfma_f32_16x16x32_bf16 v[82:85], v[190:193], v[224:227], v[82:85]
	v_mfma_f32_16x16x32_bf16 v[70:73], v[182:185], v[232:235], v[70:73]
	v_mfma_f32_16x16x32_bf16 v[66:69], v[190:193], v[232:235], v[66:69]
	s_setprio 0
	s_barrier
	s_add_i32 s18, s46, s28
	s_add_u32 s50, s16, 0x80
	s_addc_u32 s51, s17, 0
	s_mov_b32 m0, s18
	ds_read_b128 v[194:197], v147 offset:49152
	ds_read_b128 v[208:211], v147 offset:50176
	ds_read_b128 v[212:215], v147 offset:51200
	ds_read_b128 v[216:219], v147 offset:52224
	ds_read_b128 v[220:223], v147 offset:53248
	ds_read_b128 v[224:227], v147 offset:54272
	ds_read_b128 v[228:231], v147 offset:55296
	ds_read_b128 v[232:235], v147 offset:56320
	global_load_lds_dwordx4 v64, s[50:51]
	s_add_i32 m0, s18, 0x2000
	s_add_u32 s16, s16, 0x80080
	s_addc_u32 s17, s17, 0
	s_add_i32 s18, s47, s28
	global_load_lds_dwordx4 v130, s[50:51]
	s_mov_b32 m0, s18
	s_nop 0
	global_load_lds_dwordx4 v64, s[16:17]
	s_add_i32 m0, s18, 0x2000
	s_nop 0
	global_load_lds_dwordx4 v130, s[16:17]
	s_add_u32 s100, s100, 0x80
	s_addc_u32 s101, s101, 0
	s_mov_b32 m0, s31
	s_nop 0
	global_load_lds_dwordx4 v134, s[100:101]
	s_mov_b32 m0, s34
	s_nop 0
	global_load_lds_dwordx4 v132, s[100:101]
	s_waitcnt vmcnt(8)
	s_waitcnt lgkmcnt(0)
	s_barrier
	s_setprio 1
	s_waitcnt lgkmcnt(0)
	v_mfma_f32_16x16x32_bf16 v[60:63], v[140:143], v[194:197], v[60:63]
	v_mfma_f32_16x16x32_bf16 v[56:59], v[152:155], v[194:197], v[56:59]
	v_mfma_f32_16x16x32_bf16 v[44:47], v[140:143], v[212:215], v[44:47]
	v_mfma_f32_16x16x32_bf16 v[40:43], v[152:155], v[212:215], v[40:43]
	v_mfma_f32_16x16x32_bf16 v[28:31], v[140:143], v[220:223], v[28:31]
	v_mfma_f32_16x16x32_bf16 v[24:27], v[152:155], v[220:223], v[24:27]
	v_mfma_f32_16x16x32_bf16 v[12:15], v[140:143], v[228:231], v[12:15]
	v_mfma_f32_16x16x32_bf16 v[8:11], v[152:155], v[228:231], v[8:11]
	s_setprio 0
	s_setprio 1
	v_mfma_f32_16x16x32_bf16 v[60:63], v[148:151], v[208:211], v[60:63]
	v_mfma_f32_16x16x32_bf16 v[56:59], v[156:159], v[208:211], v[56:59]
	v_mfma_f32_16x16x32_bf16 v[44:47], v[148:151], v[216:219], v[44:47]
	v_mfma_f32_16x16x32_bf16 v[40:43], v[156:159], v[216:219], v[40:43]
	v_mfma_f32_16x16x32_bf16 v[28:31], v[148:151], v[224:227], v[28:31]
	v_mfma_f32_16x16x32_bf16 v[24:27], v[156:159], v[224:227], v[24:27]
	v_mfma_f32_16x16x32_bf16 v[12:15], v[148:151], v[232:235], v[12:15]
	v_mfma_f32_16x16x32_bf16 v[8:11], v[156:159], v[232:235], v[8:11]
	s_setprio 0
	s_setprio 1
	v_mfma_f32_16x16x32_bf16 v[52:55], v[178:181], v[194:197], v[52:55]
	v_mfma_f32_16x16x32_bf16 v[48:51], v[186:189], v[194:197], v[48:51]
	v_mfma_f32_16x16x32_bf16 v[36:39], v[178:181], v[212:215], v[36:39]
	v_mfma_f32_16x16x32_bf16 v[32:35], v[186:189], v[212:215], v[32:35]
	v_mfma_f32_16x16x32_bf16 v[20:23], v[178:181], v[220:223], v[20:23]
	v_mfma_f32_16x16x32_bf16 v[16:19], v[186:189], v[220:223], v[16:19]
	v_mfma_f32_16x16x32_bf16 v[4:7], v[178:181], v[228:231], v[4:7]
	v_mfma_f32_16x16x32_bf16 v[0:3], v[186:189], v[228:231], v[0:3]
	s_setprio 0
	s_setprio 1
	v_mfma_f32_16x16x32_bf16 v[52:55], v[182:185], v[208:211], v[52:55]
	v_mfma_f32_16x16x32_bf16 v[48:51], v[190:193], v[208:211], v[48:51]
	v_mfma_f32_16x16x32_bf16 v[36:39], v[182:185], v[216:219], v[36:39]
	v_mfma_f32_16x16x32_bf16 v[32:35], v[190:193], v[216:219], v[32:35]
	v_mfma_f32_16x16x32_bf16 v[20:23], v[182:185], v[224:227], v[20:23]
	v_mfma_f32_16x16x32_bf16 v[16:19], v[190:193], v[224:227], v[16:19]
	v_mfma_f32_16x16x32_bf16 v[4:7], v[182:185], v[232:235], v[4:7]
	v_mfma_f32_16x16x32_bf16 v[0:3], v[190:193], v[232:235], v[0:3]
	s_setprio 0
	s_barrier
	s_add_i32 s45, s45, 2
	s_add_u32 s0, s0, 0x100
	s_addc_u32 s1, s1, 0
	s_add_u32 s37, s37, 0x100
	s_addc_u32 s44, s44, 0
	s_cmp_gt_u32 s45, 29
	s_cbranch_scc0 .LBB0_1571
	s_mov_b64 s[50:51], 0x80
	s_and_b64 vcc, exec, s[4:5]
	s_cbranch_vccz .LBB0_1574
	s_barrier

; #define PG8_STAGE(bufoff, gbase, voff) do { _Pragma("unroll") for (int _i = 0; _i < 2; ++_i) \
;         __builtin_amdgcn_global_load_lds((const unsigned*)((const char*)(gbase) + (voff)[_i]), (PG8_LAS unsigned*)(lds + (bufoff) + ldsw + _i * 8192), 16, 0, 0); } while (0)
; #define PG8_LDA(dst, b, h) do { _Pragma("unroll") for (int m = 0; m < 4; ++m) _Pragma("unroll") for (int k = 0; k < 2; ++k) dst[m][k] = *(const PG8_LAS bf16x8*)(lds + PG8_SA(b, h) + aoff + m * 2048 + k * 1024); } while (0)
; #define PG8_LDB(dst, b, h) do { _Pragma("unroll") for (int n = 0; n < 2; ++n) _Pragma("unroll") for (int k = 0; k < 2; ++k) dst[n][k] = *(const PG8_LAS bf16x8*)(lds + PG8_SB(b, h) + boff + n * 2048 + k * 1024); } while (0)
; #define PG8_MMA(ai, bj, At, Bt) do { __builtin_amdgcn_s_setprio(1); _Pragma("unroll") for (int m = 0; m < 4; ++m) _Pragma("unroll") for (int n = 0; n < 2; ++n) _Pragma("unroll") for (int k = 0; k < 2; ++k) \
;         acc[ai][bj][m][n] = __builtin_amdgcn_mfma_f32_16x16x32_bf16(Bt[n][k], At[m][k], acc[ai][bj][m][n], 0, 0, 0); __builtin_amdgcn_s_setprio(0); } while (0)
; #define PG8_WAIT_V(n) asm volatile("s_waitcnt vmcnt(" #n ")" ::: "memory")
; #define PG8_BAR __builtin_amdgcn_s_barrier()
; template <class Epi, class Sched, bool ALIGN_EPI = false, bool SP2 = false>
; __device__ __forceinline__ void gemm_phase(PG8_LAS unsigned char* lds, const Gemm g, const Sched& S, const Epi& E, const int wave0) {
;     ...
;         for (int t = 0; t < nt; t += 2) {
;             const bool last = (t == nt - 2);
;             const char* a1 = cA + (size_t)(t + 1) * kstep;
;             const char* a2 = last ? nA : cA + (size_t)(t + 2) * kstep; const char* b2 = last ? nB : cB + (size_t)(t + 2) * kstep;
;             const char* a3 = a2 + kstep; const char* b3 = b2 + kstep;
;             if (last && has_next) S.a_ready(nxt);
;             if constexpr (SP2) {
;             PG8_LDB(B0, 0, 0); PG8_LDB(B1, 0, 1); PG8_SCHED; PG8_LDA(At, 0, 0); PG8_STAGE(PG8_SA(1, 1), a1 + hstepA, voffA);
;             PG8_WAIT_V(8); PG8_WAIT_L(0); PG8_BAR; PG8_MMA(0, 0, At, B0); PG8_MMA(0, 1, At, B1); PG8_BAR; PG8_SCHED;
;             PG8_LDA(At, 0, 1); PG8_STAGE(PG8_SB(0, 0), b2, voffB); PG8_STAGE(PG8_SB(0, 1), b2 + hstepB, voffB); PG8_STAGE(PG8_SA(0, 0), a2, voffA);
;             PG8_WAIT_V(8); PG8_WAIT_L(0); PG8_BAR; PG8_MMA(1, 0, At, B0); PG8_MMA(1, 1, At, B1); PG8_BAR; PG8_SCHED;
.LBB0_1685:
	s_add_u32 s16, s0, 0xffe00080
	s_addc_u32 s17, s1, -1
	s_add_i32 s43, 0, 0x10000
	s_cmpk_eq_i32 s42, 0x7c
	s_cselect_b32 s19, s11, s17
	s_cselect_b32 s18, s34, s16
	s_cselect_b32 s17, s9, s37
	s_cselect_b32 s16, s35, s36
	s_add_i32 s46, 0, 0x14000
	ds_read_b128 v[144:147], v252
	ds_read_b128 v[148:151], v252 offset:1024
	ds_read_b128 v[152:155], v252 offset:2048
	ds_read_b128 v[156:159], v252 offset:3072
	ds_read_b128 v[178:181], v253
	ds_read_b128 v[182:185], v253 offset:1024
	ds_read_b128 v[186:189], v253 offset:2048
	ds_read_b128 v[190:193], v253 offset:3072
	s_add_i32 m0, s21, 0xc000
	ds_read_b128 v[194:197], v143
	ds_read_b128 v[208:211], v143 offset:1024
	ds_read_b128 v[212:215], v143 offset:2048
	ds_read_b128 v[216:219], v143 offset:3072
	ds_read_b128 v[220:223], v143 offset:4096
	ds_read_b128 v[224:227], v143 offset:5120
	ds_read_b128 v[228:231], v143 offset:6144
	ds_read_b128 v[232:235], v143 offset:7168
	global_load_lds_dwordx4 v136, s[0:1]
	s_add_i32 m0, s21, 0xe000
	s_nop 0
	global_load_lds_dwordx4 v138, s[0:1]
	s_waitcnt vmcnt(8)
	s_waitcnt lgkmcnt(0)
	s_barrier
	s_setprio 1
	s_waitcnt lgkmcnt(0)
	v_mfma_f32_16x16x32_bf16 v[126:129], v[144:147], v[194:197], v[126:129]
	v_mfma_f32_16x16x32_bf16 v[122:125], v[152:155], v[194:197], v[122:125]
	v_mfma_f32_16x16x32_bf16 v[118:121], v[144:147], v[212:215], v[118:121]
	v_mfma_f32_16x16x32_bf16 v[114:117], v[152:155], v[212:215], v[114:117]
	v_mfma_f32_16x16x32_bf16 v[102:105], v[144:147], v[220:223], v[102:105]
	v_mfma_f32_16x16x32_bf16 v[98:101], v[152:155], v[220:223], v[98:101]
	v_mfma_f32_16x16x32_bf16 v[86:89], v[144:147], v[228:231], v[86:89]
	v_mfma_f32_16x16x32_bf16 v[82:85], v[152:155], v[228:231], v[82:85]
	s_setprio 0
	s_setprio 1
	v_mfma_f32_16x16x32_bf16 v[126:129], v[148:151], v[208:211], v[126:129]
	v_mfma_f32_16x16x32_bf16 v[122:125], v[156:159], v[208:211], v[122:125]
	v_mfma_f32_16x16x32_bf16 v[118:121], v[148:151], v[216:219], v[118:121]
	v_mfma_f32_16x16x32_bf16 v[114:117], v[156:159], v[216:219], v[114:117]
	v_mfma_f32_16x16x32_bf16 v[102:105], v[148:151], v[224:227], v[102:105]
	v_mfma_f32_16x16x32_bf16 v[98:101], v[156:159], v[224:227], v[98:101]
	v_mfma_f32_16x16x32_bf16 v[86:89], v[148:151], v[232:235], v[86:89]
	v_mfma_f32_16x16x32_bf16 v[82:85], v[156:159], v[232:235], v[82:85]
	s_setprio 0
	s_setprio 1
	v_mfma_f32_16x16x32_bf16 v[110:113], v[178:181], v[194:197], v[110:113]
	v_mfma_f32_16x16x32_bf16 v[106:109], v[186:189], v[194:197], v[106:109]
	v_mfma_f32_16x16x32_bf16 v[94:97], v[178:181], v[212:215], v[94:97]
	v_mfma_f32_16x16x32_bf16 v[90:93], v[186:189], v[212:215], v[90:93]
	v_mfma_f32_16x16x32_bf16 v[78:81], v[178:181], v[220:223], v[78:81]
	v_mfma_f32_16x16x32_bf16 v[74:77], v[186:189], v[220:223], v[74:77]
	v_mfma_f32_16x16x32_bf16 v[70:73], v[178:181], v[228:231], v[70:73]
	v_mfma_f32_16x16x32_bf16 v[66:69], v[186:189], v[228:231], v[66:69]
	s_setprio 0
	s_setprio 1
	v_mfma_f32_16x16x32_bf16 v[110:113], v[182:185], v[208:211], v[110:113]
	v_mfma_f32_16x16x32_bf16 v[106:109], v[190:193], v[208:211], v[106:109]
	v_mfma_f32_16x16x32_bf16 v[94:97], v[182:185], v[216:219], v[94:97]
	v_mfma_f32_16x16x32_bf16 v[90:93], v[190:193], v[216:219], v[90:93]
	v_mfma_f32_16x16x32_bf16 v[78:81], v[182:185], v[224:227], v[78:81]
	v_mfma_f32_16x16x32_bf16 v[74:77], v[190:193], v[224:227], v[74:77]
	v_mfma_f32_16x16x32_bf16 v[70:73], v[182:185], v[232:235], v[70:73]
	v_mfma_f32_16x16x32_bf16 v[66:69], v[190:193], v[232:235], v[66:69]
	s_setprio 0
	s_barrier
	s_add_i32 s43, s43, s20
	s_mov_b32 m0, s43
	ds_read_b128 v[194:197], v143 offset:16384
	ds_read_b128 v[208:211], v143 offset:17408
	ds_read_b128 v[212:215], v143 offset:18432
	ds_read_b128 v[216:219], v143 offset:19456
	ds_read_b128 v[220:223], v143 offset:20480
	ds_read_b128 v[224:227], v143 offset:21504
	ds_read_b128 v[228:231], v143 offset:22528
	ds_read_b128 v[232:235], v143 offset:23552
	global_load_lds_dwordx4 v64, s[16:17]
	s_add_i32 m0, s43, 0x2000
	s_add_u32 s44, s16, 0x200000
	s_addc_u32 s45, s17, 0
	s_add_i32 s43, s46, s20
	global_load_lds_dwordx4 v130, s[16:17]
	s_mov_b32 m0, s43
	s_mov_b64 s[100:101], s[18:19]
	global_load_lds_dwordx4 v64, s[44:45]
	s_add_i32 m0, s43, 0x2000
	s_nop 0
	global_load_lds_dwordx4 v130, s[44:45]
	s_mov_b32 m0, s21
	s_nop 0
	global_load_lds_dwordx4 v134, s[18:19]
	s_mov_b32 m0, s25
	s_nop 0
	global_load_lds_dwordx4 v132, s[18:19]
	s_waitcnt vmcnt(8)
	s_waitcnt lgkmcnt(0)
	s_barrier
	s_setprio 1
	s_waitcnt lgkmcnt(0)
	v_mfma_f32_16x16x32_bf16 v[60:63], v[144:147], v[194:197], v[60:63]
	v_mfma_f32_16x16x32_bf16 v[56:59], v[152:155], v[194:197], v[56:59]
	v_mfma_f32_16x16x32_bf16 v[52:55], v[144:147], v[212:215], v[52:55]
	v_mfma_f32_16x16x32_bf16 v[48:51], v[152:155], v[212:215], v[48:51]
	v_mfma_f32_16x16x32_bf16 v[36:39], v[144:147], v[220:223], v[36:39]
	v_mfma_f32_16x16x32_bf16 v[32:35], v[152:155], v[220:223], v[32:35]
	v_mfma_f32_16x16x32_bf16 v[20:23], v[144:147], v[228:231], v[20:23]
	v_mfma_f32_16x16x32_bf16 v[16:19], v[152:155], v[228:231], v[16:19]
	s_setprio 0
	s_setprio 1
	v_mfma_f32_16x16x32_bf16 v[60:63], v[148:151], v[208:211], v[60:63]
	v_mfma_f32_16x16x32_bf16 v[56:59], v[156:159], v[208:211], v[56:59]
	v_mfma_f32_16x16x32_bf16 v[52:55], v[148:151], v[216:219], v[52:55]
	v_mfma_f32_16x16x32_bf16 v[48:51], v[156:159], v[216:219], v[48:51]
	v_mfma_f32_16x16x32_bf16 v[36:39], v[148:151], v[224:227], v[36:39]
	v_mfma_f32_16x16x32_bf16 v[32:35], v[156:159], v[224:227], v[32:35]
	v_mfma_f32_16x16x32_bf16 v[20:23], v[148:151], v[232:235], v[20:23]
	v_mfma_f32_16x16x32_bf16 v[16:19], v[156:159], v[232:235], v[16:19]
	s_setprio 0
	s_setprio 1
	v_mfma_f32_16x16x32_bf16 v[44:47], v[178:181], v[194:197], v[44:47]
	v_mfma_f32_16x16x32_bf16 v[40:43], v[186:189], v[194:197], v[40:43]
	v_mfma_f32_16x16x32_bf16 v[28:31], v[178:181], v[212:215], v[28:31]
	v_mfma_f32_16x16x32_bf16 v[24:27], v[186:189], v[212:215], v[24:27]
	v_mfma_f32_16x16x32_bf16 v[12:15], v[178:181], v[220:223], v[12:15]
	v_mfma_f32_16x16x32_bf16 v[8:11], v[186:189], v[220:223], v[8:11]
	v_mfma_f32_16x16x32_bf16 v[4:7], v[178:181], v[228:231], v[4:7]
	v_mfma_f32_16x16x32_bf16 v[0:3], v[186:189], v[228:231], v[0:3]
	s_setprio 0
	s_setprio 1
	v_mfma_f32_16x16x32_bf16 v[44:47], v[182:185], v[208:211], v[44:47]
	v_mfma_f32_16x16x32_bf16 v[40:43], v[190:193], v[208:211], v[40:43]
	v_mfma_f32_16x16x32_bf16 v[28:31], v[182:185], v[216:219], v[28:31]
	v_mfma_f32_16x16x32_bf16 v[24:27], v[190:193], v[216:219], v[24:27]
	v_mfma_f32_16x16x32_bf16 v[12:15], v[182:185], v[224:227], v[12:15]
	v_mfma_f32_16x16x32_bf16 v[8:11], v[190:193], v[224:227], v[8:11]
	v_mfma_f32_16x16x32_bf16 v[4:7], v[182:185], v[232:235], v[4:7]
	v_mfma_f32_16x16x32_bf16 v[0:3], v[190:193], v[232:235], v[0:3]
	s_setprio 0
	s_barrier
; #define PG8_STAGE(bufoff, gbase, voff) do { _Pragma("unroll") for (int _i = 0; _i < 2; ++_i) \
;         __builtin_amdgcn_global_load_lds((const unsigned*)((const char*)(gbase) + (voff)[_i]), (PG8_LAS unsigned*)(lds + (bufoff) + ldsw + _i * 8192), 16, 0, 0); } while (0)
; #define PG8_LDA(dst, b, h) do { _Pragma("unroll") for (int m = 0; m < 4; ++m) _Pragma("unroll") for (int k = 0; k < 2; ++k) dst[m][k] = *(const PG8_LAS bf16x8*)(lds + PG8_SA(b, h) + aoff + m * 2048 + k * 1024); } while (0)
; #define PG8_LDB(dst, b, h) do { _Pragma("unroll") for (int n = 0; n < 2; ++n) _Pragma("unroll") for (int k = 0; k < 2; ++k) dst[n][k] = *(const PG8_LAS bf16x8*)(lds + PG8_SB(b, h) + boff + n * 2048 + k * 1024); } while (0)
; #define PG8_MMA(ai, bj, At, Bt) do { __builtin_amdgcn_s_setprio(1); _Pragma("unroll") for (int m = 0; m < 4; ++m) _Pragma("unroll") for (int n = 0; n < 2; ++n) _Pragma("unroll") for (int k = 0; k < 2; ++k) \
;         acc[ai][bj][m][n] = __builtin_amdgcn_mfma_f32_16x16x32_bf16(Bt[n][k], At[m][k], acc[ai][bj][m][n], 0, 0, 0); __builtin_amdgcn_s_setprio(0); } while (0)
; #define PG8_WAIT_V(n) asm volatile("s_waitcnt vmcnt(" #n ")" ::: "memory")
; #define PG8_WAIT_L(n) asm volatile("s_waitcnt lgkmcnt(" #n ")" ::: "memory")
; #define PG8_BAR __builtin_amdgcn_s_barrier()
; #define PG8_SCHED __builtin_amdgcn_sched_barrier(0)
; template <class Epi, class Sched, bool ALIGN_EPI = false, bool SP2 = false>
; __device__ __forceinline__ void gemm_phase(PG8_LAS unsigned char* lds, const Gemm g, const Sched& S, const Epi& E, const int wave0) {
;     ...
;             PG8_LDB(B0, 1, 0); PG8_LDB(B1, 1, 1); PG8_SCHED; PG8_LDA(At, 1, 0); PG8_STAGE(PG8_SA(0, 1), a2 + hstepA, voffA);
;             PG8_WAIT_V(8); PG8_WAIT_L(0); PG8_BAR; PG8_MMA(0, 0, At, B0); PG8_MMA(0, 1, At, B1); PG8_BAR; PG8_SCHED;
;             PG8_LDA(At, 1, 1); PG8_STAGE(PG8_SB(1, 0), b3, voffB); PG8_STAGE(PG8_SB(1, 1), b3 + hstepB, voffB); PG8_STAGE(PG8_SA(1, 0), a3, voffA);
;             PG8_WAIT_V(8); PG8_WAIT_L(0); PG8_BAR; PG8_MMA(1, 0, At, B0); PG8_MMA(1, 1, At, B1); PG8_BAR; PG8_SCHED;
;     ...
;         if constexpr (ALIGN_EPI) { if (wr == 0) PG8_BAR; }
	s_add_i32 s43, 0, 0x18000
	s_add_i32 s44, 0, 0x1c000
	ds_read_b128 v[144:147], v254
	ds_read_b128 v[148:151], v254 offset:1024
	ds_read_b128 v[152:155], v254 offset:2048
	ds_read_b128 v[156:159], v254 offset:3072
	ds_read_b128 v[178:181], v255
	ds_read_b128 v[182:185], v255 offset:1024
	ds_read_b128 v[186:189], v255 offset:2048
	ds_read_b128 v[190:193], v255 offset:3072
	s_add_u32 s18, s18, 0x200000
	s_addc_u32 s19, s19, 0
	s_mov_b32 m0, s26
	ds_read_b128 v[194:197], v143 offset:32768
	ds_read_b128 v[208:211], v143 offset:33792
	ds_read_b128 v[212:215], v143 offset:34816
	ds_read_b128 v[216:219], v143 offset:35840
	ds_read_b128 v[220:223], v143 offset:36864
	ds_read_b128 v[224:227], v143 offset:37888
	ds_read_b128 v[228:231], v143 offset:38912
	ds_read_b128 v[232:235], v143 offset:39936
	global_load_lds_dwordx4 v134, s[18:19]
	s_mov_b32 m0, s27
	s_nop 0
	global_load_lds_dwordx4 v132, s[18:19]
	s_waitcnt vmcnt(8)
	s_waitcnt lgkmcnt(0)
	s_barrier
	s_setprio 1
	s_waitcnt lgkmcnt(0)
	v_mfma_f32_16x16x32_bf16 v[126:129], v[144:147], v[194:197], v[126:129]
	v_mfma_f32_16x16x32_bf16 v[122:125], v[152:155], v[194:197], v[122:125]
	v_mfma_f32_16x16x32_bf16 v[118:121], v[144:147], v[212:215], v[118:121]
	v_mfma_f32_16x16x32_bf16 v[114:117], v[152:155], v[212:215], v[114:117]
	v_mfma_f32_16x16x32_bf16 v[102:105], v[144:147], v[220:223], v[102:105]
	v_mfma_f32_16x16x32_bf16 v[98:101], v[152:155], v[220:223], v[98:101]
	v_mfma_f32_16x16x32_bf16 v[86:89], v[144:147], v[228:231], v[86:89]
	v_mfma_f32_16x16x32_bf16 v[82:85], v[152:155], v[228:231], v[82:85]
	s_setprio 0
	s_setprio 1
	v_mfma_f32_16x16x32_bf16 v[126:129], v[148:151], v[208:211], v[126:129]
	v_mfma_f32_16x16x32_bf16 v[122:125], v[156:159], v[208:211], v[122:125]
	v_mfma_f32_16x16x32_bf16 v[118:121], v[148:151], v[216:219], v[118:121]
	v_mfma_f32_16x16x32_bf16 v[114:117], v[156:159], v[216:219], v[114:117]
	v_mfma_f32_16x16x32_bf16 v[102:105], v[148:151], v[224:227], v[102:105]
	v_mfma_f32_16x16x32_bf16 v[98:101], v[156:159], v[224:227], v[98:101]
	v_mfma_f32_16x16x32_bf16 v[86:89], v[148:151], v[232:235], v[86:89]
	v_mfma_f32_16x16x32_bf16 v[82:85], v[156:159], v[232:235], v[82:85]
	s_setprio 0
	s_setprio 1
	v_mfma_f32_16x16x32_bf16 v[110:113], v[178:181], v[194:197], v[110:113]
	v_mfma_f32_16x16x32_bf16 v[106:109], v[186:189], v[194:197], v[106:109]
	v_mfma_f32_16x16x32_bf16 v[94:97], v[178:181], v[212:215], v[94:97]
	v_mfma_f32_16x16x32_bf16 v[90:93], v[186:189], v[212:215], v[90:93]
	v_mfma_f32_16x16x32_bf16 v[78:81], v[178:181], v[220:223], v[78:81]
	v_mfma_f32_16x16x32_bf16 v[74:77], v[186:189], v[220:223], v[74:77]
	v_mfma_f32_16x16x32_bf16 v[70:73], v[178:181], v[228:231], v[70:73]
	v_mfma_f32_16x16x32_bf16 v[66:69], v[186:189], v[228:231], v[66:69]
	s_setprio 0
	s_setprio 1
	v_mfma_f32_16x16x32_bf16 v[110:113], v[182:185], v[208:211], v[110:113]
	v_mfma_f32_16x16x32_bf16 v[106:109], v[190:193], v[208:211], v[106:109]
	v_mfma_f32_16x16x32_bf16 v[94:97], v[182:185], v[216:219], v[94:97]
	v_mfma_f32_16x16x32_bf16 v[90:93], v[190:193], v[216:219], v[90:93]
	v_mfma_f32_16x16x32_bf16 v[78:81], v[182:185], v[224:227], v[78:81]
	v_mfma_f32_16x16x32_bf16 v[74:77], v[190:193], v[224:227], v[74:77]
	v_mfma_f32_16x16x32_bf16 v[70:73], v[182:185], v[232:235], v[70:73]
	v_mfma_f32_16x16x32_bf16 v[66:69], v[190:193], v[232:235], v[66:69]
	s_setprio 0
	s_barrier
	s_add_i32 s18, s43, s20
	s_add_u32 s48, s16, 0x80
	s_addc_u32 s49, s17, 0
	s_mov_b32 m0, s18
	ds_read_b128 v[194:197], v143 offset:49152
	ds_read_b128 v[208:211], v143 offset:50176
	ds_read_b128 v[212:215], v143 offset:51200
	ds_read_b128 v[216:219], v143 offset:52224
	ds_read_b128 v[220:223], v143 offset:53248
	ds_read_b128 v[224:227], v143 offset:54272
	ds_read_b128 v[228:231], v143 offset:55296
	ds_read_b128 v[232:235], v143 offset:56320
	global_load_lds_dwordx4 v64, s[48:49]
	s_add_i32 m0, s18, 0x2000
	s_add_u32 s16, s16, 0x200080
	s_addc_u32 s17, s17, 0
	s_add_i32 s18, s44, s20
	global_load_lds_dwordx4 v130, s[48:49]
	s_mov_b32 m0, s18
	s_nop 0
	global_load_lds_dwordx4 v64, s[16:17]
	s_add_i32 m0, s18, 0x2000
	s_nop 0
	global_load_lds_dwordx4 v130, s[16:17]
	s_add_u32 s100, s100, 0x80
	s_addc_u32 s101, s101, 0
	s_mov_b32 m0, s28
	s_nop 0
	global_load_lds_dwordx4 v134, s[100:101]
	s_mov_b32 m0, s29
	s_nop 0
	global_load_lds_dwordx4 v132, s[100:101]
	s_waitcnt vmcnt(8)
	s_waitcnt lgkmcnt(0)
	s_barrier
	s_setprio 1
	s_waitcnt lgkmcnt(0)
	v_mfma_f32_16x16x32_bf16 v[60:63], v[144:147], v[194:197], v[60:63]
	v_mfma_f32_16x16x32_bf16 v[56:59], v[152:155], v[194:197], v[56:59]
	v_mfma_f32_16x16x32_bf16 v[52:55], v[144:147], v[212:215], v[52:55]
	v_mfma_f32_16x16x32_bf16 v[48:51], v[152:155], v[212:215], v[48:51]
	v_mfma_f32_16x16x32_bf16 v[36:39], v[144:147], v[220:223], v[36:39]
	v_mfma_f32_16x16x32_bf16 v[32:35], v[152:155], v[220:223], v[32:35]
	v_mfma_f32_16x16x32_bf16 v[20:23], v[144:147], v[228:231], v[20:23]
	v_mfma_f32_16x16x32_bf16 v[16:19], v[152:155], v[228:231], v[16:19]
	s_setprio 0
	s_setprio 1
	v_mfma_f32_16x16x32_bf16 v[60:63], v[148:151], v[208:211], v[60:63]
	v_mfma_f32_16x16x32_bf16 v[56:59], v[156:159], v[208:211], v[56:59]
	v_mfma_f32_16x16x32_bf16 v[52:55], v[148:151], v[216:219], v[52:55]
	v_mfma_f32_16x16x32_bf16 v[48:51], v[156:159], v[216:219], v[48:51]
	v_mfma_f32_16x16x32_bf16 v[36:39], v[148:151], v[224:227], v[36:39]
	v_mfma_f32_16x16x32_bf16 v[32:35], v[156:159], v[224:227], v[32:35]
	v_mfma_f32_16x16x32_bf16 v[20:23], v[148:151], v[232:235], v[20:23]
	v_mfma_f32_16x16x32_bf16 v[16:19], v[156:159], v[232:235], v[16:19]
	s_setprio 0
	s_setprio 1
	v_mfma_f32_16x16x32_bf16 v[44:47], v[178:181], v[194:197], v[44:47]
	v_mfma_f32_16x16x32_bf16 v[40:43], v[186:189], v[194:197], v[40:43]
	v_mfma_f32_16x16x32_bf16 v[28:31], v[178:181], v[212:215], v[28:31]
	v_mfma_f32_16x16x32_bf16 v[24:27], v[186:189], v[212:215], v[24:27]
	v_mfma_f32_16x16x32_bf16 v[12:15], v[178:181], v[220:223], v[12:15]
	v_mfma_f32_16x16x32_bf16 v[8:11], v[186:189], v[220:223], v[8:11]
	v_mfma_f32_16x16x32_bf16 v[4:7], v[178:181], v[228:231], v[4:7]
	v_mfma_f32_16x16x32_bf16 v[0:3], v[186:189], v[228:231], v[0:3]
	s_setprio 0
	s_setprio 1
	v_mfma_f32_16x16x32_bf16 v[44:47], v[182:185], v[208:211], v[44:47]
	v_mfma_f32_16x16x32_bf16 v[40:43], v[190:193], v[208:211], v[40:43]
	v_mfma_f32_16x16x32_bf16 v[28:31], v[182:185], v[216:219], v[28:31]
	v_mfma_f32_16x16x32_bf16 v[24:27], v[190:193], v[216:219], v[24:27]
	v_mfma_f32_16x16x32_bf16 v[12:15], v[182:185], v[224:227], v[12:15]
	v_mfma_f32_16x16x32_bf16 v[8:11], v[190:193], v[224:227], v[8:11]
	v_mfma_f32_16x16x32_bf16 v[4:7], v[182:185], v[232:235], v[4:7]
	v_mfma_f32_16x16x32_bf16 v[0:3], v[190:193], v[232:235], v[0:3]
	s_setprio 0
	s_barrier
	s_add_i32 s42, s42, 2
	s_add_u32 s0, s0, 0x100
	s_addc_u32 s1, s1, 0
	s_add_u32 s36, s36, 0x100
	s_addc_u32 s37, s37, 0
	s_cmpk_gt_u32 s42, 0x7d
	s_cbranch_scc0 .LBB0_1685
	s_mov_b64 s[48:49], 0x80
	s_and_b64 vcc, exec, s[6:7]
	s_mov_b64 s[34:35], 0x45000
	s_cbranch_vccz .LBB0_1688
	s_barrier

; #define PG8_STAGE(bufoff, gbase, voff) do { _Pragma("unroll") for (int _i = 0; _i < 2; ++_i) \
;         __builtin_amdgcn_global_load_lds((const unsigned*)((const char*)(gbase) + (voff)[_i]), (PG8_LAS unsigned*)(lds + (bufoff) + ldsw + _i * 8192), 16, 0, 0); } while (0)
; #define PG8_LDA(dst, b, h) do { _Pragma("unroll") for (int m = 0; m < 4; ++m) _Pragma("unroll") for (int k = 0; k < 2; ++k) dst[m][k] = *(const PG8_LAS bf16x8*)(lds + PG8_SA(b, h) + aoff + m * 2048 + k * 1024); } while (0)
; #define PG8_LDB(dst, b, h) do { _Pragma("unroll") for (int n = 0; n < 2; ++n) _Pragma("unroll") for (int k = 0; k < 2; ++k) dst[n][k] = *(const PG8_LAS bf16x8*)(lds + PG8_SB(b, h) + boff + n * 2048 + k * 1024); } while (0)
; #define PG8_MMA(ai, bj, At, Bt) do { __builtin_amdgcn_s_setprio(1); _Pragma("unroll") for (int m = 0; m < 4; ++m) _Pragma("unroll") for (int n = 0; n < 2; ++n) _Pragma("unroll") for (int k = 0; k < 2; ++k) \
;         acc[ai][bj][m][n] = __builtin_amdgcn_mfma_f32_16x16x32_bf16(Bt[n][k], At[m][k], acc[ai][bj][m][n], 0, 0, 0); __builtin_amdgcn_s_setprio(0); } while (0)
; #define PG8_WAIT_V(n) asm volatile("s_waitcnt vmcnt(" #n ")" ::: "memory")
; #define PG8_BAR __builtin_amdgcn_s_barrier()
; template <class Epi, class Sched, bool ALIGN_EPI = false, bool SP2 = false>
; __device__ __forceinline__ void gemm_phase(PG8_LAS unsigned char* lds, const Gemm g, const Sched& S, const Epi& E, const int wave0) {
;     ...
;         for (int t = 0; t < nt; t += 2) {
;             const bool last = (t == nt - 2);
;             const char* a1 = cA + (size_t)(t + 1) * kstep;
;             const char* a2 = last ? nA : cA + (size_t)(t + 2) * kstep; const char* b2 = last ? nB : cB + (size_t)(t + 2) * kstep;
;             const char* a3 = a2 + kstep; const char* b3 = b2 + kstep;
;             if (last && has_next) S.a_ready(nxt);
;             if constexpr (SP2) {
;             PG8_LDB(B0, 0, 0); PG8_LDB(B1, 0, 1); PG8_SCHED; PG8_LDA(At, 0, 0); PG8_STAGE(PG8_SA(1, 1), a1 + hstepA, voffA);
;             PG8_WAIT_V(8); PG8_WAIT_L(0); PG8_BAR; PG8_MMA(0, 0, At, B0); PG8_MMA(0, 1, At, B1); PG8_BAR; PG8_SCHED;
;             PG8_LDA(At, 0, 1); PG8_STAGE(PG8_SB(0, 0), b2, voffB); PG8_STAGE(PG8_SB(0, 1), b2 + hstepB, voffB); PG8_STAGE(PG8_SA(0, 0), a2, voffA);
;             PG8_WAIT_V(8); PG8_WAIT_L(0); PG8_BAR; PG8_MMA(1, 0, At, B0); PG8_MMA(1, 1, At, B1); PG8_BAR; PG8_SCHED;
.LBB0_1702:
	s_add_u32 s18, s16, 0xffe00080
	s_addc_u32 s19, s17, -1
	s_add_i32 s44, 0, 0x10000
	s_cmp_eq_u32 s43, 12
	s_cselect_b32 s21, s9, s19
	s_cselect_b32 s20, s11, s18
	s_cselect_b32 s19, s13, s42
	s_cselect_b32 s18, s38, s39
	s_add_i32 s46, 0, 0x14000
	ds_read_b128 v[144:147], v252
	ds_read_b128 v[148:151], v252 offset:1024
	ds_read_b128 v[152:155], v252 offset:2048
	ds_read_b128 v[156:159], v252 offset:3072
	ds_read_b128 v[178:181], v253
	ds_read_b128 v[182:185], v253 offset:1024
	ds_read_b128 v[186:189], v253 offset:2048
	ds_read_b128 v[190:193], v253 offset:3072
	s_add_i32 m0, s28, 0xc000
	ds_read_b128 v[194:197], v143
	ds_read_b128 v[208:211], v143 offset:1024
	ds_read_b128 v[212:215], v143 offset:2048
	ds_read_b128 v[216:219], v143 offset:3072
	ds_read_b128 v[220:223], v143 offset:4096
	ds_read_b128 v[224:227], v143 offset:5120
	ds_read_b128 v[228:231], v143 offset:6144
	ds_read_b128 v[232:235], v143 offset:7168
	global_load_lds_dwordx4 v136, s[16:17]
	s_add_i32 m0, s28, 0xe000
	s_nop 0
	global_load_lds_dwordx4 v138, s[16:17]
	s_waitcnt vmcnt(8)
	s_waitcnt lgkmcnt(0)
	s_barrier
	s_setprio 1
	s_waitcnt lgkmcnt(0)
	v_mfma_f32_16x16x32_bf16 v[126:129], v[144:147], v[194:197], v[126:129]
	v_mfma_f32_16x16x32_bf16 v[122:125], v[152:155], v[194:197], v[122:125]
	v_mfma_f32_16x16x32_bf16 v[118:121], v[144:147], v[212:215], v[118:121]
	v_mfma_f32_16x16x32_bf16 v[114:117], v[152:155], v[212:215], v[114:117]
	v_mfma_f32_16x16x32_bf16 v[102:105], v[144:147], v[220:223], v[102:105]
	v_mfma_f32_16x16x32_bf16 v[98:101], v[152:155], v[220:223], v[98:101]
	v_mfma_f32_16x16x32_bf16 v[86:89], v[144:147], v[228:231], v[86:89]
	v_mfma_f32_16x16x32_bf16 v[82:85], v[152:155], v[228:231], v[82:85]
	s_setprio 0
	s_setprio 1
	v_mfma_f32_16x16x32_bf16 v[126:129], v[148:151], v[208:211], v[126:129]
	v_mfma_f32_16x16x32_bf16 v[122:125], v[156:159], v[208:211], v[122:125]
	v_mfma_f32_16x16x32_bf16 v[118:121], v[148:151], v[216:219], v[118:121]
	v_mfma_f32_16x16x32_bf16 v[114:117], v[156:159], v[216:219], v[114:117]
	v_mfma_f32_16x16x32_bf16 v[102:105], v[148:151], v[224:227], v[102:105]
	v_mfma_f32_16x16x32_bf16 v[98:101], v[156:159], v[224:227], v[98:101]
	v_mfma_f32_16x16x32_bf16 v[86:89], v[148:151], v[232:235], v[86:89]
	v_mfma_f32_16x16x32_bf16 v[82:85], v[156:159], v[232:235], v[82:85]
	s_setprio 0
	s_setprio 1
	v_mfma_f32_16x16x32_bf16 v[110:113], v[178:181], v[194:197], v[110:113]
	v_mfma_f32_16x16x32_bf16 v[106:109], v[186:189], v[194:197], v[106:109]
	v_mfma_f32_16x16x32_bf16 v[94:97], v[178:181], v[212:215], v[94:97]
	v_mfma_f32_16x16x32_bf16 v[90:93], v[186:189], v[212:215], v[90:93]
	v_mfma_f32_16x16x32_bf16 v[78:81], v[178:181], v[220:223], v[78:81]
	v_mfma_f32_16x16x32_bf16 v[74:77], v[186:189], v[220:223], v[74:77]
	v_mfma_f32_16x16x32_bf16 v[70:73], v[178:181], v[228:231], v[70:73]
	v_mfma_f32_16x16x32_bf16 v[66:69], v[186:189], v[228:231], v[66:69]
	s_setprio 0
	s_setprio 1
	v_mfma_f32_16x16x32_bf16 v[110:113], v[182:185], v[208:211], v[110:113]
	v_mfma_f32_16x16x32_bf16 v[106:109], v[190:193], v[208:211], v[106:109]
	v_mfma_f32_16x16x32_bf16 v[94:97], v[182:185], v[216:219], v[94:97]
	v_mfma_f32_16x16x32_bf16 v[90:93], v[190:193], v[216:219], v[90:93]
	v_mfma_f32_16x16x32_bf16 v[78:81], v[182:185], v[224:227], v[78:81]
	v_mfma_f32_16x16x32_bf16 v[74:77], v[190:193], v[224:227], v[74:77]
	v_mfma_f32_16x16x32_bf16 v[70:73], v[182:185], v[232:235], v[70:73]
	v_mfma_f32_16x16x32_bf16 v[66:69], v[190:193], v[232:235], v[66:69]
	s_setprio 0
	s_barrier
	s_add_i32 s44, s44, s25
	s_mov_b32 m0, s44
	ds_read_b128 v[194:197], v143 offset:16384
	ds_read_b128 v[208:211], v143 offset:17408
	ds_read_b128 v[212:215], v143 offset:18432
	ds_read_b128 v[216:219], v143 offset:19456
	ds_read_b128 v[220:223], v143 offset:20480
	ds_read_b128 v[224:227], v143 offset:21504
	ds_read_b128 v[228:231], v143 offset:22528
	ds_read_b128 v[232:235], v143 offset:23552
	global_load_lds_dwordx4 v64, s[18:19]
	s_add_i32 m0, s44, 0x2000
	s_add_u32 s44, s18, 0x200000
	s_addc_u32 s45, s19, 0
	s_add_i32 s46, s46, s25
	global_load_lds_dwordx4 v130, s[18:19]
	s_mov_b32 m0, s46
	s_mov_b64 s[100:101], s[20:21]
	global_load_lds_dwordx4 v64, s[44:45]
	s_add_i32 m0, s46, 0x2000
	s_nop 0
	global_load_lds_dwordx4 v130, s[44:45]
	s_mov_b32 m0, s28
	s_nop 0
	global_load_lds_dwordx4 v134, s[20:21]
	s_mov_b32 m0, s29
	s_nop 0
	global_load_lds_dwordx4 v132, s[20:21]
	s_waitcnt vmcnt(8)
	s_waitcnt lgkmcnt(0)
	s_barrier
	s_setprio 1
	s_waitcnt lgkmcnt(0)
	v_mfma_f32_16x16x32_bf16 v[60:63], v[144:147], v[194:197], v[60:63]
	v_mfma_f32_16x16x32_bf16 v[56:59], v[152:155], v[194:197], v[56:59]
	v_mfma_f32_16x16x32_bf16 v[52:55], v[144:147], v[212:215], v[52:55]
	v_mfma_f32_16x16x32_bf16 v[48:51], v[152:155], v[212:215], v[48:51]
	v_mfma_f32_16x16x32_bf16 v[36:39], v[144:147], v[220:223], v[36:39]
	v_mfma_f32_16x16x32_bf16 v[32:35], v[152:155], v[220:223], v[32:35]
	v_mfma_f32_16x16x32_bf16 v[20:23], v[144:147], v[228:231], v[20:23]
	v_mfma_f32_16x16x32_bf16 v[16:19], v[152:155], v[228:231], v[16:19]
	s_setprio 0
	s_setprio 1
	v_mfma_f32_16x16x32_bf16 v[60:63], v[148:151], v[208:211], v[60:63]
	v_mfma_f32_16x16x32_bf16 v[56:59], v[156:159], v[208:211], v[56:59]
	v_mfma_f32_16x16x32_bf16 v[52:55], v[148:151], v[216:219], v[52:55]
	v_mfma_f32_16x16x32_bf16 v[48:51], v[156:159], v[216:219], v[48:51]
	v_mfma_f32_16x16x32_bf16 v[36:39], v[148:151], v[224:227], v[36:39]
	v_mfma_f32_16x16x32_bf16 v[32:35], v[156:159], v[224:227], v[32:35]
	v_mfma_f32_16x16x32_bf16 v[20:23], v[148:151], v[232:235], v[20:23]
	v_mfma_f32_16x16x32_bf16 v[16:19], v[156:159], v[232:235], v[16:19]
	s_setprio 0
	s_setprio 1
	v_mfma_f32_16x16x32_bf16 v[44:47], v[178:181], v[194:197], v[44:47]
	v_mfma_f32_16x16x32_bf16 v[40:43], v[186:189], v[194:197], v[40:43]
	v_mfma_f32_16x16x32_bf16 v[28:31], v[178:181], v[212:215], v[28:31]
	v_mfma_f32_16x16x32_bf16 v[24:27], v[186:189], v[212:215], v[24:27]
	v_mfma_f32_16x16x32_bf16 v[12:15], v[178:181], v[220:223], v[12:15]
	v_mfma_f32_16x16x32_bf16 v[8:11], v[186:189], v[220:223], v[8:11]
	v_mfma_f32_16x16x32_bf16 v[4:7], v[178:181], v[228:231], v[4:7]
	v_mfma_f32_16x16x32_bf16 v[0:3], v[186:189], v[228:231], v[0:3]
	s_setprio 0
	s_setprio 1
	v_mfma_f32_16x16x32_bf16 v[44:47], v[182:185], v[208:211], v[44:47]
	v_mfma_f32_16x16x32_bf16 v[40:43], v[190:193], v[208:211], v[40:43]
	v_mfma_f32_16x16x32_bf16 v[28:31], v[182:185], v[216:219], v[28:31]
	v_mfma_f32_16x16x32_bf16 v[24:27], v[190:193], v[216:219], v[24:27]
	v_mfma_f32_16x16x32_bf16 v[12:15], v[182:185], v[224:227], v[12:15]
	v_mfma_f32_16x16x32_bf16 v[8:11], v[190:193], v[224:227], v[8:11]
	v_mfma_f32_16x16x32_bf16 v[4:7], v[182:185], v[232:235], v[4:7]
	v_mfma_f32_16x16x32_bf16 v[0:3], v[190:193], v[232:235], v[0:3]
	s_setprio 0
	s_barrier
; #define PG8_STAGE(bufoff, gbase, voff) do { _Pragma("unroll") for (int _i = 0; _i < 2; ++_i) \
;         __builtin_amdgcn_global_load_lds((const unsigned*)((const char*)(gbase) + (voff)[_i]), (PG8_LAS unsigned*)(lds + (bufoff) + ldsw + _i * 8192), 16, 0, 0); } while (0)
; #define PG8_LDA(dst, b, h) do { _Pragma("unroll") for (int m = 0; m < 4; ++m) _Pragma("unroll") for (int k = 0; k < 2; ++k) dst[m][k] = *(const PG8_LAS bf16x8*)(lds + PG8_SA(b, h) + aoff + m * 2048 + k * 1024); } while (0)
; #define PG8_LDB(dst, b, h) do { _Pragma("unroll") for (int n = 0; n < 2; ++n) _Pragma("unroll") for (int k = 0; k < 2; ++k) dst[n][k] = *(const PG8_LAS bf16x8*)(lds + PG8_SB(b, h) + boff + n * 2048 + k * 1024); } while (0)
; #define PG8_MMA(ai, bj, At, Bt) do { __builtin_amdgcn_s_setprio(1); _Pragma("unroll") for (int m = 0; m < 4; ++m) _Pragma("unroll") for (int n = 0; n < 2; ++n) _Pragma("unroll") for (int k = 0; k < 2; ++k) \
;         acc[ai][bj][m][n] = __builtin_amdgcn_mfma_f32_16x16x32_bf16(Bt[n][k], At[m][k], acc[ai][bj][m][n], 0, 0, 0); __builtin_amdgcn_s_setprio(0); } while (0)
; #define PG8_WAIT_V(n) asm volatile("s_waitcnt vmcnt(" #n ")" ::: "memory")
; #define PG8_WAIT_L(n) asm volatile("s_waitcnt lgkmcnt(" #n ")" ::: "memory")
; #define PG8_BAR __builtin_amdgcn_s_barrier()
; #define PG8_SCHED __builtin_amdgcn_sched_barrier(0)
; template <class Epi, class Sched, bool ALIGN_EPI = false, bool SP2 = false>
; __device__ __forceinline__ void gemm_phase(PG8_LAS unsigned char* lds, const Gemm g, const Sched& S, const Epi& E, const int wave0) {
;     ...
;             PG8_LDB(B0, 1, 0); PG8_LDB(B1, 1, 1); PG8_SCHED; PG8_LDA(At, 1, 0); PG8_STAGE(PG8_SA(0, 1), a2 + hstepA, voffA);
;             PG8_WAIT_V(8); PG8_WAIT_L(0); PG8_BAR; PG8_MMA(0, 0, At, B0); PG8_MMA(0, 1, At, B1); PG8_BAR; PG8_SCHED;
;             PG8_LDA(At, 1, 1); PG8_STAGE(PG8_SB(1, 0), b3, voffB); PG8_STAGE(PG8_SB(1, 1), b3 + hstepB, voffB); PG8_STAGE(PG8_SA(1, 0), a3, voffA);
;             PG8_WAIT_V(8); PG8_WAIT_L(0); PG8_BAR; PG8_MMA(1, 0, At, B0); PG8_MMA(1, 1, At, B1); PG8_BAR; PG8_SCHED;
;     ...
;         if constexpr (ALIGN_EPI) { if (wr == 0) PG8_BAR; }
	s_add_i32 s44, 0, 0x18000
	s_add_i32 s45, 0, 0x1c000
	ds_read_b128 v[144:147], v254
	ds_read_b128 v[148:151], v254 offset:1024
	ds_read_b128 v[152:155], v254 offset:2048
	ds_read_b128 v[156:159], v254 offset:3072
	ds_read_b128 v[178:181], v255
	ds_read_b128 v[182:185], v255 offset:1024
	ds_read_b128 v[186:189], v255 offset:2048
	ds_read_b128 v[190:193], v255 offset:3072
	s_add_u32 s20, s20, 0x200000
	s_addc_u32 s21, s21, 0
	s_mov_b32 m0, s30
	ds_read_b128 v[194:197], v143 offset:32768
	ds_read_b128 v[208:211], v143 offset:33792
	ds_read_b128 v[212:215], v143 offset:34816
	ds_read_b128 v[216:219], v143 offset:35840
	ds_read_b128 v[220:223], v143 offset:36864
	ds_read_b128 v[224:227], v143 offset:37888
	ds_read_b128 v[228:231], v143 offset:38912
	ds_read_b128 v[232:235], v143 offset:39936
	global_load_lds_dwordx4 v134, s[20:21]
	s_mov_b32 m0, s31
	s_nop 0
	global_load_lds_dwordx4 v132, s[20:21]
	s_waitcnt vmcnt(8)
	s_waitcnt lgkmcnt(0)
	s_barrier
	s_setprio 1
	s_waitcnt lgkmcnt(0)
	v_mfma_f32_16x16x32_bf16 v[126:129], v[144:147], v[194:197], v[126:129]
	v_mfma_f32_16x16x32_bf16 v[122:125], v[152:155], v[194:197], v[122:125]
	v_mfma_f32_16x16x32_bf16 v[118:121], v[144:147], v[212:215], v[118:121]
	v_mfma_f32_16x16x32_bf16 v[114:117], v[152:155], v[212:215], v[114:117]
	v_mfma_f32_16x16x32_bf16 v[102:105], v[144:147], v[220:223], v[102:105]
	v_mfma_f32_16x16x32_bf16 v[98:101], v[152:155], v[220:223], v[98:101]
	v_mfma_f32_16x16x32_bf16 v[86:89], v[144:147], v[228:231], v[86:89]
	v_mfma_f32_16x16x32_bf16 v[82:85], v[152:155], v[228:231], v[82:85]
	s_setprio 0
	s_setprio 1
	v_mfma_f32_16x16x32_bf16 v[126:129], v[148:151], v[208:211], v[126:129]
	v_mfma_f32_16x16x32_bf16 v[122:125], v[156:159], v[208:211], v[122:125]
	v_mfma_f32_16x16x32_bf16 v[118:121], v[148:151], v[216:219], v[118:121]
	v_mfma_f32_16x16x32_bf16 v[114:117], v[156:159], v[216:219], v[114:117]
	v_mfma_f32_16x16x32_bf16 v[102:105], v[148:151], v[224:227], v[102:105]
	v_mfma_f32_16x16x32_bf16 v[98:101], v[156:159], v[224:227], v[98:101]
	v_mfma_f32_16x16x32_bf16 v[86:89], v[148:151], v[232:235], v[86:89]
	v_mfma_f32_16x16x32_bf16 v[82:85], v[156:159], v[232:235], v[82:85]
	s_setprio 0
	s_setprio 1
	v_mfma_f32_16x16x32_bf16 v[110:113], v[178:181], v[194:197], v[110:113]
	v_mfma_f32_16x16x32_bf16 v[106:109], v[186:189], v[194:197], v[106:109]
	v_mfma_f32_16x16x32_bf16 v[94:97], v[178:181], v[212:215], v[94:97]
	v_mfma_f32_16x16x32_bf16 v[90:93], v[186:189], v[212:215], v[90:93]
	v_mfma_f32_16x16x32_bf16 v[78:81], v[178:181], v[220:223], v[78:81]
	v_mfma_f32_16x16x32_bf16 v[74:77], v[186:189], v[220:223], v[74:77]
	v_mfma_f32_16x16x32_bf16 v[70:73], v[178:181], v[228:231], v[70:73]
	v_mfma_f32_16x16x32_bf16 v[66:69], v[186:189], v[228:231], v[66:69]
	s_setprio 0
	s_setprio 1
	v_mfma_f32_16x16x32_bf16 v[110:113], v[182:185], v[208:211], v[110:113]
	v_mfma_f32_16x16x32_bf16 v[106:109], v[190:193], v[208:211], v[106:109]
	v_mfma_f32_16x16x32_bf16 v[94:97], v[182:185], v[216:219], v[94:97]
	v_mfma_f32_16x16x32_bf16 v[90:93], v[190:193], v[216:219], v[90:93]
	v_mfma_f32_16x16x32_bf16 v[78:81], v[182:185], v[224:227], v[78:81]
	v_mfma_f32_16x16x32_bf16 v[74:77], v[190:193], v[224:227], v[74:77]
	v_mfma_f32_16x16x32_bf16 v[70:73], v[182:185], v[232:235], v[70:73]
	v_mfma_f32_16x16x32_bf16 v[66:69], v[190:193], v[232:235], v[66:69]
	s_setprio 0
	s_barrier
	s_add_i32 s20, s44, s25
	s_add_u32 s48, s18, 0x80
	s_addc_u32 s49, s19, 0
	s_mov_b32 m0, s20
	ds_read_b128 v[194:197], v143 offset:49152
	ds_read_b128 v[208:211], v143 offset:50176
	ds_read_b128 v[212:215], v143 offset:51200
	ds_read_b128 v[216:219], v143 offset:52224
	ds_read_b128 v[220:223], v143 offset:53248
	ds_read_b128 v[224:227], v143 offset:54272
	ds_read_b128 v[228:231], v143 offset:55296
	ds_read_b128 v[232:235], v143 offset:56320
	global_load_lds_dwordx4 v64, s[48:49]
	s_add_i32 m0, s20, 0x2000
	s_add_u32 s18, s18, 0x200080
	s_addc_u32 s19, s19, 0
	s_add_i32 s20, s45, s25
	global_load_lds_dwordx4 v130, s[48:49]
	s_mov_b32 m0, s20
	s_nop 0
	global_load_lds_dwordx4 v64, s[18:19]
	s_add_i32 m0, s20, 0x2000
	s_nop 0
	global_load_lds_dwordx4 v130, s[18:19]
	s_add_u32 s100, s100, 0x80
	s_addc_u32 s101, s101, 0
	s_mov_b32 m0, s33
	s_nop 0
	global_load_lds_dwordx4 v134, s[100:101]
	s_mov_b32 m0, s34
	s_nop 0
	global_load_lds_dwordx4 v132, s[100:101]
	s_waitcnt vmcnt(8)
	s_waitcnt lgkmcnt(0)
	s_barrier
	s_setprio 1
	s_waitcnt lgkmcnt(0)
	v_mfma_f32_16x16x32_bf16 v[60:63], v[144:147], v[194:197], v[60:63]
	v_mfma_f32_16x16x32_bf16 v[56:59], v[152:155], v[194:197], v[56:59]
	v_mfma_f32_16x16x32_bf16 v[52:55], v[144:147], v[212:215], v[52:55]
	v_mfma_f32_16x16x32_bf16 v[48:51], v[152:155], v[212:215], v[48:51]
	v_mfma_f32_16x16x32_bf16 v[36:39], v[144:147], v[220:223], v[36:39]
	v_mfma_f32_16x16x32_bf16 v[32:35], v[152:155], v[220:223], v[32:35]
	v_mfma_f32_16x16x32_bf16 v[20:23], v[144:147], v[228:231], v[20:23]
	v_mfma_f32_16x16x32_bf16 v[16:19], v[152:155], v[228:231], v[16:19]
	s_setprio 0
	s_setprio 1
	v_mfma_f32_16x16x32_bf16 v[60:63], v[148:151], v[208:211], v[60:63]
	v_mfma_f32_16x16x32_bf16 v[56:59], v[156:159], v[208:211], v[56:59]
	v_mfma_f32_16x16x32_bf16 v[52:55], v[148:151], v[216:219], v[52:55]
	v_mfma_f32_16x16x32_bf16 v[48:51], v[156:159], v[216:219], v[48:51]
	v_mfma_f32_16x16x32_bf16 v[36:39], v[148:151], v[224:227], v[36:39]
	v_mfma_f32_16x16x32_bf16 v[32:35], v[156:159], v[224:227], v[32:35]
	v_mfma_f32_16x16x32_bf16 v[20:23], v[148:151], v[232:235], v[20:23]
	v_mfma_f32_16x16x32_bf16 v[16:19], v[156:159], v[232:235], v[16:19]
	s_setprio 0
	s_setprio 1
	v_mfma_f32_16x16x32_bf16 v[44:47], v[178:181], v[194:197], v[44:47]
	v_mfma_f32_16x16x32_bf16 v[40:43], v[186:189], v[194:197], v[40:43]
	v_mfma_f32_16x16x32_bf16 v[28:31], v[178:181], v[212:215], v[28:31]
	v_mfma_f32_16x16x32_bf16 v[24:27], v[186:189], v[212:215], v[24:27]
	v_mfma_f32_16x16x32_bf16 v[12:15], v[178:181], v[220:223], v[12:15]
	v_mfma_f32_16x16x32_bf16 v[8:11], v[186:189], v[220:223], v[8:11]
	v_mfma_f32_16x16x32_bf16 v[4:7], v[178:181], v[228:231], v[4:7]
	v_mfma_f32_16x16x32_bf16 v[0:3], v[186:189], v[228:231], v[0:3]
	s_setprio 0
	s_setprio 1
	v_mfma_f32_16x16x32_bf16 v[44:47], v[182:185], v[208:211], v[44:47]
	v_mfma_f32_16x16x32_bf16 v[40:43], v[190:193], v[208:211], v[40:43]
	v_mfma_f32_16x16x32_bf16 v[28:31], v[182:185], v[216:219], v[28:31]
	v_mfma_f32_16x16x32_bf16 v[24:27], v[190:193], v[216:219], v[24:27]
	v_mfma_f32_16x16x32_bf16 v[12:15], v[182:185], v[224:227], v[12:15]
	v_mfma_f32_16x16x32_bf16 v[8:11], v[190:193], v[224:227], v[8:11]
	v_mfma_f32_16x16x32_bf16 v[4:7], v[182:185], v[232:235], v[4:7]
	v_mfma_f32_16x16x32_bf16 v[0:3], v[190:193], v[232:235], v[0:3]
	s_setprio 0
	s_barrier
	s_add_i32 s43, s43, 2
	s_add_u32 s16, s16, 0x100
	s_addc_u32 s17, s17, 0
	s_add_u32 s39, s39, 0x100
	s_addc_u32 s42, s42, 0
	s_cmp_gt_u32 s43, 13
	s_cbranch_scc0 .LBB0_1702
	s_mov_b64 s[48:49], 0x80
	s_and_b64 vcc, exec, s[6:7]
	s_cbranch_vccz .LBB0_1705
	s_barrier
